# Barrier ending each MFMA burst signalled two MFMAs early, with the burst tail raised to priority 2 so it is not starved by the partner wave's new burst
# speedup vs baseline: 1.1208x; 1.0697x over previous
; #define PG8_STAGE(bufoff, gbase, voff) do { _Pragma("unroll") for (int _i = 0; _i < 2; ++_i) \
;         __builtin_amdgcn_global_load_lds((const unsigned*)((const char*)(gbase) + (voff)[_i]), (PG8_LAS unsigned*)(lds + (bufoff) + ldsw + _i * 8192), 16, 0, 0); } while (0)
; #define PG8_LDA(dst, b, h) do { _Pragma("unroll") for (int m = 0; m < 4; ++m) _Pragma("unroll") for (int k = 0; k < 2; ++k) dst[m][k] = *(const PG8_LAS bf16x8*)(lds + PG8_SA(b, h) + aoff + m * 2048 + k * 1024); } while (0)
; #define PG8_LDB(dst, b, h) do { _Pragma("unroll") for (int n = 0; n < 2; ++n) _Pragma("unroll") for (int k = 0; k < 2; ++k) dst[n][k] = *(const PG8_LAS bf16x8*)(lds + PG8_SB(b, h) + boff + n * 2048 + k * 1024); } while (0)
; #define PG8_MMA(ai, bj, At, Bt) do { __builtin_amdgcn_s_setprio(1); _Pragma("unroll") for (int m = 0; m < 4; ++m) _Pragma("unroll") for (int n = 0; n < 2; ++n) _Pragma("unroll") for (int k = 0; k < 2; ++k) \
;         acc[ai][bj][m][n] = __builtin_amdgcn_mfma_f32_16x16x32_bf16(Bt[n][k], At[m][k], acc[ai][bj][m][n], 0, 0, 0); __builtin_amdgcn_s_setprio(0); } while (0)
; #define PG8_WAIT_V(n) asm volatile("s_waitcnt vmcnt(" #n ")" ::: "memory")
; #define PG8_WAIT_L(n) asm volatile("s_waitcnt lgkmcnt(" #n ")" ::: "memory")
; #define PG8_BAR __builtin_amdgcn_s_barrier()
; template <class Epi, class Sched, bool ALIGN_EPI = false, bool SP2 = false>
; __device__ __forceinline__ void gemm_phase(PG8_LAS unsigned char* lds, const Gemm g, const Sched& S, const Epi& E) {
;     ...
;         for (int t = 0; t < nt; t += 2) {
;             const bool last = (t == nt - 2);
;             const char* a1 = cA + (size_t)(t + 1) * kstep;
;             const char* a2 = last ? nA : cA + (size_t)(t + 2) * kstep; const char* b2 = last ? nB : cB + (size_t)(t + 2) * kstep;
;             const char* a3 = a2 + kstep; const char* b3 = b2 + kstep;
;             if constexpr (SP2) {
;             PG8_LDB(B0, 0, 0); PG8_LDB(B1, 0, 1); PG8_SCHED; PG8_LDA(At, 0, 0); PG8_STAGE(PG8_SA(1, 1), a1 + hstep, voffA);
;             PG8_WAIT_V(8); PG8_WAIT_L(0); PG8_BAR; PG8_MMA(0, 0, At, B0); PG8_MMA(0, 1, At, B1); PG8_BAR; PG8_SCHED;
;             PG8_LDA(At, 0, 1); PG8_STAGE(PG8_SB(0, 0), b2, voffB); PG8_STAGE(PG8_SB(0, 1), b2 + hstep, voffB); PG8_STAGE(PG8_SA(0, 0), a2, voffA);
;             PG8_WAIT_V(8); PG8_WAIT_L(0); PG8_BAR; PG8_MMA(1, 0, At, B0); PG8_MMA(1, 1, At, B1); PG8_BAR; PG8_SCHED;
.LBB0_200:
	ds_read_b128 v[148:151], v164
	ds_read_b128 v[152:155], v164 offset:1024
	ds_read_b128 v[156:159], v164 offset:2048
	ds_read_b128 v[168:171], v164 offset:3072
	ds_read_b128 v[172:175], v165
	ds_read_b128 v[176:179], v165 offset:1024
	ds_read_b128 v[180:183], v165 offset:2048
	ds_read_b128 v[184:187], v165 offset:3072
	s_add_u32 s52, s70, 0xfff80080
	s_addc_u32 s53, s71, -1
	s_cmp_eq_u32 s93, 28
	s_cselect_b32 s75, s39, s53
	s_cselect_b32 s74, s69, s52
	s_cselect_b32 s73, s35, s92
	s_cselect_b32 s72, s90, s91
	v_lshl_add_u64 v[220:221], s[70:71], 0, v[138:139]
	s_add_i32 m0, s33, 0xc000
	ds_read_b128 v[188:191], v166
	ds_read_b128 v[192:195], v166 offset:1024
	ds_read_b128 v[196:199], v166 offset:2048
	ds_read_b128 v[200:203], v166 offset:3072
	ds_read_b128 v[204:207], v166 offset:4096
	ds_read_b128 v[208:211], v166 offset:5120
	ds_read_b128 v[212:215], v166 offset:6144
	ds_read_b128 v[216:219], v166 offset:7168
	global_load_lds_dwordx4 v[220:221], off
	v_lshl_add_u64 v[220:221], s[70:71], 0, v[140:141]
	s_add_i32 m0, s33, 0xe000
	s_nop 0
	global_load_lds_dwordx4 v[220:221], off
	s_waitcnt vmcnt(8)
	s_waitcnt lgkmcnt(0)
	s_barrier
	s_setprio 1
	s_waitcnt lgkmcnt(0)
	v_mfma_f32_16x16x32_bf16 v[124:127], v[148:151], v[188:191], v[124:127]
	v_mfma_f32_16x16x32_bf16 v[120:123], v[156:159], v[188:191], v[120:123]
	v_mfma_f32_16x16x32_bf16 v[116:119], v[148:151], v[196:199], v[116:119]
	v_mfma_f32_16x16x32_bf16 v[108:111], v[156:159], v[196:199], v[108:111]
	v_mfma_f32_16x16x32_bf16 v[100:103], v[148:151], v[204:207], v[100:103]
	v_mfma_f32_16x16x32_bf16 v[92:95], v[156:159], v[204:207], v[92:95]
	v_mfma_f32_16x16x32_bf16 v[84:87], v[148:151], v[212:215], v[84:87]
	v_mfma_f32_16x16x32_bf16 v[76:79], v[156:159], v[212:215], v[76:79]
	v_mfma_f32_16x16x32_bf16 v[124:127], v[152:155], v[192:195], v[124:127]
	v_mfma_f32_16x16x32_bf16 v[120:123], v[168:171], v[192:195], v[120:123]
	v_mfma_f32_16x16x32_bf16 v[116:119], v[152:155], v[200:203], v[116:119]
	v_mfma_f32_16x16x32_bf16 v[108:111], v[168:171], v[200:203], v[108:111]
	v_mfma_f32_16x16x32_bf16 v[100:103], v[152:155], v[208:211], v[100:103]
	v_mfma_f32_16x16x32_bf16 v[92:95], v[168:171], v[208:211], v[92:95]
	v_mfma_f32_16x16x32_bf16 v[84:87], v[152:155], v[216:219], v[84:87]
	v_mfma_f32_16x16x32_bf16 v[76:79], v[168:171], v[216:219], v[76:79]
	s_setprio 0
	s_setprio 1
	v_mfma_f32_16x16x32_bf16 v[112:115], v[172:175], v[188:191], v[112:115]
	v_mfma_f32_16x16x32_bf16 v[104:107], v[180:183], v[188:191], v[104:107]
	v_mfma_f32_16x16x32_bf16 v[96:99], v[172:175], v[196:199], v[96:99]
	v_mfma_f32_16x16x32_bf16 v[88:91], v[180:183], v[196:199], v[88:91]
	v_mfma_f32_16x16x32_bf16 v[80:83], v[172:175], v[204:207], v[80:83]
	v_mfma_f32_16x16x32_bf16 v[72:75], v[180:183], v[204:207], v[72:75]
	v_mfma_f32_16x16x32_bf16 v[68:71], v[172:175], v[212:215], v[68:71]
	v_mfma_f32_16x16x32_bf16 v[64:67], v[180:183], v[212:215], v[64:67]
	v_mfma_f32_16x16x32_bf16 v[112:115], v[176:179], v[192:195], v[112:115]
	v_mfma_f32_16x16x32_bf16 v[104:107], v[184:187], v[192:195], v[104:107]
	v_mfma_f32_16x16x32_bf16 v[96:99], v[176:179], v[200:203], v[96:99]
	v_mfma_f32_16x16x32_bf16 v[88:91], v[184:187], v[200:203], v[88:91]
	v_mfma_f32_16x16x32_bf16 v[80:83], v[176:179], v[208:211], v[80:83]
	v_mfma_f32_16x16x32_bf16 v[72:75], v[184:187], v[208:211], v[72:75]
	s_setprio 2
	s_barrier
	v_mfma_f32_16x16x32_bf16 v[68:71], v[176:179], v[216:219], v[68:71]
	v_mfma_f32_16x16x32_bf16 v[64:67], v[184:187], v[216:219], v[64:67]
	s_setprio 0
	s_add_i32 s52, s84, s3
	v_lshl_add_u64 v[220:221], s[72:73], 0, v[132:133]
	s_mov_b32 m0, s52
	ds_read_b128 v[188:191], v166 offset:16384
	ds_read_b128 v[192:195], v166 offset:17408
	ds_read_b128 v[196:199], v166 offset:18432
	ds_read_b128 v[200:203], v166 offset:19456
	ds_read_b128 v[204:207], v166 offset:20480
	ds_read_b128 v[208:211], v166 offset:21504
	ds_read_b128 v[212:215], v166 offset:22528
	ds_read_b128 v[216:219], v166 offset:23552
	global_load_lds_dwordx4 v[220:221], off
	s_add_i32 m0, s52, 0x2000
	s_add_u32 s96, s72, 0x80000
	v_lshl_add_u64 v[222:223], s[72:73], 0, v[128:129]
	s_addc_u32 s97, s73, 0
	s_add_i32 s52, s85, s3
	global_load_lds_dwordx4 v[222:223], off
	v_lshl_add_u64 v[224:225], s[96:97], 0, v[132:133]
	s_mov_b32 m0, s52
	v_lshl_add_u64 v[226:227], s[74:75], 0, v[130:131]
	global_load_lds_dwordx4 v[224:225], off
	v_lshl_add_u64 v[224:225], s[96:97], 0, v[128:129]
	s_add_i32 m0, s52, 0x2000
	s_nop 0
	global_load_lds_dwordx4 v[224:225], off
	v_lshl_add_u64 v[224:225], s[74:75], 0, v[134:135]
	s_mov_b32 m0, s33
	s_nop 0
	global_load_lds_dwordx4 v[224:225], off
	s_mov_b32 m0, s76
	s_nop 0
	global_load_lds_dwordx4 v[226:227], off
	s_waitcnt vmcnt(8)
	s_waitcnt lgkmcnt(0)
	s_barrier
; #define PG8_STAGE(bufoff, gbase, voff) do { _Pragma("unroll") for (int _i = 0; _i < 2; ++_i) \
;         __builtin_amdgcn_global_load_lds((const unsigned*)((const char*)(gbase) + (voff)[_i]), (PG8_LAS unsigned*)(lds + (bufoff) + ldsw + _i * 8192), 16, 0, 0); } while (0)
; #define PG8_LDA(dst, b, h) do { _Pragma("unroll") for (int m = 0; m < 4; ++m) _Pragma("unroll") for (int k = 0; k < 2; ++k) dst[m][k] = *(const PG8_LAS bf16x8*)(lds + PG8_SA(b, h) + aoff + m * 2048 + k * 1024); } while (0)
; #define PG8_LDB(dst, b, h) do { _Pragma("unroll") for (int n = 0; n < 2; ++n) _Pragma("unroll") for (int k = 0; k < 2; ++k) dst[n][k] = *(const PG8_LAS bf16x8*)(lds + PG8_SB(b, h) + boff + n * 2048 + k * 1024); } while (0)
; #define PG8_MMA(ai, bj, At, Bt) do { __builtin_amdgcn_s_setprio(1); _Pragma("unroll") for (int m = 0; m < 4; ++m) _Pragma("unroll") for (int n = 0; n < 2; ++n) _Pragma("unroll") for (int k = 0; k < 2; ++k) \
;         acc[ai][bj][m][n] = __builtin_amdgcn_mfma_f32_16x16x32_bf16(Bt[n][k], At[m][k], acc[ai][bj][m][n], 0, 0, 0); __builtin_amdgcn_s_setprio(0); } while (0)
; #define PG8_WAIT_V(n) asm volatile("s_waitcnt vmcnt(" #n ")" ::: "memory")
; #define PG8_WAIT_L(n) asm volatile("s_waitcnt lgkmcnt(" #n ")" ::: "memory")
; #define PG8_BAR __builtin_amdgcn_s_barrier()
; #define PG8_SCHED __builtin_amdgcn_sched_barrier(0)
; template <class Epi, class Sched, bool ALIGN_EPI = false, bool SP2 = false>
; __device__ __forceinline__ void gemm_phase(PG8_LAS unsigned char* lds, const Gemm g, const Sched& S, const Epi& E) {
;     ...
;             PG8_WAIT_V(8); PG8_WAIT_L(0); PG8_BAR; PG8_MMA(1, 0, At, B0); PG8_MMA(1, 1, At, B1); PG8_BAR; PG8_SCHED;
;             PG8_LDB(B0, 1, 0); PG8_LDB(B1, 1, 1); PG8_SCHED; PG8_LDA(At, 1, 0); PG8_STAGE(PG8_SA(0, 1), a2 + hstep, voffA);
;             PG8_WAIT_V(8); PG8_WAIT_L(0); PG8_BAR; PG8_MMA(0, 0, At, B0); PG8_MMA(0, 1, At, B1); PG8_BAR; PG8_SCHED;
	s_setprio 1
	s_waitcnt lgkmcnt(0)
	v_mfma_f32_16x16x32_bf16 v[60:63], v[148:151], v[188:191], v[60:63]
	v_mfma_f32_16x16x32_bf16 v[56:59], v[156:159], v[188:191], v[56:59]
	v_mfma_f32_16x16x32_bf16 v[52:55], v[148:151], v[196:199], v[52:55]
	v_mfma_f32_16x16x32_bf16 v[44:47], v[156:159], v[196:199], v[44:47]
	v_mfma_f32_16x16x32_bf16 v[36:39], v[148:151], v[204:207], v[36:39]
	v_mfma_f32_16x16x32_bf16 v[28:31], v[156:159], v[204:207], v[28:31]
	v_mfma_f32_16x16x32_bf16 v[20:23], v[148:151], v[212:215], v[20:23]
	v_mfma_f32_16x16x32_bf16 v[12:15], v[156:159], v[212:215], v[12:15]
	v_mfma_f32_16x16x32_bf16 v[60:63], v[152:155], v[192:195], v[60:63]
	v_mfma_f32_16x16x32_bf16 v[56:59], v[168:171], v[192:195], v[56:59]
	v_mfma_f32_16x16x32_bf16 v[52:55], v[152:155], v[200:203], v[52:55]
	v_mfma_f32_16x16x32_bf16 v[44:47], v[168:171], v[200:203], v[44:47]
	v_mfma_f32_16x16x32_bf16 v[36:39], v[152:155], v[208:211], v[36:39]
	v_mfma_f32_16x16x32_bf16 v[28:31], v[168:171], v[208:211], v[28:31]
	v_mfma_f32_16x16x32_bf16 v[20:23], v[152:155], v[216:219], v[20:23]
	v_mfma_f32_16x16x32_bf16 v[12:15], v[168:171], v[216:219], v[12:15]
	s_setprio 0
	s_setprio 1
	v_mfma_f32_16x16x32_bf16 v[48:51], v[172:175], v[188:191], v[48:51]
	v_mfma_f32_16x16x32_bf16 v[40:43], v[180:183], v[188:191], v[40:43]
	v_mfma_f32_16x16x32_bf16 v[32:35], v[172:175], v[196:199], v[32:35]
	v_mfma_f32_16x16x32_bf16 v[24:27], v[180:183], v[196:199], v[24:27]
	v_mfma_f32_16x16x32_bf16 v[16:19], v[172:175], v[204:207], v[16:19]
	v_mfma_f32_16x16x32_bf16 v[8:11], v[180:183], v[204:207], v[8:11]
	v_mfma_f32_16x16x32_bf16 v[4:7], v[172:175], v[212:215], v[4:7]
	v_mfma_f32_16x16x32_bf16 v[0:3], v[180:183], v[212:215], v[0:3]
	v_mfma_f32_16x16x32_bf16 v[48:51], v[176:179], v[192:195], v[48:51]
	v_mfma_f32_16x16x32_bf16 v[40:43], v[184:187], v[192:195], v[40:43]
	v_mfma_f32_16x16x32_bf16 v[32:35], v[176:179], v[200:203], v[32:35]
	v_mfma_f32_16x16x32_bf16 v[24:27], v[184:187], v[200:203], v[24:27]
	v_mfma_f32_16x16x32_bf16 v[16:19], v[176:179], v[208:211], v[16:19]
	v_mfma_f32_16x16x32_bf16 v[8:11], v[184:187], v[208:211], v[8:11]
	s_setprio 2
	s_barrier
	v_mfma_f32_16x16x32_bf16 v[4:7], v[176:179], v[216:219], v[4:7]
	v_mfma_f32_16x16x32_bf16 v[0:3], v[184:187], v[216:219], v[0:3]
	s_setprio 0
	s_add_i32 s52, 0, 0x18000
	v_add_u32_e32 v136, s52, v161
	s_add_i32 s53, 0, 0x1c000
	ds_read_b128 v[148:151], v136
	ds_read_b128 v[152:155], v136 offset:1024
	ds_read_b128 v[156:159], v136 offset:2048
	ds_read_b128 v[168:171], v136 offset:3072
	v_add_u32_e32 v136, s53, v161
	ds_read_b128 v[172:175], v136
	ds_read_b128 v[176:179], v136 offset:1024
	ds_read_b128 v[180:183], v136 offset:2048
	ds_read_b128 v[184:187], v136 offset:3072
	s_add_u32 s74, s74, 0x80000
	s_addc_u32 s75, s75, 0
	s_mov_b32 m0, s77
	v_lshl_add_u64 v[228:229], s[74:75], 0, v[134:135]
	ds_read_b128 v[188:191], v166 offset:32768
	ds_read_b128 v[192:195], v166 offset:33792
	ds_read_b128 v[196:199], v166 offset:34816
	ds_read_b128 v[200:203], v166 offset:35840
	ds_read_b128 v[204:207], v166 offset:36864
	ds_read_b128 v[208:211], v166 offset:37888
	ds_read_b128 v[212:215], v166 offset:38912
	ds_read_b128 v[216:219], v166 offset:39936
	global_load_lds_dwordx4 v[228:229], off
	v_lshl_add_u64 v[228:229], s[74:75], 0, v[130:131]
	s_mov_b32 m0, s78
	s_nop 0
	global_load_lds_dwordx4 v[228:229], off
	s_waitcnt vmcnt(8)
	s_waitcnt lgkmcnt(0)
	s_barrier
	s_setprio 1
	s_waitcnt lgkmcnt(0)
	v_mfma_f32_16x16x32_bf16 v[124:127], v[148:151], v[188:191], v[124:127]
	v_mfma_f32_16x16x32_bf16 v[120:123], v[156:159], v[188:191], v[120:123]
	v_mfma_f32_16x16x32_bf16 v[116:119], v[148:151], v[196:199], v[116:119]
	v_mfma_f32_16x16x32_bf16 v[108:111], v[156:159], v[196:199], v[108:111]
	v_mfma_f32_16x16x32_bf16 v[100:103], v[148:151], v[204:207], v[100:103]
	v_mfma_f32_16x16x32_bf16 v[92:95], v[156:159], v[204:207], v[92:95]
	v_mfma_f32_16x16x32_bf16 v[84:87], v[148:151], v[212:215], v[84:87]
	v_mfma_f32_16x16x32_bf16 v[76:79], v[156:159], v[212:215], v[76:79]
	v_mfma_f32_16x16x32_bf16 v[124:127], v[152:155], v[192:195], v[124:127]
	v_mfma_f32_16x16x32_bf16 v[120:123], v[168:171], v[192:195], v[120:123]
	v_mfma_f32_16x16x32_bf16 v[116:119], v[152:155], v[200:203], v[116:119]
	v_mfma_f32_16x16x32_bf16 v[108:111], v[168:171], v[200:203], v[108:111]
	v_mfma_f32_16x16x32_bf16 v[100:103], v[152:155], v[208:211], v[100:103]
	v_mfma_f32_16x16x32_bf16 v[92:95], v[168:171], v[208:211], v[92:95]
	v_mfma_f32_16x16x32_bf16 v[84:87], v[152:155], v[216:219], v[84:87]
	v_mfma_f32_16x16x32_bf16 v[76:79], v[168:171], v[216:219], v[76:79]
	s_setprio 0
	s_setprio 1
	v_mfma_f32_16x16x32_bf16 v[112:115], v[172:175], v[188:191], v[112:115]
	v_mfma_f32_16x16x32_bf16 v[104:107], v[180:183], v[188:191], v[104:107]
	v_mfma_f32_16x16x32_bf16 v[96:99], v[172:175], v[196:199], v[96:99]
	v_mfma_f32_16x16x32_bf16 v[88:91], v[180:183], v[196:199], v[88:91]
	v_mfma_f32_16x16x32_bf16 v[80:83], v[172:175], v[204:207], v[80:83]
	v_mfma_f32_16x16x32_bf16 v[72:75], v[180:183], v[204:207], v[72:75]
	v_mfma_f32_16x16x32_bf16 v[68:71], v[172:175], v[212:215], v[68:71]
	v_mfma_f32_16x16x32_bf16 v[64:67], v[180:183], v[212:215], v[64:67]
	v_mfma_f32_16x16x32_bf16 v[112:115], v[176:179], v[192:195], v[112:115]
	v_mfma_f32_16x16x32_bf16 v[104:107], v[184:187], v[192:195], v[104:107]
	v_mfma_f32_16x16x32_bf16 v[96:99], v[176:179], v[200:203], v[96:99]
	v_mfma_f32_16x16x32_bf16 v[88:91], v[184:187], v[200:203], v[88:91]
	v_mfma_f32_16x16x32_bf16 v[80:83], v[176:179], v[208:211], v[80:83]
	v_mfma_f32_16x16x32_bf16 v[72:75], v[184:187], v[208:211], v[72:75]
	s_setprio 2
	s_barrier
; #define PG8_STAGE(bufoff, gbase, voff) do { _Pragma("unroll") for (int _i = 0; _i < 2; ++_i) \
;         __builtin_amdgcn_global_load_lds((const unsigned*)((const char*)(gbase) + (voff)[_i]), (PG8_LAS unsigned*)(lds + (bufoff) + ldsw + _i * 8192), 16, 0, 0); } while (0)
; #define PG8_LDA(dst, b, h) do { _Pragma("unroll") for (int m = 0; m < 4; ++m) _Pragma("unroll") for (int k = 0; k < 2; ++k) dst[m][k] = *(const PG8_LAS bf16x8*)(lds + PG8_SA(b, h) + aoff + m * 2048 + k * 1024); } while (0)
; #define PG8_MMA(ai, bj, At, Bt) do { __builtin_amdgcn_s_setprio(1); _Pragma("unroll") for (int m = 0; m < 4; ++m) _Pragma("unroll") for (int n = 0; n < 2; ++n) _Pragma("unroll") for (int k = 0; k < 2; ++k) \
;         acc[ai][bj][m][n] = __builtin_amdgcn_mfma_f32_16x16x32_bf16(Bt[n][k], At[m][k], acc[ai][bj][m][n], 0, 0, 0); __builtin_amdgcn_s_setprio(0); } while (0)
; #define PG8_WAIT_V(n) asm volatile("s_waitcnt vmcnt(" #n ")" ::: "memory")
; #define PG8_WAIT_L(n) asm volatile("s_waitcnt lgkmcnt(" #n ")" ::: "memory")
; #define PG8_BAR __builtin_amdgcn_s_barrier()
; #define PG8_SCHED __builtin_amdgcn_sched_barrier(0)
; template <class Epi, class Sched, bool ALIGN_EPI = false, bool SP2 = false>
; __device__ __forceinline__ void gemm_phase(PG8_LAS unsigned char* lds, const Gemm g, const Sched& S, const Epi& E) {
;     ...
;             PG8_WAIT_V(8); PG8_WAIT_L(0); PG8_BAR; PG8_MMA(0, 0, At, B0); PG8_MMA(0, 1, At, B1); PG8_BAR; PG8_SCHED;
;             PG8_LDA(At, 1, 1); PG8_STAGE(PG8_SB(1, 0), b3, voffB); PG8_STAGE(PG8_SB(1, 1), b3 + hstep, voffB); PG8_STAGE(PG8_SA(1, 0), a3, voffA);
;             PG8_WAIT_V(8); PG8_WAIT_L(0); PG8_BAR; PG8_MMA(1, 0, At, B0); PG8_MMA(1, 1, At, B1); PG8_BAR; PG8_SCHED;
	v_mfma_f32_16x16x32_bf16 v[68:71], v[176:179], v[216:219], v[68:71]
	v_mfma_f32_16x16x32_bf16 v[64:67], v[184:187], v[216:219], v[64:67]
	s_setprio 0
	s_add_i32 s52, s52, s3
	v_lshl_add_u64 v[220:221], v[220:221], 0, s[12:13]
	s_mov_b32 m0, s52
	ds_read_b128 v[188:191], v166 offset:49152
	ds_read_b128 v[192:195], v166 offset:50176
	ds_read_b128 v[196:199], v166 offset:51200
	ds_read_b128 v[200:203], v166 offset:52224
	ds_read_b128 v[204:207], v166 offset:53248
	ds_read_b128 v[208:211], v166 offset:54272
	ds_read_b128 v[212:215], v166 offset:55296
	ds_read_b128 v[216:219], v166 offset:56320
	global_load_lds_dwordx4 v[220:221], off
	s_add_i32 m0, s52, 0x2000
	s_add_u32 s72, s72, 0x80080
	v_lshl_add_u64 v[220:221], v[222:223], 0, s[12:13]
	s_addc_u32 s73, s73, 0
	s_add_i32 s52, s53, s3
	global_load_lds_dwordx4 v[220:221], off
	v_lshl_add_u64 v[220:221], s[72:73], 0, v[132:133]
	s_mov_b32 m0, s52
	s_nop 0
	global_load_lds_dwordx4 v[220:221], off
	v_lshl_add_u64 v[220:221], s[72:73], 0, v[128:129]
	s_add_i32 m0, s52, 0x2000
	s_nop 0
	global_load_lds_dwordx4 v[220:221], off
	v_lshl_add_u64 v[220:221], v[224:225], 0, s[12:13]
	s_mov_b32 m0, s80
	s_nop 0
	global_load_lds_dwordx4 v[220:221], off
	v_lshl_add_u64 v[220:221], v[226:227], 0, s[12:13]
	s_mov_b32 m0, s81
	s_nop 0
	global_load_lds_dwordx4 v[220:221], off
	s_waitcnt vmcnt(8)
	s_waitcnt lgkmcnt(0)
	s_barrier
	s_setprio 1
	s_waitcnt lgkmcnt(0)
	v_mfma_f32_16x16x32_bf16 v[60:63], v[148:151], v[188:191], v[60:63]
	v_mfma_f32_16x16x32_bf16 v[56:59], v[156:159], v[188:191], v[56:59]
	v_mfma_f32_16x16x32_bf16 v[52:55], v[148:151], v[196:199], v[52:55]
	v_mfma_f32_16x16x32_bf16 v[44:47], v[156:159], v[196:199], v[44:47]
	v_mfma_f32_16x16x32_bf16 v[36:39], v[148:151], v[204:207], v[36:39]
	v_mfma_f32_16x16x32_bf16 v[28:31], v[156:159], v[204:207], v[28:31]
	v_mfma_f32_16x16x32_bf16 v[20:23], v[148:151], v[212:215], v[20:23]
	v_mfma_f32_16x16x32_bf16 v[12:15], v[156:159], v[212:215], v[12:15]
	v_mfma_f32_16x16x32_bf16 v[60:63], v[152:155], v[192:195], v[60:63]
	v_mfma_f32_16x16x32_bf16 v[56:59], v[168:171], v[192:195], v[56:59]
	v_mfma_f32_16x16x32_bf16 v[52:55], v[152:155], v[200:203], v[52:55]
	v_mfma_f32_16x16x32_bf16 v[44:47], v[168:171], v[200:203], v[44:47]
	v_mfma_f32_16x16x32_bf16 v[36:39], v[152:155], v[208:211], v[36:39]
	v_mfma_f32_16x16x32_bf16 v[28:31], v[168:171], v[208:211], v[28:31]
	v_mfma_f32_16x16x32_bf16 v[20:23], v[152:155], v[216:219], v[20:23]
	v_mfma_f32_16x16x32_bf16 v[12:15], v[168:171], v[216:219], v[12:15]
	s_setprio 0
	s_setprio 1
	v_mfma_f32_16x16x32_bf16 v[48:51], v[172:175], v[188:191], v[48:51]
	v_mfma_f32_16x16x32_bf16 v[40:43], v[180:183], v[188:191], v[40:43]
	v_mfma_f32_16x16x32_bf16 v[32:35], v[172:175], v[196:199], v[32:35]
	v_mfma_f32_16x16x32_bf16 v[24:27], v[180:183], v[196:199], v[24:27]
	v_mfma_f32_16x16x32_bf16 v[16:19], v[172:175], v[204:207], v[16:19]
	v_mfma_f32_16x16x32_bf16 v[8:11], v[180:183], v[204:207], v[8:11]
	v_mfma_f32_16x16x32_bf16 v[4:7], v[172:175], v[212:215], v[4:7]
	v_mfma_f32_16x16x32_bf16 v[0:3], v[180:183], v[212:215], v[0:3]
	v_mfma_f32_16x16x32_bf16 v[48:51], v[176:179], v[192:195], v[48:51]
	v_mfma_f32_16x16x32_bf16 v[40:43], v[184:187], v[192:195], v[40:43]
	v_mfma_f32_16x16x32_bf16 v[32:35], v[176:179], v[200:203], v[32:35]
	v_mfma_f32_16x16x32_bf16 v[24:27], v[184:187], v[200:203], v[24:27]
	v_mfma_f32_16x16x32_bf16 v[16:19], v[176:179], v[208:211], v[16:19]
	v_mfma_f32_16x16x32_bf16 v[8:11], v[184:187], v[208:211], v[8:11]
	s_setprio 2
	s_barrier
	v_mfma_f32_16x16x32_bf16 v[4:7], v[176:179], v[216:219], v[4:7]
	v_mfma_f32_16x16x32_bf16 v[0:3], v[184:187], v[216:219], v[0:3]
	s_setprio 0
	s_add_i32 s93, s93, 2
	s_add_u32 s70, s70, 0x100
	s_addc_u32 s71, s71, 0
	s_add_u32 s91, s91, 0x100
	s_addc_u32 s92, s92, 0
	s_cmp_gt_u32 s93, 29
	s_cbranch_scc0 .LBB0_200
	s_and_b64 vcc, exec, s[14:15]
	s_cbranch_vccz .LBB0_203
	s_barrier

; #define PG8_STAGE(bufoff, gbase, voff) do { _Pragma("unroll") for (int _i = 0; _i < 2; ++_i) \
;         __builtin_amdgcn_global_load_lds((const unsigned*)((const char*)(gbase) + (voff)[_i]), (PG8_LAS unsigned*)(lds + (bufoff) + ldsw + _i * 8192), 16, 0, 0); } while (0)
; #define PG8_LDA(dst, b, h) do { _Pragma("unroll") for (int m = 0; m < 4; ++m) _Pragma("unroll") for (int k = 0; k < 2; ++k) dst[m][k] = *(const PG8_LAS bf16x8*)(lds + PG8_SA(b, h) + aoff + m * 2048 + k * 1024); } while (0)
; #define PG8_LDB(dst, b, h) do { _Pragma("unroll") for (int n = 0; n < 2; ++n) _Pragma("unroll") for (int k = 0; k < 2; ++k) dst[n][k] = *(const PG8_LAS bf16x8*)(lds + PG8_SB(b, h) + boff + n * 2048 + k * 1024); } while (0)
; #define PG8_MMA(ai, bj, At, Bt) do { __builtin_amdgcn_s_setprio(1); _Pragma("unroll") for (int m = 0; m < 4; ++m) _Pragma("unroll") for (int n = 0; n < 2; ++n) _Pragma("unroll") for (int k = 0; k < 2; ++k) \
;         acc[ai][bj][m][n] = __builtin_amdgcn_mfma_f32_16x16x32_bf16(Bt[n][k], At[m][k], acc[ai][bj][m][n], 0, 0, 0); __builtin_amdgcn_s_setprio(0); } while (0)
; #define PG8_WAIT_V(n) asm volatile("s_waitcnt vmcnt(" #n ")" ::: "memory")
; #define PG8_WAIT_L(n) asm volatile("s_waitcnt lgkmcnt(" #n ")" ::: "memory")
; #define PG8_BAR __builtin_amdgcn_s_barrier()
; template <class Epi, class Sched, bool ALIGN_EPI = false, bool SP2 = false>
; __device__ __forceinline__ void gemm_phase(PG8_LAS unsigned char* lds, const Gemm g, const Sched& S, const Epi& E) {
;     ...
;         for (int t = 0; t < nt; t += 2) {
;             const bool last = (t == nt - 2);
;             const char* a1 = cA + (size_t)(t + 1) * kstep;
;             const char* a2 = last ? nA : cA + (size_t)(t + 2) * kstep; const char* b2 = last ? nB : cB + (size_t)(t + 2) * kstep;
;             const char* a3 = a2 + kstep; const char* b3 = b2 + kstep;
;             if constexpr (SP2) {
;             PG8_LDB(B0, 0, 0); PG8_LDB(B1, 0, 1); PG8_SCHED; PG8_LDA(At, 0, 0); PG8_STAGE(PG8_SA(1, 1), a1 + hstep, voffA);
;             PG8_WAIT_V(8); PG8_WAIT_L(0); PG8_BAR; PG8_MMA(0, 0, At, B0); PG8_MMA(0, 1, At, B1); PG8_BAR; PG8_SCHED;
;             PG8_LDA(At, 0, 1); PG8_STAGE(PG8_SB(0, 0), b2, voffB); PG8_STAGE(PG8_SB(0, 1), b2 + hstep, voffB); PG8_STAGE(PG8_SA(0, 0), a2, voffA);
;             PG8_WAIT_V(8); PG8_WAIT_L(0); PG8_BAR; PG8_MMA(1, 0, At, B0); PG8_MMA(1, 1, At, B1); PG8_BAR; PG8_SCHED;
.LBB0_374:
	ds_read_b128 v[128:131], v230
	ds_read_b128 v[132:135], v230 offset:1024
	ds_read_b128 v[158:161], v230 offset:2048
	ds_read_b128 v[162:165], v230 offset:3072
	ds_read_b128 v[166:169], v231
	ds_read_b128 v[170:173], v231 offset:1024
	ds_read_b128 v[174:177], v231 offset:2048
	ds_read_b128 v[178:181], v231 offset:3072
	s_add_u32 s52, s76, 0xfff80080
	s_addc_u32 s53, s77, -1
	s_cmp_eq_u32 vcc_hi, 28
	s_cselect_b32 s81, s11, s53
	s_cselect_b32 s80, s55, s52
	s_cselect_b32 s79, s51, vcc_lo
	s_cselect_b32 s78, s73, s75
	v_lshl_add_u64 v[214:215], s[76:77], 0, v[150:151]
	s_add_i32 m0, s28, 0xc000
	ds_read_b128 v[182:185], v232
	ds_read_b128 v[186:189], v232 offset:1024
	ds_read_b128 v[190:193], v232 offset:2048
	ds_read_b128 v[194:197], v232 offset:3072
	ds_read_b128 v[198:201], v232 offset:4096
	ds_read_b128 v[202:205], v232 offset:5120
	ds_read_b128 v[206:209], v232 offset:6144
	ds_read_b128 v[210:213], v232 offset:7168
	global_load_lds_dwordx4 v[214:215], off
	v_lshl_add_u64 v[214:215], s[76:77], 0, v[152:153]
	s_add_i32 m0, s28, 0xe000
	s_nop 0
	global_load_lds_dwordx4 v[214:215], off
	s_waitcnt vmcnt(8)
	s_waitcnt lgkmcnt(0)
	s_barrier
	s_setprio 1
	s_waitcnt lgkmcnt(0)
	v_mfma_f32_16x16x32_bf16 v[124:127], v[128:131], v[182:185], v[124:127]
	v_mfma_f32_16x16x32_bf16 v[120:123], v[158:161], v[182:185], v[120:123]
	v_mfma_f32_16x16x32_bf16 v[116:119], v[128:131], v[190:193], v[116:119]
	v_mfma_f32_16x16x32_bf16 v[112:115], v[158:161], v[190:193], v[112:115]
	v_mfma_f32_16x16x32_bf16 v[108:111], v[128:131], v[198:201], v[108:111]
	v_mfma_f32_16x16x32_bf16 v[104:107], v[158:161], v[198:201], v[104:107]
	v_mfma_f32_16x16x32_bf16 v[100:103], v[128:131], v[206:209], v[100:103]
	v_mfma_f32_16x16x32_bf16 v[96:99], v[158:161], v[206:209], v[96:99]
	v_mfma_f32_16x16x32_bf16 v[124:127], v[132:135], v[186:189], v[124:127]
	v_mfma_f32_16x16x32_bf16 v[120:123], v[162:165], v[186:189], v[120:123]
	v_mfma_f32_16x16x32_bf16 v[116:119], v[132:135], v[194:197], v[116:119]
	v_mfma_f32_16x16x32_bf16 v[112:115], v[162:165], v[194:197], v[112:115]
	v_mfma_f32_16x16x32_bf16 v[108:111], v[132:135], v[202:205], v[108:111]
	v_mfma_f32_16x16x32_bf16 v[104:107], v[162:165], v[202:205], v[104:107]
	v_mfma_f32_16x16x32_bf16 v[100:103], v[132:135], v[210:213], v[100:103]
	v_mfma_f32_16x16x32_bf16 v[96:99], v[162:165], v[210:213], v[96:99]
	s_setprio 0
	s_setprio 1
	v_mfma_f32_16x16x32_bf16 v[60:63], v[166:169], v[182:185], v[60:63]
	v_mfma_f32_16x16x32_bf16 v[56:59], v[174:177], v[182:185], v[56:59]
	v_mfma_f32_16x16x32_bf16 v[52:55], v[166:169], v[190:193], v[52:55]
	v_mfma_f32_16x16x32_bf16 v[48:51], v[174:177], v[190:193], v[48:51]
	v_mfma_f32_16x16x32_bf16 v[44:47], v[166:169], v[198:201], v[44:47]
	v_mfma_f32_16x16x32_bf16 v[40:43], v[174:177], v[198:201], v[40:43]
	v_mfma_f32_16x16x32_bf16 v[36:39], v[166:169], v[206:209], v[36:39]
	v_mfma_f32_16x16x32_bf16 v[32:35], v[174:177], v[206:209], v[32:35]
	v_mfma_f32_16x16x32_bf16 v[60:63], v[170:173], v[186:189], v[60:63]
	v_mfma_f32_16x16x32_bf16 v[56:59], v[178:181], v[186:189], v[56:59]
	v_mfma_f32_16x16x32_bf16 v[52:55], v[170:173], v[194:197], v[52:55]
	v_mfma_f32_16x16x32_bf16 v[48:51], v[178:181], v[194:197], v[48:51]
	v_mfma_f32_16x16x32_bf16 v[44:47], v[170:173], v[202:205], v[44:47]
	v_mfma_f32_16x16x32_bf16 v[40:43], v[178:181], v[202:205], v[40:43]
	s_setprio 2
	s_barrier
	v_mfma_f32_16x16x32_bf16 v[36:39], v[170:173], v[210:213], v[36:39]
	v_mfma_f32_16x16x32_bf16 v[32:35], v[178:181], v[210:213], v[32:35]
	s_setprio 0
	s_add_i32 s52, s93, s3
	v_lshl_add_u64 v[214:215], s[78:79], 0, v[138:139]
	s_mov_b32 m0, s52
	ds_read_b128 v[182:185], v232 offset:16384
	ds_read_b128 v[186:189], v232 offset:17408
	ds_read_b128 v[190:193], v232 offset:18432
	ds_read_b128 v[194:197], v232 offset:19456
	ds_read_b128 v[198:201], v232 offset:20480
	ds_read_b128 v[202:205], v232 offset:21504
	ds_read_b128 v[206:209], v232 offset:22528
	ds_read_b128 v[210:213], v232 offset:23552
	global_load_lds_dwordx4 v[214:215], off
	s_add_i32 m0, s52, 0x2000
	s_add_u32 s52, s78, 0x80000
	v_lshl_add_u64 v[216:217], s[78:79], 0, v[142:143]
	s_addc_u32 s53, s79, 0
	s_add_i32 s56, s10, s3
	global_load_lds_dwordx4 v[216:217], off
	v_lshl_add_u64 v[218:219], s[52:53], 0, v[138:139]
	s_mov_b32 m0, s56
	v_lshl_add_u64 v[220:221], s[80:81], 0, v[140:141]
	global_load_lds_dwordx4 v[218:219], off
	v_lshl_add_u64 v[218:219], s[52:53], 0, v[142:143]
	s_add_i32 m0, s56, 0x2000
	s_nop 0
	global_load_lds_dwordx4 v[218:219], off
	v_lshl_add_u64 v[218:219], s[80:81], 0, v[136:137]
	s_mov_b32 m0, s28
	s_nop 0
	global_load_lds_dwordx4 v[218:219], off
	s_mov_b32 m0, s29
	s_nop 0
	global_load_lds_dwordx4 v[220:221], off
	s_waitcnt vmcnt(8)
	s_waitcnt lgkmcnt(0)
	s_barrier
; #define PG8_STAGE(bufoff, gbase, voff) do { _Pragma("unroll") for (int _i = 0; _i < 2; ++_i) \
;         __builtin_amdgcn_global_load_lds((const unsigned*)((const char*)(gbase) + (voff)[_i]), (PG8_LAS unsigned*)(lds + (bufoff) + ldsw + _i * 8192), 16, 0, 0); } while (0)
; #define PG8_LDA(dst, b, h) do { _Pragma("unroll") for (int m = 0; m < 4; ++m) _Pragma("unroll") for (int k = 0; k < 2; ++k) dst[m][k] = *(const PG8_LAS bf16x8*)(lds + PG8_SA(b, h) + aoff + m * 2048 + k * 1024); } while (0)
; #define PG8_LDB(dst, b, h) do { _Pragma("unroll") for (int n = 0; n < 2; ++n) _Pragma("unroll") for (int k = 0; k < 2; ++k) dst[n][k] = *(const PG8_LAS bf16x8*)(lds + PG8_SB(b, h) + boff + n * 2048 + k * 1024); } while (0)
; #define PG8_MMA(ai, bj, At, Bt) do { __builtin_amdgcn_s_setprio(1); _Pragma("unroll") for (int m = 0; m < 4; ++m) _Pragma("unroll") for (int n = 0; n < 2; ++n) _Pragma("unroll") for (int k = 0; k < 2; ++k) \
;         acc[ai][bj][m][n] = __builtin_amdgcn_mfma_f32_16x16x32_bf16(Bt[n][k], At[m][k], acc[ai][bj][m][n], 0, 0, 0); __builtin_amdgcn_s_setprio(0); } while (0)
; #define PG8_WAIT_V(n) asm volatile("s_waitcnt vmcnt(" #n ")" ::: "memory")
; #define PG8_WAIT_L(n) asm volatile("s_waitcnt lgkmcnt(" #n ")" ::: "memory")
; #define PG8_BAR __builtin_amdgcn_s_barrier()
; #define PG8_SCHED __builtin_amdgcn_sched_barrier(0)
; template <class Epi, class Sched, bool ALIGN_EPI = false, bool SP2 = false>
; __device__ __forceinline__ void gemm_phase(PG8_LAS unsigned char* lds, const Gemm g, const Sched& S, const Epi& E) {
;     ...
;             PG8_WAIT_V(8); PG8_WAIT_L(0); PG8_BAR; PG8_MMA(1, 0, At, B0); PG8_MMA(1, 1, At, B1); PG8_BAR; PG8_SCHED;
;             PG8_LDB(B0, 1, 0); PG8_LDB(B1, 1, 1); PG8_SCHED; PG8_LDA(At, 1, 0); PG8_STAGE(PG8_SA(0, 1), a2 + hstep, voffA);
;             PG8_WAIT_V(8); PG8_WAIT_L(0); PG8_BAR; PG8_MMA(0, 0, At, B0); PG8_MMA(0, 1, At, B1); PG8_BAR; PG8_SCHED;
	s_setprio 1
	s_waitcnt lgkmcnt(0)
	v_mfma_f32_16x16x32_bf16 v[92:95], v[128:131], v[182:185], v[92:95]
	v_mfma_f32_16x16x32_bf16 v[88:91], v[158:161], v[182:185], v[88:91]
	v_mfma_f32_16x16x32_bf16 v[84:87], v[128:131], v[190:193], v[84:87]
	v_mfma_f32_16x16x32_bf16 v[80:83], v[158:161], v[190:193], v[80:83]
	v_mfma_f32_16x16x32_bf16 v[76:79], v[128:131], v[198:201], v[76:79]
	v_mfma_f32_16x16x32_bf16 v[72:75], v[158:161], v[198:201], v[72:75]
	v_mfma_f32_16x16x32_bf16 v[68:71], v[128:131], v[206:209], v[68:71]
	v_mfma_f32_16x16x32_bf16 v[64:67], v[158:161], v[206:209], v[64:67]
	v_mfma_f32_16x16x32_bf16 v[92:95], v[132:135], v[186:189], v[92:95]
	v_mfma_f32_16x16x32_bf16 v[88:91], v[162:165], v[186:189], v[88:91]
	v_mfma_f32_16x16x32_bf16 v[84:87], v[132:135], v[194:197], v[84:87]
	v_mfma_f32_16x16x32_bf16 v[80:83], v[162:165], v[194:197], v[80:83]
	v_mfma_f32_16x16x32_bf16 v[76:79], v[132:135], v[202:205], v[76:79]
	v_mfma_f32_16x16x32_bf16 v[72:75], v[162:165], v[202:205], v[72:75]
	v_mfma_f32_16x16x32_bf16 v[68:71], v[132:135], v[210:213], v[68:71]
	v_mfma_f32_16x16x32_bf16 v[64:67], v[162:165], v[210:213], v[64:67]
	s_setprio 0
	s_setprio 1
	v_mfma_f32_16x16x32_bf16 v[28:31], v[166:169], v[182:185], v[28:31]
	v_mfma_f32_16x16x32_bf16 v[24:27], v[174:177], v[182:185], v[24:27]
	v_mfma_f32_16x16x32_bf16 v[20:23], v[166:169], v[190:193], v[20:23]
	v_mfma_f32_16x16x32_bf16 v[16:19], v[174:177], v[190:193], v[16:19]
	v_mfma_f32_16x16x32_bf16 v[12:15], v[166:169], v[198:201], v[12:15]
	v_mfma_f32_16x16x32_bf16 v[8:11], v[174:177], v[198:201], v[8:11]
	v_mfma_f32_16x16x32_bf16 v[4:7], v[166:169], v[206:209], v[4:7]
	v_mfma_f32_16x16x32_bf16 v[0:3], v[174:177], v[206:209], v[0:3]
	v_mfma_f32_16x16x32_bf16 v[28:31], v[170:173], v[186:189], v[28:31]
	v_mfma_f32_16x16x32_bf16 v[24:27], v[178:181], v[186:189], v[24:27]
	v_mfma_f32_16x16x32_bf16 v[20:23], v[170:173], v[194:197], v[20:23]
	v_mfma_f32_16x16x32_bf16 v[16:19], v[178:181], v[194:197], v[16:19]
	v_mfma_f32_16x16x32_bf16 v[12:15], v[170:173], v[202:205], v[12:15]
	v_mfma_f32_16x16x32_bf16 v[8:11], v[178:181], v[202:205], v[8:11]
	s_setprio 2
	s_barrier
	v_mfma_f32_16x16x32_bf16 v[4:7], v[170:173], v[210:213], v[4:7]
	v_mfma_f32_16x16x32_bf16 v[0:3], v[178:181], v[210:213], v[0:3]
	s_setprio 0
	s_add_i32 s56, 0, 0x18000
	s_add_i32 s57, 0, 0x1c000
	v_add_u32_e32 v162, s56, v228
	v_add_u32_e32 v178, s57, v228
	ds_read_b128 v[128:131], v162
	ds_read_b128 v[132:135], v162 offset:1024
	ds_read_b128 v[158:161], v162 offset:2048
	ds_read_b128 v[162:165], v162 offset:3072
	ds_read_b128 v[166:169], v178
	ds_read_b128 v[170:173], v178 offset:1024
	ds_read_b128 v[174:177], v178 offset:2048
	ds_read_b128 v[178:181], v178 offset:3072
	s_add_u32 s52, s80, 0x80000
	s_addc_u32 s53, s81, 0
	s_mov_b32 m0, s33
	v_lshl_add_u64 v[234:235], s[52:53], 0, v[136:137]
	ds_read_b128 v[182:185], v232 offset:32768
	ds_read_b128 v[186:189], v232 offset:33792
	ds_read_b128 v[190:193], v232 offset:34816
	ds_read_b128 v[194:197], v232 offset:35840
	ds_read_b128 v[198:201], v232 offset:36864
	ds_read_b128 v[202:205], v232 offset:37888
	ds_read_b128 v[206:209], v232 offset:38912
	ds_read_b128 v[210:213], v232 offset:39936
	global_load_lds_dwordx4 v[234:235], off
	v_lshl_add_u64 v[234:235], s[52:53], 0, v[140:141]
	s_mov_b32 m0, s38
	s_nop 0
	global_load_lds_dwordx4 v[234:235], off
	s_waitcnt vmcnt(8)
	s_waitcnt lgkmcnt(0)
	s_barrier
	s_setprio 1
	s_waitcnt lgkmcnt(0)
	v_mfma_f32_16x16x32_bf16 v[124:127], v[128:131], v[182:185], v[124:127]
	v_mfma_f32_16x16x32_bf16 v[120:123], v[158:161], v[182:185], v[120:123]
	v_mfma_f32_16x16x32_bf16 v[116:119], v[128:131], v[190:193], v[116:119]
	v_mfma_f32_16x16x32_bf16 v[112:115], v[158:161], v[190:193], v[112:115]
	v_mfma_f32_16x16x32_bf16 v[108:111], v[128:131], v[198:201], v[108:111]
	v_mfma_f32_16x16x32_bf16 v[104:107], v[158:161], v[198:201], v[104:107]
	v_mfma_f32_16x16x32_bf16 v[100:103], v[128:131], v[206:209], v[100:103]
	v_mfma_f32_16x16x32_bf16 v[96:99], v[158:161], v[206:209], v[96:99]
	v_mfma_f32_16x16x32_bf16 v[124:127], v[132:135], v[186:189], v[124:127]
	v_mfma_f32_16x16x32_bf16 v[120:123], v[162:165], v[186:189], v[120:123]
	v_mfma_f32_16x16x32_bf16 v[116:119], v[132:135], v[194:197], v[116:119]
	v_mfma_f32_16x16x32_bf16 v[112:115], v[162:165], v[194:197], v[112:115]
	v_mfma_f32_16x16x32_bf16 v[108:111], v[132:135], v[202:205], v[108:111]
	v_mfma_f32_16x16x32_bf16 v[104:107], v[162:165], v[202:205], v[104:107]
	v_mfma_f32_16x16x32_bf16 v[100:103], v[132:135], v[210:213], v[100:103]
	v_mfma_f32_16x16x32_bf16 v[96:99], v[162:165], v[210:213], v[96:99]
	s_setprio 0
	s_setprio 1
	v_mfma_f32_16x16x32_bf16 v[60:63], v[166:169], v[182:185], v[60:63]
	v_mfma_f32_16x16x32_bf16 v[56:59], v[174:177], v[182:185], v[56:59]
	v_mfma_f32_16x16x32_bf16 v[52:55], v[166:169], v[190:193], v[52:55]
	v_mfma_f32_16x16x32_bf16 v[48:51], v[174:177], v[190:193], v[48:51]
	v_mfma_f32_16x16x32_bf16 v[44:47], v[166:169], v[198:201], v[44:47]
	v_mfma_f32_16x16x32_bf16 v[40:43], v[174:177], v[198:201], v[40:43]
	v_mfma_f32_16x16x32_bf16 v[36:39], v[166:169], v[206:209], v[36:39]
	v_mfma_f32_16x16x32_bf16 v[32:35], v[174:177], v[206:209], v[32:35]
	v_mfma_f32_16x16x32_bf16 v[60:63], v[170:173], v[186:189], v[60:63]
	v_mfma_f32_16x16x32_bf16 v[56:59], v[178:181], v[186:189], v[56:59]
	v_mfma_f32_16x16x32_bf16 v[52:55], v[170:173], v[194:197], v[52:55]
	v_mfma_f32_16x16x32_bf16 v[48:51], v[178:181], v[194:197], v[48:51]
	v_mfma_f32_16x16x32_bf16 v[44:47], v[170:173], v[202:205], v[44:47]
	v_mfma_f32_16x16x32_bf16 v[40:43], v[178:181], v[202:205], v[40:43]
	s_setprio 2
	s_barrier
; #define PG8_STAGE(bufoff, gbase, voff) do { _Pragma("unroll") for (int _i = 0; _i < 2; ++_i) \
;         __builtin_amdgcn_global_load_lds((const unsigned*)((const char*)(gbase) + (voff)[_i]), (PG8_LAS unsigned*)(lds + (bufoff) + ldsw + _i * 8192), 16, 0, 0); } while (0)
; #define PG8_LDA(dst, b, h) do { _Pragma("unroll") for (int m = 0; m < 4; ++m) _Pragma("unroll") for (int k = 0; k < 2; ++k) dst[m][k] = *(const PG8_LAS bf16x8*)(lds + PG8_SA(b, h) + aoff + m * 2048 + k * 1024); } while (0)
; #define PG8_MMA(ai, bj, At, Bt) do { __builtin_amdgcn_s_setprio(1); _Pragma("unroll") for (int m = 0; m < 4; ++m) _Pragma("unroll") for (int n = 0; n < 2; ++n) _Pragma("unroll") for (int k = 0; k < 2; ++k) \
;         acc[ai][bj][m][n] = __builtin_amdgcn_mfma_f32_16x16x32_bf16(Bt[n][k], At[m][k], acc[ai][bj][m][n], 0, 0, 0); __builtin_amdgcn_s_setprio(0); } while (0)
; #define PG8_WAIT_V(n) asm volatile("s_waitcnt vmcnt(" #n ")" ::: "memory")
; #define PG8_WAIT_L(n) asm volatile("s_waitcnt lgkmcnt(" #n ")" ::: "memory")
; #define PG8_BAR __builtin_amdgcn_s_barrier()
; #define PG8_SCHED __builtin_amdgcn_sched_barrier(0)
; template <class Epi, class Sched, bool ALIGN_EPI = false, bool SP2 = false>
; __device__ __forceinline__ void gemm_phase(PG8_LAS unsigned char* lds, const Gemm g, const Sched& S, const Epi& E) {
;     ...
;             PG8_WAIT_V(8); PG8_WAIT_L(0); PG8_BAR; PG8_MMA(0, 0, At, B0); PG8_MMA(0, 1, At, B1); PG8_BAR; PG8_SCHED;
;             PG8_LDA(At, 1, 1); PG8_STAGE(PG8_SB(1, 0), b3, voffB); PG8_STAGE(PG8_SB(1, 1), b3 + hstep, voffB); PG8_STAGE(PG8_SA(1, 0), a3, voffA);
;             PG8_WAIT_V(8); PG8_WAIT_L(0); PG8_BAR; PG8_MMA(1, 0, At, B0); PG8_MMA(1, 1, At, B1); PG8_BAR; PG8_SCHED;
	v_mfma_f32_16x16x32_bf16 v[36:39], v[170:173], v[210:213], v[36:39]
	v_mfma_f32_16x16x32_bf16 v[32:35], v[178:181], v[210:213], v[32:35]
	s_setprio 0
	s_add_i32 s52, s56, s3
	v_lshl_add_u64 v[214:215], v[214:215], 0, s[14:15]
	s_mov_b32 m0, s52
	ds_read_b128 v[182:185], v232 offset:49152
	ds_read_b128 v[186:189], v232 offset:50176
	ds_read_b128 v[190:193], v232 offset:51200
	ds_read_b128 v[194:197], v232 offset:52224
	ds_read_b128 v[198:201], v232 offset:53248
	ds_read_b128 v[202:205], v232 offset:54272
	ds_read_b128 v[206:209], v232 offset:55296
	ds_read_b128 v[210:213], v232 offset:56320
	global_load_lds_dwordx4 v[214:215], off
	s_add_i32 m0, s52, 0x2000
	s_add_u32 s52, s78, 0x80080
	v_lshl_add_u64 v[214:215], v[216:217], 0, s[14:15]
	s_addc_u32 s53, s79, 0
	s_add_i32 s56, s57, s3
	global_load_lds_dwordx4 v[214:215], off
	v_lshl_add_u64 v[214:215], s[52:53], 0, v[138:139]
	s_mov_b32 m0, s56
	s_nop 0
	global_load_lds_dwordx4 v[214:215], off
	v_lshl_add_u64 v[214:215], s[52:53], 0, v[142:143]
	s_add_i32 m0, s56, 0x2000
	s_nop 0
	global_load_lds_dwordx4 v[214:215], off
	v_lshl_add_u64 v[214:215], v[218:219], 0, s[14:15]
	s_mov_b32 m0, s88
	s_nop 0
	global_load_lds_dwordx4 v[214:215], off
	v_lshl_add_u64 v[214:215], v[220:221], 0, s[14:15]
	s_mov_b32 m0, s89
	s_nop 0
	global_load_lds_dwordx4 v[214:215], off
	s_waitcnt vmcnt(8)
	s_waitcnt lgkmcnt(0)
	s_barrier
	s_setprio 1
	s_waitcnt lgkmcnt(0)
	v_mfma_f32_16x16x32_bf16 v[92:95], v[128:131], v[182:185], v[92:95]
	v_mfma_f32_16x16x32_bf16 v[88:91], v[158:161], v[182:185], v[88:91]
	v_mfma_f32_16x16x32_bf16 v[84:87], v[128:131], v[190:193], v[84:87]
	v_mfma_f32_16x16x32_bf16 v[80:83], v[158:161], v[190:193], v[80:83]
	v_mfma_f32_16x16x32_bf16 v[76:79], v[128:131], v[198:201], v[76:79]
	v_mfma_f32_16x16x32_bf16 v[72:75], v[158:161], v[198:201], v[72:75]
	v_mfma_f32_16x16x32_bf16 v[68:71], v[128:131], v[206:209], v[68:71]
	v_mfma_f32_16x16x32_bf16 v[64:67], v[158:161], v[206:209], v[64:67]
	v_mfma_f32_16x16x32_bf16 v[92:95], v[132:135], v[186:189], v[92:95]
	v_mfma_f32_16x16x32_bf16 v[88:91], v[162:165], v[186:189], v[88:91]
	v_mfma_f32_16x16x32_bf16 v[84:87], v[132:135], v[194:197], v[84:87]
	v_mfma_f32_16x16x32_bf16 v[80:83], v[162:165], v[194:197], v[80:83]
	v_mfma_f32_16x16x32_bf16 v[76:79], v[132:135], v[202:205], v[76:79]
	v_mfma_f32_16x16x32_bf16 v[72:75], v[162:165], v[202:205], v[72:75]
	v_mfma_f32_16x16x32_bf16 v[68:71], v[132:135], v[210:213], v[68:71]
	v_mfma_f32_16x16x32_bf16 v[64:67], v[162:165], v[210:213], v[64:67]
	s_setprio 0
	s_setprio 1
	v_mfma_f32_16x16x32_bf16 v[28:31], v[166:169], v[182:185], v[28:31]
	v_mfma_f32_16x16x32_bf16 v[24:27], v[174:177], v[182:185], v[24:27]
	v_mfma_f32_16x16x32_bf16 v[20:23], v[166:169], v[190:193], v[20:23]
	v_mfma_f32_16x16x32_bf16 v[16:19], v[174:177], v[190:193], v[16:19]
	v_mfma_f32_16x16x32_bf16 v[12:15], v[166:169], v[198:201], v[12:15]
	v_mfma_f32_16x16x32_bf16 v[8:11], v[174:177], v[198:201], v[8:11]
	v_mfma_f32_16x16x32_bf16 v[4:7], v[166:169], v[206:209], v[4:7]
	v_mfma_f32_16x16x32_bf16 v[0:3], v[174:177], v[206:209], v[0:3]
	v_mfma_f32_16x16x32_bf16 v[28:31], v[170:173], v[186:189], v[28:31]
	v_mfma_f32_16x16x32_bf16 v[24:27], v[178:181], v[186:189], v[24:27]
	v_mfma_f32_16x16x32_bf16 v[20:23], v[170:173], v[194:197], v[20:23]
	v_mfma_f32_16x16x32_bf16 v[16:19], v[178:181], v[194:197], v[16:19]
	v_mfma_f32_16x16x32_bf16 v[12:15], v[170:173], v[202:205], v[12:15]
	v_mfma_f32_16x16x32_bf16 v[8:11], v[178:181], v[202:205], v[8:11]
	s_setprio 2
	s_barrier
	v_mfma_f32_16x16x32_bf16 v[4:7], v[170:173], v[210:213], v[4:7]
	v_mfma_f32_16x16x32_bf16 v[0:3], v[178:181], v[210:213], v[0:3]
	s_setprio 0
	s_add_i32 vcc_hi, vcc_hi, 2
	s_add_u32 s76, s76, 0x100
	s_addc_u32 s77, s77, 0
	s_add_u32 s75, s75, 0x100
	s_addc_u32 vcc_lo, vcc_lo, 0
	s_cmp_gt_u32 vcc_hi, 29
	s_cbranch_scc0 .LBB0_374
	s_and_b64 vcc, exec, s[48:49]
	s_cbranch_vccz .LBB0_377
	s_barrier

; #define PG8_STAGE(bufoff, gbase, voff) do { _Pragma("unroll") for (int _i = 0; _i < 2; ++_i) \
;         __builtin_amdgcn_global_load_lds((const unsigned*)((const char*)(gbase) + (voff)[_i]), (PG8_LAS unsigned*)(lds + (bufoff) + ldsw + _i * 8192), 16, 0, 0); } while (0)
; #define PG8_LDA(dst, b, h) do { _Pragma("unroll") for (int m = 0; m < 4; ++m) _Pragma("unroll") for (int k = 0; k < 2; ++k) dst[m][k] = *(const PG8_LAS bf16x8*)(lds + PG8_SA(b, h) + aoff + m * 2048 + k * 1024); } while (0)
; #define PG8_LDB(dst, b, h) do { _Pragma("unroll") for (int n = 0; n < 2; ++n) _Pragma("unroll") for (int k = 0; k < 2; ++k) dst[n][k] = *(const PG8_LAS bf16x8*)(lds + PG8_SB(b, h) + boff + n * 2048 + k * 1024); } while (0)
; #define PG8_MMA(ai, bj, At, Bt) do { __builtin_amdgcn_s_setprio(1); _Pragma("unroll") for (int m = 0; m < 4; ++m) _Pragma("unroll") for (int n = 0; n < 2; ++n) _Pragma("unroll") for (int k = 0; k < 2; ++k) \
;         acc[ai][bj][m][n] = __builtin_amdgcn_mfma_f32_16x16x32_bf16(Bt[n][k], At[m][k], acc[ai][bj][m][n], 0, 0, 0); __builtin_amdgcn_s_setprio(0); } while (0)
; #define PG8_WAIT_V(n) asm volatile("s_waitcnt vmcnt(" #n ")" ::: "memory")
; #define PG8_WAIT_L(n) asm volatile("s_waitcnt lgkmcnt(" #n ")" ::: "memory")
; #define PG8_BAR __builtin_amdgcn_s_barrier()
; template <class Epi, class Sched, bool ALIGN_EPI = false, bool SP2 = false>
; __device__ __forceinline__ void gemm_phase(PG8_LAS unsigned char* lds, const Gemm g, const Sched& S, const Epi& E) {
;     ...
;         for (int t = 0; t < nt; t += 2) {
;             const bool last = (t == nt - 2);
;             const char* a1 = cA + (size_t)(t + 1) * kstep;
;             const char* a2 = last ? nA : cA + (size_t)(t + 2) * kstep; const char* b2 = last ? nB : cB + (size_t)(t + 2) * kstep;
;             const char* a3 = a2 + kstep; const char* b3 = b2 + kstep;
;             if constexpr (SP2) {
;             PG8_LDB(B0, 0, 0); PG8_LDB(B1, 0, 1); PG8_SCHED; PG8_LDA(At, 0, 0); PG8_STAGE(PG8_SA(1, 1), a1 + hstep, voffA);
;             PG8_WAIT_V(8); PG8_WAIT_L(0); PG8_BAR; PG8_MMA(0, 0, At, B0); PG8_MMA(0, 1, At, B1); PG8_BAR; PG8_SCHED;
;             PG8_LDA(At, 0, 1); PG8_STAGE(PG8_SB(0, 0), b2, voffB); PG8_STAGE(PG8_SB(0, 1), b2 + hstep, voffB); PG8_STAGE(PG8_SA(0, 0), a2, voffA);
;             PG8_WAIT_V(8); PG8_WAIT_L(0); PG8_BAR; PG8_MMA(1, 0, At, B0); PG8_MMA(1, 1, At, B1); PG8_BAR; PG8_SCHED;
.LBB0_410:
	ds_read_b128 v[166:169], v145
	ds_read_b128 v[170:173], v145 offset:1024
	ds_read_b128 v[174:177], v145 offset:2048
	ds_read_b128 v[178:181], v145 offset:3072
	ds_read_b128 v[182:185], v149
	ds_read_b128 v[186:189], v149 offset:1024
	ds_read_b128 v[190:193], v149 offset:2048
	ds_read_b128 v[194:197], v149 offset:3072
	s_add_u32 s52, s74, 0xfff80080
	s_addc_u32 s53, s75, -1
	s_cmp_eq_u32 s51, 4
	s_cselect_b32 s79, s55, s53
	s_cselect_b32 s78, s54, s52
	s_cselect_b32 s77, s69, s49
	s_cselect_b32 s76, s68, s37
	s_mov_b32 m0, s80
	v_lshl_add_u64 v[230:231], s[74:75], 0, v[160:161]
	ds_read_b128 v[198:201], v164
	ds_read_b128 v[202:205], v164 offset:1024
	ds_read_b128 v[206:209], v164 offset:2048
	ds_read_b128 v[210:213], v164 offset:3072
	ds_read_b128 v[214:217], v164 offset:4096
	ds_read_b128 v[218:221], v164 offset:5120
	ds_read_b128 v[222:225], v164 offset:6144
	ds_read_b128 v[226:229], v164 offset:7168
	global_load_lds_dwordx4 v[230:231], off
	v_lshl_add_u64 v[230:231], s[74:75], 0, v[162:163]
	s_mov_b32 m0, s81
	s_nop 0
	global_load_lds_dwordx4 v[230:231], off
	s_waitcnt vmcnt(8)
	s_waitcnt lgkmcnt(0)
	s_barrier
	s_setprio 1
	s_waitcnt lgkmcnt(0)
	v_mfma_f32_16x16x32_bf16 v[124:127], v[166:169], v[198:201], v[124:127]
	v_mfma_f32_16x16x32_bf16 v[120:123], v[174:177], v[198:201], v[120:123]
	v_mfma_f32_16x16x32_bf16 v[116:119], v[166:169], v[206:209], v[116:119]
	v_mfma_f32_16x16x32_bf16 v[108:111], v[174:177], v[206:209], v[108:111]
	v_mfma_f32_16x16x32_bf16 v[100:103], v[166:169], v[214:217], v[100:103]
	v_mfma_f32_16x16x32_bf16 v[92:95], v[174:177], v[214:217], v[92:95]
	v_mfma_f32_16x16x32_bf16 v[84:87], v[166:169], v[222:225], v[84:87]
	v_mfma_f32_16x16x32_bf16 v[76:79], v[174:177], v[222:225], v[76:79]
	v_mfma_f32_16x16x32_bf16 v[124:127], v[170:173], v[202:205], v[124:127]
	v_mfma_f32_16x16x32_bf16 v[120:123], v[178:181], v[202:205], v[120:123]
	v_mfma_f32_16x16x32_bf16 v[116:119], v[170:173], v[210:213], v[116:119]
	v_mfma_f32_16x16x32_bf16 v[108:111], v[178:181], v[210:213], v[108:111]
	v_mfma_f32_16x16x32_bf16 v[100:103], v[170:173], v[218:221], v[100:103]
	v_mfma_f32_16x16x32_bf16 v[92:95], v[178:181], v[218:221], v[92:95]
	v_mfma_f32_16x16x32_bf16 v[84:87], v[170:173], v[226:229], v[84:87]
	v_mfma_f32_16x16x32_bf16 v[76:79], v[178:181], v[226:229], v[76:79]
	s_setprio 0
	s_setprio 1
	v_mfma_f32_16x16x32_bf16 v[112:115], v[182:185], v[198:201], v[112:115]
	v_mfma_f32_16x16x32_bf16 v[104:107], v[190:193], v[198:201], v[104:107]
	v_mfma_f32_16x16x32_bf16 v[96:99], v[182:185], v[206:209], v[96:99]
	v_mfma_f32_16x16x32_bf16 v[88:91], v[190:193], v[206:209], v[88:91]
	v_mfma_f32_16x16x32_bf16 v[80:83], v[182:185], v[214:217], v[80:83]
	v_mfma_f32_16x16x32_bf16 v[72:75], v[190:193], v[214:217], v[72:75]
	v_mfma_f32_16x16x32_bf16 v[68:71], v[182:185], v[222:225], v[68:71]
	v_mfma_f32_16x16x32_bf16 v[64:67], v[190:193], v[222:225], v[64:67]
	v_mfma_f32_16x16x32_bf16 v[112:115], v[186:189], v[202:205], v[112:115]
	v_mfma_f32_16x16x32_bf16 v[104:107], v[194:197], v[202:205], v[104:107]
	v_mfma_f32_16x16x32_bf16 v[96:99], v[186:189], v[210:213], v[96:99]
	v_mfma_f32_16x16x32_bf16 v[88:91], v[194:197], v[210:213], v[88:91]
	v_mfma_f32_16x16x32_bf16 v[80:83], v[186:189], v[218:221], v[80:83]
	v_mfma_f32_16x16x32_bf16 v[72:75], v[194:197], v[218:221], v[72:75]
	s_setprio 2
	s_barrier
	v_mfma_f32_16x16x32_bf16 v[68:71], v[186:189], v[226:229], v[68:71]
	v_mfma_f32_16x16x32_bf16 v[64:67], v[194:197], v[226:229], v[64:67]
	s_setprio 0
	s_mov_b32 m0, s84
	v_lshl_add_u64 v[230:231], s[76:77], 0, v[138:139]
	s_add_u32 s52, s76, 0x80000
	ds_read_b128 v[198:201], v164 offset:16384
	ds_read_b128 v[202:205], v164 offset:17408
	ds_read_b128 v[206:209], v164 offset:18432
	ds_read_b128 v[210:213], v164 offset:19456
	ds_read_b128 v[214:217], v164 offset:20480
	ds_read_b128 v[218:221], v164 offset:21504
	ds_read_b128 v[222:225], v164 offset:22528
	ds_read_b128 v[226:229], v164 offset:23552
	global_load_lds_dwordx4 v[230:231], off
	v_lshl_add_u64 v[232:233], s[76:77], 0, v[142:143]
	s_mov_b32 m0, s85
	s_addc_u32 s53, s77, 0
	global_load_lds_dwordx4 v[232:233], off
	v_lshl_add_u64 v[234:235], s[52:53], 0, v[138:139]
	s_mov_b32 m0, s86
	v_lshl_add_u64 v[236:237], s[78:79], 0, v[140:141]
	global_load_lds_dwordx4 v[234:235], off
	v_lshl_add_u64 v[234:235], s[52:53], 0, v[142:143]
	s_mov_b32 m0, s87
	s_nop 0
	global_load_lds_dwordx4 v[234:235], off
	v_lshl_add_u64 v[234:235], s[78:79], 0, v[136:137]
	s_mov_b32 m0, s10
	s_nop 0
	global_load_lds_dwordx4 v[234:235], off
	s_mov_b32 m0, s11
	s_nop 0
	global_load_lds_dwordx4 v[236:237], off
	s_waitcnt vmcnt(8)
	s_waitcnt lgkmcnt(0)
	s_barrier
; #define PG8_STAGE(bufoff, gbase, voff) do { _Pragma("unroll") for (int _i = 0; _i < 2; ++_i) \
;         __builtin_amdgcn_global_load_lds((const unsigned*)((const char*)(gbase) + (voff)[_i]), (PG8_LAS unsigned*)(lds + (bufoff) + ldsw + _i * 8192), 16, 0, 0); } while (0)
; #define PG8_LDA(dst, b, h) do { _Pragma("unroll") for (int m = 0; m < 4; ++m) _Pragma("unroll") for (int k = 0; k < 2; ++k) dst[m][k] = *(const PG8_LAS bf16x8*)(lds + PG8_SA(b, h) + aoff + m * 2048 + k * 1024); } while (0)
; #define PG8_LDB(dst, b, h) do { _Pragma("unroll") for (int n = 0; n < 2; ++n) _Pragma("unroll") for (int k = 0; k < 2; ++k) dst[n][k] = *(const PG8_LAS bf16x8*)(lds + PG8_SB(b, h) + boff + n * 2048 + k * 1024); } while (0)
; #define PG8_MMA(ai, bj, At, Bt) do { __builtin_amdgcn_s_setprio(1); _Pragma("unroll") for (int m = 0; m < 4; ++m) _Pragma("unroll") for (int n = 0; n < 2; ++n) _Pragma("unroll") for (int k = 0; k < 2; ++k) \
;         acc[ai][bj][m][n] = __builtin_amdgcn_mfma_f32_16x16x32_bf16(Bt[n][k], At[m][k], acc[ai][bj][m][n], 0, 0, 0); __builtin_amdgcn_s_setprio(0); } while (0)
; #define PG8_WAIT_V(n) asm volatile("s_waitcnt vmcnt(" #n ")" ::: "memory")
; #define PG8_WAIT_L(n) asm volatile("s_waitcnt lgkmcnt(" #n ")" ::: "memory")
; #define PG8_BAR __builtin_amdgcn_s_barrier()
; #define PG8_SCHED __builtin_amdgcn_sched_barrier(0)
; template <class Epi, class Sched, bool ALIGN_EPI = false, bool SP2 = false>
; __device__ __forceinline__ void gemm_phase(PG8_LAS unsigned char* lds, const Gemm g, const Sched& S, const Epi& E) {
;     ...
;             PG8_WAIT_V(8); PG8_WAIT_L(0); PG8_BAR; PG8_MMA(1, 0, At, B0); PG8_MMA(1, 1, At, B1); PG8_BAR; PG8_SCHED;
;             PG8_LDB(B0, 1, 0); PG8_LDB(B1, 1, 1); PG8_SCHED; PG8_LDA(At, 1, 0); PG8_STAGE(PG8_SA(0, 1), a2 + hstep, voffA);
;             PG8_WAIT_V(8); PG8_WAIT_L(0); PG8_BAR; PG8_MMA(0, 0, At, B0); PG8_MMA(0, 1, At, B1); PG8_BAR; PG8_SCHED;
	s_setprio 1
	s_waitcnt lgkmcnt(0)
	v_mfma_f32_16x16x32_bf16 v[60:63], v[166:169], v[198:201], v[60:63]
	v_mfma_f32_16x16x32_bf16 v[56:59], v[174:177], v[198:201], v[56:59]
	v_mfma_f32_16x16x32_bf16 v[52:55], v[166:169], v[206:209], v[52:55]
	v_mfma_f32_16x16x32_bf16 v[44:47], v[174:177], v[206:209], v[44:47]
	v_mfma_f32_16x16x32_bf16 v[36:39], v[166:169], v[214:217], v[36:39]
	v_mfma_f32_16x16x32_bf16 v[28:31], v[174:177], v[214:217], v[28:31]
	v_mfma_f32_16x16x32_bf16 v[20:23], v[166:169], v[222:225], v[20:23]
	v_mfma_f32_16x16x32_bf16 v[12:15], v[174:177], v[222:225], v[12:15]
	v_mfma_f32_16x16x32_bf16 v[60:63], v[170:173], v[202:205], v[60:63]
	v_mfma_f32_16x16x32_bf16 v[56:59], v[178:181], v[202:205], v[56:59]
	v_mfma_f32_16x16x32_bf16 v[52:55], v[170:173], v[210:213], v[52:55]
	v_mfma_f32_16x16x32_bf16 v[44:47], v[178:181], v[210:213], v[44:47]
	v_mfma_f32_16x16x32_bf16 v[36:39], v[170:173], v[218:221], v[36:39]
	v_mfma_f32_16x16x32_bf16 v[28:31], v[178:181], v[218:221], v[28:31]
	v_mfma_f32_16x16x32_bf16 v[20:23], v[170:173], v[226:229], v[20:23]
	v_mfma_f32_16x16x32_bf16 v[12:15], v[178:181], v[226:229], v[12:15]
	s_setprio 0
	s_setprio 1
	v_mfma_f32_16x16x32_bf16 v[48:51], v[182:185], v[198:201], v[48:51]
	v_mfma_f32_16x16x32_bf16 v[40:43], v[190:193], v[198:201], v[40:43]
	v_mfma_f32_16x16x32_bf16 v[32:35], v[182:185], v[206:209], v[32:35]
	v_mfma_f32_16x16x32_bf16 v[24:27], v[190:193], v[206:209], v[24:27]
	v_mfma_f32_16x16x32_bf16 v[16:19], v[182:185], v[214:217], v[16:19]
	v_mfma_f32_16x16x32_bf16 v[8:11], v[190:193], v[214:217], v[8:11]
	v_mfma_f32_16x16x32_bf16 v[4:7], v[182:185], v[222:225], v[4:7]
	v_mfma_f32_16x16x32_bf16 v[0:3], v[190:193], v[222:225], v[0:3]
	v_mfma_f32_16x16x32_bf16 v[48:51], v[186:189], v[202:205], v[48:51]
	v_mfma_f32_16x16x32_bf16 v[40:43], v[194:197], v[202:205], v[40:43]
	v_mfma_f32_16x16x32_bf16 v[32:35], v[186:189], v[210:213], v[32:35]
	v_mfma_f32_16x16x32_bf16 v[24:27], v[194:197], v[210:213], v[24:27]
	v_mfma_f32_16x16x32_bf16 v[16:19], v[186:189], v[218:221], v[16:19]
	v_mfma_f32_16x16x32_bf16 v[8:11], v[194:197], v[218:221], v[8:11]
	s_setprio 2
	s_barrier
	v_mfma_f32_16x16x32_bf16 v[4:7], v[186:189], v[226:229], v[4:7]
	v_mfma_f32_16x16x32_bf16 v[0:3], v[194:197], v[226:229], v[0:3]
	s_setprio 0
	ds_read_b128 v[166:169], v148
	ds_read_b128 v[170:173], v148 offset:1024
	ds_read_b128 v[174:177], v148 offset:2048
	ds_read_b128 v[178:181], v148 offset:3072
	ds_read_b128 v[182:185], v165
	ds_read_b128 v[186:189], v165 offset:1024
	ds_read_b128 v[190:193], v165 offset:2048
	ds_read_b128 v[194:197], v165 offset:3072
	s_add_u32 s52, s78, 0x80000
	s_addc_u32 s53, s79, 0
	s_mov_b32 m0, s28
	v_lshl_add_u64 v[238:239], s[52:53], 0, v[136:137]
	ds_read_b128 v[198:201], v164 offset:32768
	ds_read_b128 v[202:205], v164 offset:33792
	ds_read_b128 v[206:209], v164 offset:34816
	ds_read_b128 v[210:213], v164 offset:35840
	ds_read_b128 v[214:217], v164 offset:36864
	ds_read_b128 v[218:221], v164 offset:37888
	ds_read_b128 v[222:225], v164 offset:38912
	ds_read_b128 v[226:229], v164 offset:39936
	global_load_lds_dwordx4 v[238:239], off
	v_lshl_add_u64 v[238:239], s[52:53], 0, v[140:141]
	s_mov_b32 m0, s29
	s_nop 0
	global_load_lds_dwordx4 v[238:239], off
	s_waitcnt vmcnt(8)
	s_waitcnt lgkmcnt(0)
	s_barrier
	s_setprio 1
	s_waitcnt lgkmcnt(0)
	v_mfma_f32_16x16x32_bf16 v[124:127], v[166:169], v[198:201], v[124:127]
	v_mfma_f32_16x16x32_bf16 v[120:123], v[174:177], v[198:201], v[120:123]
	v_mfma_f32_16x16x32_bf16 v[116:119], v[166:169], v[206:209], v[116:119]
	v_mfma_f32_16x16x32_bf16 v[108:111], v[174:177], v[206:209], v[108:111]
	v_mfma_f32_16x16x32_bf16 v[100:103], v[166:169], v[214:217], v[100:103]
	v_mfma_f32_16x16x32_bf16 v[92:95], v[174:177], v[214:217], v[92:95]
	v_mfma_f32_16x16x32_bf16 v[84:87], v[166:169], v[222:225], v[84:87]
	v_mfma_f32_16x16x32_bf16 v[76:79], v[174:177], v[222:225], v[76:79]
	v_mfma_f32_16x16x32_bf16 v[124:127], v[170:173], v[202:205], v[124:127]
	v_mfma_f32_16x16x32_bf16 v[120:123], v[178:181], v[202:205], v[120:123]
	v_mfma_f32_16x16x32_bf16 v[116:119], v[170:173], v[210:213], v[116:119]
	v_mfma_f32_16x16x32_bf16 v[108:111], v[178:181], v[210:213], v[108:111]
	v_mfma_f32_16x16x32_bf16 v[100:103], v[170:173], v[218:221], v[100:103]
	v_mfma_f32_16x16x32_bf16 v[92:95], v[178:181], v[218:221], v[92:95]
	v_mfma_f32_16x16x32_bf16 v[84:87], v[170:173], v[226:229], v[84:87]
	v_mfma_f32_16x16x32_bf16 v[76:79], v[178:181], v[226:229], v[76:79]
	s_setprio 0
	s_setprio 1
	v_mfma_f32_16x16x32_bf16 v[112:115], v[182:185], v[198:201], v[112:115]
	v_mfma_f32_16x16x32_bf16 v[104:107], v[190:193], v[198:201], v[104:107]
	v_mfma_f32_16x16x32_bf16 v[96:99], v[182:185], v[206:209], v[96:99]
	v_mfma_f32_16x16x32_bf16 v[88:91], v[190:193], v[206:209], v[88:91]
	v_mfma_f32_16x16x32_bf16 v[80:83], v[182:185], v[214:217], v[80:83]
	v_mfma_f32_16x16x32_bf16 v[72:75], v[190:193], v[214:217], v[72:75]
	v_mfma_f32_16x16x32_bf16 v[68:71], v[182:185], v[222:225], v[68:71]
	v_mfma_f32_16x16x32_bf16 v[64:67], v[190:193], v[222:225], v[64:67]
	v_mfma_f32_16x16x32_bf16 v[112:115], v[186:189], v[202:205], v[112:115]
	v_mfma_f32_16x16x32_bf16 v[104:107], v[194:197], v[202:205], v[104:107]
	v_mfma_f32_16x16x32_bf16 v[96:99], v[186:189], v[210:213], v[96:99]
	v_mfma_f32_16x16x32_bf16 v[88:91], v[194:197], v[210:213], v[88:91]
	v_mfma_f32_16x16x32_bf16 v[80:83], v[186:189], v[218:221], v[80:83]
	v_mfma_f32_16x16x32_bf16 v[72:75], v[194:197], v[218:221], v[72:75]
	s_setprio 2
	s_barrier
; #define PG8_STAGE(bufoff, gbase, voff) do { _Pragma("unroll") for (int _i = 0; _i < 2; ++_i) \
;         __builtin_amdgcn_global_load_lds((const unsigned*)((const char*)(gbase) + (voff)[_i]), (PG8_LAS unsigned*)(lds + (bufoff) + ldsw + _i * 8192), 16, 0, 0); } while (0)
; #define PG8_LDA(dst, b, h) do { _Pragma("unroll") for (int m = 0; m < 4; ++m) _Pragma("unroll") for (int k = 0; k < 2; ++k) dst[m][k] = *(const PG8_LAS bf16x8*)(lds + PG8_SA(b, h) + aoff + m * 2048 + k * 1024); } while (0)
; #define PG8_MMA(ai, bj, At, Bt) do { __builtin_amdgcn_s_setprio(1); _Pragma("unroll") for (int m = 0; m < 4; ++m) _Pragma("unroll") for (int n = 0; n < 2; ++n) _Pragma("unroll") for (int k = 0; k < 2; ++k) \
;         acc[ai][bj][m][n] = __builtin_amdgcn_mfma_f32_16x16x32_bf16(Bt[n][k], At[m][k], acc[ai][bj][m][n], 0, 0, 0); __builtin_amdgcn_s_setprio(0); } while (0)
; #define PG8_WAIT_V(n) asm volatile("s_waitcnt vmcnt(" #n ")" ::: "memory")
; #define PG8_WAIT_L(n) asm volatile("s_waitcnt lgkmcnt(" #n ")" ::: "memory")
; #define PG8_BAR __builtin_amdgcn_s_barrier()
; #define PG8_SCHED __builtin_amdgcn_sched_barrier(0)
; template <class Epi, class Sched, bool ALIGN_EPI = false, bool SP2 = false>
; __device__ __forceinline__ void gemm_phase(PG8_LAS unsigned char* lds, const Gemm g, const Sched& S, const Epi& E) {
;     ...
;             PG8_WAIT_V(8); PG8_WAIT_L(0); PG8_BAR; PG8_MMA(0, 0, At, B0); PG8_MMA(0, 1, At, B1); PG8_BAR; PG8_SCHED;
;             PG8_LDA(At, 1, 1); PG8_STAGE(PG8_SB(1, 0), b3, voffB); PG8_STAGE(PG8_SB(1, 1), b3 + hstep, voffB); PG8_STAGE(PG8_SA(1, 0), a3, voffA);
;             PG8_WAIT_V(8); PG8_WAIT_L(0); PG8_BAR; PG8_MMA(1, 0, At, B0); PG8_MMA(1, 1, At, B1); PG8_BAR; PG8_SCHED;
	v_mfma_f32_16x16x32_bf16 v[68:71], v[186:189], v[226:229], v[68:71]
	v_mfma_f32_16x16x32_bf16 v[64:67], v[194:197], v[226:229], v[64:67]
	s_setprio 0
	s_mov_b32 m0, s89
	v_lshl_add_u64 v[230:231], v[230:231], 0, s[12:13]
	ds_read_b128 v[198:201], v164 offset:49152
	ds_read_b128 v[202:205], v164 offset:50176
	ds_read_b128 v[206:209], v164 offset:51200
	ds_read_b128 v[210:213], v164 offset:52224
	ds_read_b128 v[214:217], v164 offset:53248
	ds_read_b128 v[218:221], v164 offset:54272
	ds_read_b128 v[222:225], v164 offset:55296
	ds_read_b128 v[226:229], v164 offset:56320
	global_load_lds_dwordx4 v[230:231], off
	s_add_i32 m0, s89, 0x2000
	s_add_u32 s52, s76, 0x80080
	v_lshl_add_u64 v[230:231], v[232:233], 0, s[12:13]
	s_addc_u32 s53, s77, 0
	s_add_i32 s56, s88, s3
	global_load_lds_dwordx4 v[230:231], off
	v_lshl_add_u64 v[230:231], s[52:53], 0, v[138:139]
	s_mov_b32 m0, s56
	s_nop 0
	global_load_lds_dwordx4 v[230:231], off
	v_lshl_add_u64 v[230:231], s[52:53], 0, v[142:143]
	s_add_i32 m0, s56, 0x2000
	s_nop 0
	global_load_lds_dwordx4 v[230:231], off
	v_lshl_add_u64 v[230:231], v[234:235], 0, s[12:13]
	s_mov_b32 m0, s38
	s_nop 0
	global_load_lds_dwordx4 v[230:231], off
	v_lshl_add_u64 v[230:231], v[236:237], 0, s[12:13]
	s_mov_b32 m0, s39
	s_nop 0
	global_load_lds_dwordx4 v[230:231], off
	s_waitcnt vmcnt(8)
	s_waitcnt lgkmcnt(0)
	s_barrier
	s_setprio 1
	s_waitcnt lgkmcnt(0)
	v_mfma_f32_16x16x32_bf16 v[60:63], v[166:169], v[198:201], v[60:63]
	v_mfma_f32_16x16x32_bf16 v[56:59], v[174:177], v[198:201], v[56:59]
	v_mfma_f32_16x16x32_bf16 v[52:55], v[166:169], v[206:209], v[52:55]
	v_mfma_f32_16x16x32_bf16 v[44:47], v[174:177], v[206:209], v[44:47]
	v_mfma_f32_16x16x32_bf16 v[36:39], v[166:169], v[214:217], v[36:39]
	v_mfma_f32_16x16x32_bf16 v[28:31], v[174:177], v[214:217], v[28:31]
	v_mfma_f32_16x16x32_bf16 v[20:23], v[166:169], v[222:225], v[20:23]
	v_mfma_f32_16x16x32_bf16 v[12:15], v[174:177], v[222:225], v[12:15]
	v_mfma_f32_16x16x32_bf16 v[60:63], v[170:173], v[202:205], v[60:63]
	v_mfma_f32_16x16x32_bf16 v[56:59], v[178:181], v[202:205], v[56:59]
	v_mfma_f32_16x16x32_bf16 v[52:55], v[170:173], v[210:213], v[52:55]
	v_mfma_f32_16x16x32_bf16 v[44:47], v[178:181], v[210:213], v[44:47]
	v_mfma_f32_16x16x32_bf16 v[36:39], v[170:173], v[218:221], v[36:39]
	v_mfma_f32_16x16x32_bf16 v[28:31], v[178:181], v[218:221], v[28:31]
	v_mfma_f32_16x16x32_bf16 v[20:23], v[170:173], v[226:229], v[20:23]
	v_mfma_f32_16x16x32_bf16 v[12:15], v[178:181], v[226:229], v[12:15]
	s_setprio 0
	s_setprio 1
	v_mfma_f32_16x16x32_bf16 v[48:51], v[182:185], v[198:201], v[48:51]
	v_mfma_f32_16x16x32_bf16 v[40:43], v[190:193], v[198:201], v[40:43]
	v_mfma_f32_16x16x32_bf16 v[32:35], v[182:185], v[206:209], v[32:35]
	v_mfma_f32_16x16x32_bf16 v[24:27], v[190:193], v[206:209], v[24:27]
	v_mfma_f32_16x16x32_bf16 v[16:19], v[182:185], v[214:217], v[16:19]
	v_mfma_f32_16x16x32_bf16 v[8:11], v[190:193], v[214:217], v[8:11]
	v_mfma_f32_16x16x32_bf16 v[4:7], v[182:185], v[222:225], v[4:7]
	v_mfma_f32_16x16x32_bf16 v[0:3], v[190:193], v[222:225], v[0:3]
	v_mfma_f32_16x16x32_bf16 v[48:51], v[186:189], v[202:205], v[48:51]
	v_mfma_f32_16x16x32_bf16 v[40:43], v[194:197], v[202:205], v[40:43]
	v_mfma_f32_16x16x32_bf16 v[32:35], v[186:189], v[210:213], v[32:35]
	v_mfma_f32_16x16x32_bf16 v[24:27], v[194:197], v[210:213], v[24:27]
	v_mfma_f32_16x16x32_bf16 v[16:19], v[186:189], v[218:221], v[16:19]
	v_mfma_f32_16x16x32_bf16 v[8:11], v[194:197], v[218:221], v[8:11]
	s_setprio 2
	s_barrier
	v_mfma_f32_16x16x32_bf16 v[4:7], v[186:189], v[226:229], v[4:7]
	v_mfma_f32_16x16x32_bf16 v[0:3], v[194:197], v[226:229], v[0:3]
	s_setprio 0
	s_add_i32 s51, s51, 2
	s_add_u32 s74, s74, 0x100
	s_addc_u32 s75, s75, 0
	s_add_u32 s37, s37, 0x100
	s_addc_u32 s49, s49, 0
	s_cmp_gt_u32 s51, 5
	s_cbranch_scc0 .LBB0_410
	s_and_b64 vcc, exec, s[14:15]
	s_cbranch_vccz .LBB0_413
	s_barrier

; #define PG8_STAGE(bufoff, gbase, voff) do { _Pragma("unroll") for (int _i = 0; _i < 2; ++_i) \
;         __builtin_amdgcn_global_load_lds((const unsigned*)((const char*)(gbase) + (voff)[_i]), (PG8_LAS unsigned*)(lds + (bufoff) + ldsw + _i * 8192), 16, 0, 0); } while (0)
; #define PG8_LDA(dst, b, h) do { _Pragma("unroll") for (int m = 0; m < 4; ++m) _Pragma("unroll") for (int k = 0; k < 2; ++k) dst[m][k] = *(const PG8_LAS bf16x8*)(lds + PG8_SA(b, h) + aoff + m * 2048 + k * 1024); } while (0)
; #define PG8_LDB(dst, b, h) do { _Pragma("unroll") for (int n = 0; n < 2; ++n) _Pragma("unroll") for (int k = 0; k < 2; ++k) dst[n][k] = *(const PG8_LAS bf16x8*)(lds + PG8_SB(b, h) + boff + n * 2048 + k * 1024); } while (0)
; #define PG8_MMA(ai, bj, At, Bt) do { __builtin_amdgcn_s_setprio(1); _Pragma("unroll") for (int m = 0; m < 4; ++m) _Pragma("unroll") for (int n = 0; n < 2; ++n) _Pragma("unroll") for (int k = 0; k < 2; ++k) \
;         acc[ai][bj][m][n] = __builtin_amdgcn_mfma_f32_16x16x32_bf16(Bt[n][k], At[m][k], acc[ai][bj][m][n], 0, 0, 0); __builtin_amdgcn_s_setprio(0); } while (0)
; #define PG8_WAIT_V(n) asm volatile("s_waitcnt vmcnt(" #n ")" ::: "memory")
; #define PG8_WAIT_L(n) asm volatile("s_waitcnt lgkmcnt(" #n ")" ::: "memory")
; #define PG8_BAR __builtin_amdgcn_s_barrier()
; template <class Epi, class Sched, bool ALIGN_EPI = false, bool SP2 = false>
; __device__ __forceinline__ void gemm_phase(PG8_LAS unsigned char* lds, const Gemm g, const Sched& S, const Epi& E) {
;     ...
;         for (int t = 0; t < nt; t += 2) {
;             const bool last = (t == nt - 2);
;             const char* a1 = cA + (size_t)(t + 1) * kstep;
;             const char* a2 = last ? nA : cA + (size_t)(t + 2) * kstep; const char* b2 = last ? nB : cB + (size_t)(t + 2) * kstep;
;             const char* a3 = a2 + kstep; const char* b3 = b2 + kstep;
;             if constexpr (SP2) {
;             PG8_LDB(B0, 0, 0); PG8_LDB(B1, 0, 1); PG8_SCHED; PG8_LDA(At, 0, 0); PG8_STAGE(PG8_SA(1, 1), a1 + hstep, voffA);
;             PG8_WAIT_V(8); PG8_WAIT_L(0); PG8_BAR; PG8_MMA(0, 0, At, B0); PG8_MMA(0, 1, At, B1); PG8_BAR; PG8_SCHED;
;             PG8_LDA(At, 0, 1); PG8_STAGE(PG8_SB(0, 0), b2, voffB); PG8_STAGE(PG8_SB(0, 1), b2 + hstep, voffB); PG8_STAGE(PG8_SA(0, 0), a2, voffA);
;             PG8_WAIT_V(8); PG8_WAIT_L(0); PG8_BAR; PG8_MMA(1, 0, At, B0); PG8_MMA(1, 1, At, B1); PG8_BAR; PG8_SCHED;
.LBB0_545:
	ds_read_b128 v[112:115], v174
	ds_read_b128 v[116:119], v174 offset:1024
	ds_read_b128 v[120:123], v174 offset:2048
	ds_read_b128 v[124:127], v174 offset:3072
	ds_read_b128 v[164:167], v175
	ds_read_b128 v[168:171], v175 offset:1024
	ds_read_b128 v[178:181], v175 offset:2048
	ds_read_b128 v[182:185], v175 offset:3072
	s_add_u32 s52, s68, 0xfff80080
	s_addc_u32 s53, s69, -1
	s_cmp_eq_u32 s88, 28
	s_cselect_b32 s73, s41, s53
	s_cselect_b32 s72, s84, s52
	s_cselect_b32 s71, s37, s87
	s_cselect_b32 s70, s85, s86
	v_lshl_add_u64 v[218:219], s[68:69], 0, v[156:157]
	s_add_i32 m0, s39, 0xc000
	ds_read_b128 v[186:189], v176
	ds_read_b128 v[190:193], v176 offset:1024
	ds_read_b128 v[194:197], v176 offset:2048
	ds_read_b128 v[198:201], v176 offset:3072
	ds_read_b128 v[202:205], v176 offset:4096
	ds_read_b128 v[206:209], v176 offset:5120
	ds_read_b128 v[210:213], v176 offset:6144
	ds_read_b128 v[214:217], v176 offset:7168
	global_load_lds_dwordx4 v[218:219], off
	v_lshl_add_u64 v[218:219], s[68:69], 0, v[158:159]
	s_add_i32 m0, s39, 0xe000
	s_nop 0
	global_load_lds_dwordx4 v[218:219], off
	s_waitcnt vmcnt(8)
	s_waitcnt lgkmcnt(0)
	s_barrier
	s_setprio 1
	s_waitcnt lgkmcnt(0)
	v_mfma_f32_16x16x32_bf16 v[140:143], v[112:115], v[186:189], v[140:143]
	v_mfma_f32_16x16x32_bf16 v[136:139], v[120:123], v[186:189], v[136:139]
	v_mfma_f32_16x16x32_bf16 v[108:111], v[112:115], v[194:197], v[108:111]
	v_mfma_f32_16x16x32_bf16 v[104:107], v[120:123], v[194:197], v[104:107]
	v_mfma_f32_16x16x32_bf16 v[92:95], v[112:115], v[202:205], v[92:95]
	v_mfma_f32_16x16x32_bf16 v[88:91], v[120:123], v[202:205], v[88:91]
	v_mfma_f32_16x16x32_bf16 v[76:79], v[112:115], v[210:213], v[76:79]
	v_mfma_f32_16x16x32_bf16 v[72:75], v[120:123], v[210:213], v[72:75]
	v_mfma_f32_16x16x32_bf16 v[140:143], v[116:119], v[190:193], v[140:143]
	v_mfma_f32_16x16x32_bf16 v[136:139], v[124:127], v[190:193], v[136:139]
	v_mfma_f32_16x16x32_bf16 v[108:111], v[116:119], v[198:201], v[108:111]
	v_mfma_f32_16x16x32_bf16 v[104:107], v[124:127], v[198:201], v[104:107]
	v_mfma_f32_16x16x32_bf16 v[92:95], v[116:119], v[206:209], v[92:95]
	v_mfma_f32_16x16x32_bf16 v[88:91], v[124:127], v[206:209], v[88:91]
	v_mfma_f32_16x16x32_bf16 v[76:79], v[116:119], v[214:217], v[76:79]
	v_mfma_f32_16x16x32_bf16 v[72:75], v[124:127], v[214:217], v[72:75]
	s_setprio 0
	s_setprio 1
	v_mfma_f32_16x16x32_bf16 v[132:135], v[164:167], v[186:189], v[132:135]
	v_mfma_f32_16x16x32_bf16 v[128:131], v[178:181], v[186:189], v[128:131]
	v_mfma_f32_16x16x32_bf16 v[100:103], v[164:167], v[194:197], v[100:103]
	v_mfma_f32_16x16x32_bf16 v[96:99], v[178:181], v[194:197], v[96:99]
	v_mfma_f32_16x16x32_bf16 v[84:87], v[164:167], v[202:205], v[84:87]
	v_mfma_f32_16x16x32_bf16 v[80:83], v[178:181], v[202:205], v[80:83]
	v_mfma_f32_16x16x32_bf16 v[68:71], v[164:167], v[210:213], v[68:71]
	v_mfma_f32_16x16x32_bf16 v[64:67], v[178:181], v[210:213], v[64:67]
	v_mfma_f32_16x16x32_bf16 v[132:135], v[168:171], v[190:193], v[132:135]
	v_mfma_f32_16x16x32_bf16 v[128:131], v[182:185], v[190:193], v[128:131]
	v_mfma_f32_16x16x32_bf16 v[100:103], v[168:171], v[198:201], v[100:103]
	v_mfma_f32_16x16x32_bf16 v[96:99], v[182:185], v[198:201], v[96:99]
	v_mfma_f32_16x16x32_bf16 v[84:87], v[168:171], v[206:209], v[84:87]
	v_mfma_f32_16x16x32_bf16 v[80:83], v[182:185], v[206:209], v[80:83]
	s_setprio 2
	s_barrier
	v_mfma_f32_16x16x32_bf16 v[68:71], v[168:171], v[214:217], v[68:71]
	v_mfma_f32_16x16x32_bf16 v[64:67], v[182:185], v[214:217], v[64:67]
	s_setprio 0
	s_add_i32 s52, s81, s29
	v_lshl_add_u64 v[218:219], s[70:71], 0, v[152:153]
	s_mov_b32 m0, s52
	ds_read_b128 v[186:189], v176 offset:16384
	ds_read_b128 v[190:193], v176 offset:17408
	ds_read_b128 v[194:197], v176 offset:18432
	ds_read_b128 v[198:201], v176 offset:19456
	ds_read_b128 v[202:205], v176 offset:20480
	ds_read_b128 v[206:209], v176 offset:21504
	ds_read_b128 v[210:213], v176 offset:22528
	ds_read_b128 v[214:217], v176 offset:23552
	global_load_lds_dwordx4 v[218:219], off
	s_add_i32 m0, s52, 0x2000
	s_add_u32 s52, s70, 0x80000
	v_lshl_add_u64 v[220:221], s[70:71], 0, v[148:149]
	s_addc_u32 s53, s71, 0
	s_add_i32 s56, s82, s29
	global_load_lds_dwordx4 v[220:221], off
	v_lshl_add_u64 v[222:223], s[52:53], 0, v[152:153]
	s_mov_b32 m0, s56
	v_lshl_add_u64 v[224:225], s[72:73], 0, v[150:151]
	global_load_lds_dwordx4 v[222:223], off
	v_lshl_add_u64 v[222:223], s[52:53], 0, v[148:149]
	s_add_i32 m0, s56, 0x2000
	s_nop 0
	global_load_lds_dwordx4 v[222:223], off
	v_lshl_add_u64 v[222:223], s[72:73], 0, v[154:155]
	s_mov_b32 m0, s39
	s_nop 0
	global_load_lds_dwordx4 v[222:223], off
	s_mov_b32 m0, s55
	s_nop 0
	global_load_lds_dwordx4 v[224:225], off
	s_waitcnt vmcnt(8)
	s_waitcnt lgkmcnt(0)
	s_barrier
; #define PG8_STAGE(bufoff, gbase, voff) do { _Pragma("unroll") for (int _i = 0; _i < 2; ++_i) \
;         __builtin_amdgcn_global_load_lds((const unsigned*)((const char*)(gbase) + (voff)[_i]), (PG8_LAS unsigned*)(lds + (bufoff) + ldsw + _i * 8192), 16, 0, 0); } while (0)
; #define PG8_LDA(dst, b, h) do { _Pragma("unroll") for (int m = 0; m < 4; ++m) _Pragma("unroll") for (int k = 0; k < 2; ++k) dst[m][k] = *(const PG8_LAS bf16x8*)(lds + PG8_SA(b, h) + aoff + m * 2048 + k * 1024); } while (0)
; #define PG8_LDB(dst, b, h) do { _Pragma("unroll") for (int n = 0; n < 2; ++n) _Pragma("unroll") for (int k = 0; k < 2; ++k) dst[n][k] = *(const PG8_LAS bf16x8*)(lds + PG8_SB(b, h) + boff + n * 2048 + k * 1024); } while (0)
; #define PG8_MMA(ai, bj, At, Bt) do { __builtin_amdgcn_s_setprio(1); _Pragma("unroll") for (int m = 0; m < 4; ++m) _Pragma("unroll") for (int n = 0; n < 2; ++n) _Pragma("unroll") for (int k = 0; k < 2; ++k) \
;         acc[ai][bj][m][n] = __builtin_amdgcn_mfma_f32_16x16x32_bf16(Bt[n][k], At[m][k], acc[ai][bj][m][n], 0, 0, 0); __builtin_amdgcn_s_setprio(0); } while (0)
; #define PG8_WAIT_V(n) asm volatile("s_waitcnt vmcnt(" #n ")" ::: "memory")
; #define PG8_WAIT_L(n) asm volatile("s_waitcnt lgkmcnt(" #n ")" ::: "memory")
; #define PG8_BAR __builtin_amdgcn_s_barrier()
; #define PG8_SCHED __builtin_amdgcn_sched_barrier(0)
; template <class Epi, class Sched, bool ALIGN_EPI = false, bool SP2 = false>
; __device__ __forceinline__ void gemm_phase(PG8_LAS unsigned char* lds, const Gemm g, const Sched& S, const Epi& E) {
;     ...
;             PG8_WAIT_V(8); PG8_WAIT_L(0); PG8_BAR; PG8_MMA(1, 0, At, B0); PG8_MMA(1, 1, At, B1); PG8_BAR; PG8_SCHED;
;             PG8_LDB(B0, 1, 0); PG8_LDB(B1, 1, 1); PG8_SCHED; PG8_LDA(At, 1, 0); PG8_STAGE(PG8_SA(0, 1), a2 + hstep, voffA);
;             PG8_WAIT_V(8); PG8_WAIT_L(0); PG8_BAR; PG8_MMA(0, 0, At, B0); PG8_MMA(0, 1, At, B1); PG8_BAR; PG8_SCHED;
	s_setprio 1
	s_waitcnt lgkmcnt(0)
	v_mfma_f32_16x16x32_bf16 v[60:63], v[112:115], v[186:189], v[60:63]
	v_mfma_f32_16x16x32_bf16 v[56:59], v[120:123], v[186:189], v[56:59]
	v_mfma_f32_16x16x32_bf16 v[44:47], v[112:115], v[194:197], v[44:47]
	v_mfma_f32_16x16x32_bf16 v[40:43], v[120:123], v[194:197], v[40:43]
	v_mfma_f32_16x16x32_bf16 v[28:31], v[112:115], v[202:205], v[28:31]
	v_mfma_f32_16x16x32_bf16 v[24:27], v[120:123], v[202:205], v[24:27]
	v_mfma_f32_16x16x32_bf16 v[12:15], v[112:115], v[210:213], v[12:15]
	v_mfma_f32_16x16x32_bf16 v[8:11], v[120:123], v[210:213], v[8:11]
	v_mfma_f32_16x16x32_bf16 v[60:63], v[116:119], v[190:193], v[60:63]
	v_mfma_f32_16x16x32_bf16 v[56:59], v[124:127], v[190:193], v[56:59]
	v_mfma_f32_16x16x32_bf16 v[44:47], v[116:119], v[198:201], v[44:47]
	v_mfma_f32_16x16x32_bf16 v[40:43], v[124:127], v[198:201], v[40:43]
	v_mfma_f32_16x16x32_bf16 v[28:31], v[116:119], v[206:209], v[28:31]
	v_mfma_f32_16x16x32_bf16 v[24:27], v[124:127], v[206:209], v[24:27]
	v_mfma_f32_16x16x32_bf16 v[12:15], v[116:119], v[214:217], v[12:15]
	v_mfma_f32_16x16x32_bf16 v[8:11], v[124:127], v[214:217], v[8:11]
	s_setprio 0
	s_setprio 1
	v_mfma_f32_16x16x32_bf16 v[52:55], v[164:167], v[186:189], v[52:55]
	v_mfma_f32_16x16x32_bf16 v[48:51], v[178:181], v[186:189], v[48:51]
	v_mfma_f32_16x16x32_bf16 v[36:39], v[164:167], v[194:197], v[36:39]
	v_mfma_f32_16x16x32_bf16 v[32:35], v[178:181], v[194:197], v[32:35]
	v_mfma_f32_16x16x32_bf16 v[20:23], v[164:167], v[202:205], v[20:23]
	v_mfma_f32_16x16x32_bf16 v[16:19], v[178:181], v[202:205], v[16:19]
	v_mfma_f32_16x16x32_bf16 v[4:7], v[164:167], v[210:213], v[4:7]
	v_mfma_f32_16x16x32_bf16 v[0:3], v[178:181], v[210:213], v[0:3]
	v_mfma_f32_16x16x32_bf16 v[52:55], v[168:171], v[190:193], v[52:55]
	v_mfma_f32_16x16x32_bf16 v[48:51], v[182:185], v[190:193], v[48:51]
	v_mfma_f32_16x16x32_bf16 v[36:39], v[168:171], v[198:201], v[36:39]
	v_mfma_f32_16x16x32_bf16 v[32:35], v[182:185], v[198:201], v[32:35]
	v_mfma_f32_16x16x32_bf16 v[20:23], v[168:171], v[206:209], v[20:23]
	v_mfma_f32_16x16x32_bf16 v[16:19], v[182:185], v[206:209], v[16:19]
	s_setprio 2
	s_barrier
	v_mfma_f32_16x16x32_bf16 v[4:7], v[168:171], v[214:217], v[4:7]
	v_mfma_f32_16x16x32_bf16 v[0:3], v[182:185], v[214:217], v[0:3]
	s_setprio 0
	s_add_i32 s56, 0, 0x18000
	s_add_i32 s57, 0, 0x1c000
	v_add_u32_e32 v124, s56, v172
	v_add_u32_e32 v177, s57, v172
	ds_read_b128 v[112:115], v124
	ds_read_b128 v[116:119], v124 offset:1024
	ds_read_b128 v[120:123], v124 offset:2048
	ds_read_b128 v[124:127], v124 offset:3072
	ds_read_b128 v[164:167], v177
	ds_read_b128 v[168:171], v177 offset:1024
	ds_read_b128 v[178:181], v177 offset:2048
	ds_read_b128 v[182:185], v177 offset:3072
	s_add_u32 s52, s72, 0x80000
	s_addc_u32 s53, s73, 0
	s_mov_b32 m0, s74
	v_lshl_add_u64 v[226:227], s[52:53], 0, v[154:155]
	ds_read_b128 v[186:189], v176 offset:32768
	ds_read_b128 v[190:193], v176 offset:33792
	ds_read_b128 v[194:197], v176 offset:34816
	ds_read_b128 v[198:201], v176 offset:35840
	ds_read_b128 v[202:205], v176 offset:36864
	ds_read_b128 v[206:209], v176 offset:37888
	ds_read_b128 v[210:213], v176 offset:38912
	ds_read_b128 v[214:217], v176 offset:39936
	global_load_lds_dwordx4 v[226:227], off
	v_lshl_add_u64 v[226:227], s[52:53], 0, v[150:151]
	s_mov_b32 m0, s75
	s_nop 0
	global_load_lds_dwordx4 v[226:227], off
	s_waitcnt vmcnt(8)
	s_waitcnt lgkmcnt(0)
	s_barrier
	s_setprio 1
	s_waitcnt lgkmcnt(0)
	v_mfma_f32_16x16x32_bf16 v[140:143], v[112:115], v[186:189], v[140:143]
	v_mfma_f32_16x16x32_bf16 v[136:139], v[120:123], v[186:189], v[136:139]
	v_mfma_f32_16x16x32_bf16 v[108:111], v[112:115], v[194:197], v[108:111]
	v_mfma_f32_16x16x32_bf16 v[104:107], v[120:123], v[194:197], v[104:107]
	v_mfma_f32_16x16x32_bf16 v[92:95], v[112:115], v[202:205], v[92:95]
	v_mfma_f32_16x16x32_bf16 v[88:91], v[120:123], v[202:205], v[88:91]
	v_mfma_f32_16x16x32_bf16 v[76:79], v[112:115], v[210:213], v[76:79]
	v_mfma_f32_16x16x32_bf16 v[72:75], v[120:123], v[210:213], v[72:75]
	v_mfma_f32_16x16x32_bf16 v[140:143], v[116:119], v[190:193], v[140:143]
	v_mfma_f32_16x16x32_bf16 v[136:139], v[124:127], v[190:193], v[136:139]
	v_mfma_f32_16x16x32_bf16 v[108:111], v[116:119], v[198:201], v[108:111]
	v_mfma_f32_16x16x32_bf16 v[104:107], v[124:127], v[198:201], v[104:107]
	v_mfma_f32_16x16x32_bf16 v[92:95], v[116:119], v[206:209], v[92:95]
	v_mfma_f32_16x16x32_bf16 v[88:91], v[124:127], v[206:209], v[88:91]
	v_mfma_f32_16x16x32_bf16 v[76:79], v[116:119], v[214:217], v[76:79]
	v_mfma_f32_16x16x32_bf16 v[72:75], v[124:127], v[214:217], v[72:75]
	s_setprio 0
	s_setprio 1
	v_mfma_f32_16x16x32_bf16 v[132:135], v[164:167], v[186:189], v[132:135]
	v_mfma_f32_16x16x32_bf16 v[128:131], v[178:181], v[186:189], v[128:131]
	v_mfma_f32_16x16x32_bf16 v[100:103], v[164:167], v[194:197], v[100:103]
	v_mfma_f32_16x16x32_bf16 v[96:99], v[178:181], v[194:197], v[96:99]
	v_mfma_f32_16x16x32_bf16 v[84:87], v[164:167], v[202:205], v[84:87]
	v_mfma_f32_16x16x32_bf16 v[80:83], v[178:181], v[202:205], v[80:83]
	v_mfma_f32_16x16x32_bf16 v[68:71], v[164:167], v[210:213], v[68:71]
	v_mfma_f32_16x16x32_bf16 v[64:67], v[178:181], v[210:213], v[64:67]
	v_mfma_f32_16x16x32_bf16 v[132:135], v[168:171], v[190:193], v[132:135]
	v_mfma_f32_16x16x32_bf16 v[128:131], v[182:185], v[190:193], v[128:131]
	v_mfma_f32_16x16x32_bf16 v[100:103], v[168:171], v[198:201], v[100:103]
	v_mfma_f32_16x16x32_bf16 v[96:99], v[182:185], v[198:201], v[96:99]
	v_mfma_f32_16x16x32_bf16 v[84:87], v[168:171], v[206:209], v[84:87]
	v_mfma_f32_16x16x32_bf16 v[80:83], v[182:185], v[206:209], v[80:83]
	s_setprio 2
	s_barrier
; #define PG8_STAGE(bufoff, gbase, voff) do { _Pragma("unroll") for (int _i = 0; _i < 2; ++_i) \
;         __builtin_amdgcn_global_load_lds((const unsigned*)((const char*)(gbase) + (voff)[_i]), (PG8_LAS unsigned*)(lds + (bufoff) + ldsw + _i * 8192), 16, 0, 0); } while (0)
; #define PG8_LDA(dst, b, h) do { _Pragma("unroll") for (int m = 0; m < 4; ++m) _Pragma("unroll") for (int k = 0; k < 2; ++k) dst[m][k] = *(const PG8_LAS bf16x8*)(lds + PG8_SA(b, h) + aoff + m * 2048 + k * 1024); } while (0)
; #define PG8_MMA(ai, bj, At, Bt) do { __builtin_amdgcn_s_setprio(1); _Pragma("unroll") for (int m = 0; m < 4; ++m) _Pragma("unroll") for (int n = 0; n < 2; ++n) _Pragma("unroll") for (int k = 0; k < 2; ++k) \
;         acc[ai][bj][m][n] = __builtin_amdgcn_mfma_f32_16x16x32_bf16(Bt[n][k], At[m][k], acc[ai][bj][m][n], 0, 0, 0); __builtin_amdgcn_s_setprio(0); } while (0)
; #define PG8_WAIT_V(n) asm volatile("s_waitcnt vmcnt(" #n ")" ::: "memory")
; #define PG8_WAIT_L(n) asm volatile("s_waitcnt lgkmcnt(" #n ")" ::: "memory")
; #define PG8_BAR __builtin_amdgcn_s_barrier()
; #define PG8_SCHED __builtin_amdgcn_sched_barrier(0)
; template <class Epi, class Sched, bool ALIGN_EPI = false, bool SP2 = false>
; __device__ __forceinline__ void gemm_phase(PG8_LAS unsigned char* lds, const Gemm g, const Sched& S, const Epi& E) {
;     ...
;             PG8_WAIT_V(8); PG8_WAIT_L(0); PG8_BAR; PG8_MMA(0, 0, At, B0); PG8_MMA(0, 1, At, B1); PG8_BAR; PG8_SCHED;
;             PG8_LDA(At, 1, 1); PG8_STAGE(PG8_SB(1, 0), b3, voffB); PG8_STAGE(PG8_SB(1, 1), b3 + hstep, voffB); PG8_STAGE(PG8_SA(1, 0), a3, voffA);
;             PG8_WAIT_V(8); PG8_WAIT_L(0); PG8_BAR; PG8_MMA(1, 0, At, B0); PG8_MMA(1, 1, At, B1); PG8_BAR; PG8_SCHED;
	v_mfma_f32_16x16x32_bf16 v[68:71], v[168:171], v[214:217], v[68:71]
	v_mfma_f32_16x16x32_bf16 v[64:67], v[182:185], v[214:217], v[64:67]
	s_setprio 0
	s_add_i32 s52, s56, s29
	v_lshl_add_u64 v[218:219], v[218:219], 0, s[12:13]
	s_mov_b32 m0, s52
	ds_read_b128 v[186:189], v176 offset:49152
	ds_read_b128 v[190:193], v176 offset:50176
	ds_read_b128 v[194:197], v176 offset:51200
	ds_read_b128 v[198:201], v176 offset:52224
	ds_read_b128 v[202:205], v176 offset:53248
	ds_read_b128 v[206:209], v176 offset:54272
	ds_read_b128 v[210:213], v176 offset:55296
	ds_read_b128 v[214:217], v176 offset:56320
	global_load_lds_dwordx4 v[218:219], off
	s_add_i32 m0, s52, 0x2000
	s_add_u32 s52, s70, 0x80080
	v_lshl_add_u64 v[218:219], v[220:221], 0, s[12:13]
	s_addc_u32 s53, s71, 0
	s_add_i32 s56, s57, s29
	global_load_lds_dwordx4 v[218:219], off
	v_lshl_add_u64 v[218:219], s[52:53], 0, v[152:153]
	s_mov_b32 m0, s56
	s_nop 0
	global_load_lds_dwordx4 v[218:219], off
	v_lshl_add_u64 v[218:219], s[52:53], 0, v[148:149]
	s_add_i32 m0, s56, 0x2000
	s_nop 0
	global_load_lds_dwordx4 v[218:219], off
	v_lshl_add_u64 v[218:219], v[222:223], 0, s[12:13]
	s_mov_b32 m0, s77
	s_nop 0
	global_load_lds_dwordx4 v[218:219], off
	v_lshl_add_u64 v[218:219], v[224:225], 0, s[12:13]
	s_mov_b32 m0, s78
	s_nop 0
	global_load_lds_dwordx4 v[218:219], off
	s_waitcnt vmcnt(8)
	s_waitcnt lgkmcnt(0)
	s_barrier
	s_setprio 1
	s_waitcnt lgkmcnt(0)
	v_mfma_f32_16x16x32_bf16 v[60:63], v[112:115], v[186:189], v[60:63]
	v_mfma_f32_16x16x32_bf16 v[56:59], v[120:123], v[186:189], v[56:59]
	v_mfma_f32_16x16x32_bf16 v[44:47], v[112:115], v[194:197], v[44:47]
	v_mfma_f32_16x16x32_bf16 v[40:43], v[120:123], v[194:197], v[40:43]
	v_mfma_f32_16x16x32_bf16 v[28:31], v[112:115], v[202:205], v[28:31]
	v_mfma_f32_16x16x32_bf16 v[24:27], v[120:123], v[202:205], v[24:27]
	v_mfma_f32_16x16x32_bf16 v[12:15], v[112:115], v[210:213], v[12:15]
	v_mfma_f32_16x16x32_bf16 v[8:11], v[120:123], v[210:213], v[8:11]
	v_mfma_f32_16x16x32_bf16 v[60:63], v[116:119], v[190:193], v[60:63]
	v_mfma_f32_16x16x32_bf16 v[56:59], v[124:127], v[190:193], v[56:59]
	v_mfma_f32_16x16x32_bf16 v[44:47], v[116:119], v[198:201], v[44:47]
	v_mfma_f32_16x16x32_bf16 v[40:43], v[124:127], v[198:201], v[40:43]
	v_mfma_f32_16x16x32_bf16 v[28:31], v[116:119], v[206:209], v[28:31]
	v_mfma_f32_16x16x32_bf16 v[24:27], v[124:127], v[206:209], v[24:27]
	v_mfma_f32_16x16x32_bf16 v[12:15], v[116:119], v[214:217], v[12:15]
	v_mfma_f32_16x16x32_bf16 v[8:11], v[124:127], v[214:217], v[8:11]
	s_setprio 0
	s_setprio 1
	v_mfma_f32_16x16x32_bf16 v[52:55], v[164:167], v[186:189], v[52:55]
	v_mfma_f32_16x16x32_bf16 v[48:51], v[178:181], v[186:189], v[48:51]
	v_mfma_f32_16x16x32_bf16 v[36:39], v[164:167], v[194:197], v[36:39]
	v_mfma_f32_16x16x32_bf16 v[32:35], v[178:181], v[194:197], v[32:35]
	v_mfma_f32_16x16x32_bf16 v[20:23], v[164:167], v[202:205], v[20:23]
	v_mfma_f32_16x16x32_bf16 v[16:19], v[178:181], v[202:205], v[16:19]
	v_mfma_f32_16x16x32_bf16 v[4:7], v[164:167], v[210:213], v[4:7]
	v_mfma_f32_16x16x32_bf16 v[0:3], v[178:181], v[210:213], v[0:3]
	v_mfma_f32_16x16x32_bf16 v[52:55], v[168:171], v[190:193], v[52:55]
	v_mfma_f32_16x16x32_bf16 v[48:51], v[182:185], v[190:193], v[48:51]
	v_mfma_f32_16x16x32_bf16 v[36:39], v[168:171], v[198:201], v[36:39]
	v_mfma_f32_16x16x32_bf16 v[32:35], v[182:185], v[198:201], v[32:35]
	v_mfma_f32_16x16x32_bf16 v[20:23], v[168:171], v[206:209], v[20:23]
	v_mfma_f32_16x16x32_bf16 v[16:19], v[182:185], v[206:209], v[16:19]
	s_setprio 2
	s_barrier
	v_mfma_f32_16x16x32_bf16 v[4:7], v[168:171], v[214:217], v[4:7]
	v_mfma_f32_16x16x32_bf16 v[0:3], v[182:185], v[214:217], v[0:3]
	s_setprio 0
	s_add_i32 s88, s88, 2
	s_add_u32 s68, s68, 0x100
	s_addc_u32 s69, s69, 0
	s_add_u32 s86, s86, 0x100
	s_addc_u32 s87, s87, 0
	s_cmp_gt_u32 s88, 29
	s_cbranch_scc0 .LBB0_545
	s_and_b64 vcc, exec, s[14:15]
	s_cbranch_vccz .LBB0_548
	s_barrier

; #define PG8_STAGE(bufoff, gbase, voff) do { _Pragma("unroll") for (int _i = 0; _i < 2; ++_i) \
;         __builtin_amdgcn_global_load_lds((const unsigned*)((const char*)(gbase) + (voff)[_i]), (PG8_LAS unsigned*)(lds + (bufoff) + ldsw + _i * 8192), 16, 0, 0); } while (0)
; #define PG8_LDA(dst, b, h) do { _Pragma("unroll") for (int m = 0; m < 4; ++m) _Pragma("unroll") for (int k = 0; k < 2; ++k) dst[m][k] = *(const PG8_LAS bf16x8*)(lds + PG8_SA(b, h) + aoff + m * 2048 + k * 1024); } while (0)
; #define PG8_LDB(dst, b, h) do { _Pragma("unroll") for (int n = 0; n < 2; ++n) _Pragma("unroll") for (int k = 0; k < 2; ++k) dst[n][k] = *(const PG8_LAS bf16x8*)(lds + PG8_SB(b, h) + boff + n * 2048 + k * 1024); } while (0)
; #define PG8_MMA(ai, bj, At, Bt) do { __builtin_amdgcn_s_setprio(1); _Pragma("unroll") for (int m = 0; m < 4; ++m) _Pragma("unroll") for (int n = 0; n < 2; ++n) _Pragma("unroll") for (int k = 0; k < 2; ++k) \
;         acc[ai][bj][m][n] = __builtin_amdgcn_mfma_f32_16x16x32_bf16(Bt[n][k], At[m][k], acc[ai][bj][m][n], 0, 0, 0); __builtin_amdgcn_s_setprio(0); } while (0)
; #define PG8_WAIT_V(n) asm volatile("s_waitcnt vmcnt(" #n ")" ::: "memory")
; #define PG8_WAIT_L(n) asm volatile("s_waitcnt lgkmcnt(" #n ")" ::: "memory")
; #define PG8_BAR __builtin_amdgcn_s_barrier()
; template <class Epi, class Sched, bool ALIGN_EPI = false, bool SP2 = false>
; __device__ __forceinline__ void gemm_phase(PG8_LAS unsigned char* lds, const Gemm g, const Sched& S, const Epi& E) {
;     ...
;         for (int t = 0; t < nt; t += 2) {
;             const bool last = (t == nt - 2);
;             const char* a1 = cA + (size_t)(t + 1) * kstep;
;             const char* a2 = last ? nA : cA + (size_t)(t + 2) * kstep; const char* b2 = last ? nB : cB + (size_t)(t + 2) * kstep;
;             const char* a3 = a2 + kstep; const char* b3 = b2 + kstep;
;             if constexpr (SP2) {
;             PG8_LDB(B0, 0, 0); PG8_LDB(B1, 0, 1); PG8_SCHED; PG8_LDA(At, 0, 0); PG8_STAGE(PG8_SA(1, 1), a1 + hstep, voffA);
;             PG8_WAIT_V(8); PG8_WAIT_L(0); PG8_BAR; PG8_MMA(0, 0, At, B0); PG8_MMA(0, 1, At, B1); PG8_BAR; PG8_SCHED;
;             PG8_LDA(At, 0, 1); PG8_STAGE(PG8_SB(0, 0), b2, voffB); PG8_STAGE(PG8_SB(0, 1), b2 + hstep, voffB); PG8_STAGE(PG8_SA(0, 0), a2, voffA);
;             PG8_WAIT_V(8); PG8_WAIT_L(0); PG8_BAR; PG8_MMA(1, 0, At, B0); PG8_MMA(1, 1, At, B1); PG8_BAR; PG8_SCHED;
.LBB0_624:
	ds_read_b128 v[128:131], v214
	ds_read_b128 v[132:135], v214 offset:1024
	ds_read_b128 v[158:161], v214 offset:2048
	ds_read_b128 v[162:165], v214 offset:3072
	ds_read_b128 v[166:169], v215
	ds_read_b128 v[170:173], v215 offset:1024
	ds_read_b128 v[174:177], v215 offset:2048
	ds_read_b128 v[178:181], v215 offset:3072
	s_add_u32 s52, s74, 0xffe00080
	s_addc_u32 s53, s75, -1
	s_cmpk_eq_i32 vcc_hi, 0x7c
	s_cselect_b32 s79, s51, s53
	s_cselect_b32 s78, s71, s52
	s_cselect_b32 s77, s49, vcc_lo
	s_cselect_b32 s76, s73, s93
	v_lshl_add_u64 v[226:227], s[74:75], 0, v[150:151]
	s_add_i32 m0, s83, 0xc000
	ds_read_b128 v[182:185], v216
	ds_read_b128 v[186:189], v216 offset:1024
	ds_read_b128 v[190:193], v216 offset:2048
	ds_read_b128 v[194:197], v216 offset:3072
	ds_read_b128 v[198:201], v216 offset:4096
	ds_read_b128 v[202:205], v216 offset:5120
	ds_read_b128 v[218:221], v216 offset:6144
	ds_read_b128 v[222:225], v216 offset:7168
	global_load_lds_dwordx4 v[226:227], off
	v_lshl_add_u64 v[226:227], s[74:75], 0, v[152:153]
	s_add_i32 m0, s83, 0xe000
	s_nop 0
	global_load_lds_dwordx4 v[226:227], off
	s_waitcnt vmcnt(8)
	s_waitcnt lgkmcnt(0)
	s_barrier
	s_setprio 1
	s_waitcnt lgkmcnt(0)
	v_mfma_f32_16x16x32_bf16 v[124:127], v[128:131], v[182:185], v[124:127]
	v_mfma_f32_16x16x32_bf16 v[120:123], v[158:161], v[182:185], v[120:123]
	v_mfma_f32_16x16x32_bf16 v[116:119], v[128:131], v[190:193], v[116:119]
	v_mfma_f32_16x16x32_bf16 v[112:115], v[158:161], v[190:193], v[112:115]
	v_mfma_f32_16x16x32_bf16 v[108:111], v[128:131], v[198:201], v[108:111]
	v_mfma_f32_16x16x32_bf16 v[104:107], v[158:161], v[198:201], v[104:107]
	v_mfma_f32_16x16x32_bf16 v[100:103], v[128:131], v[218:221], v[100:103]
	v_mfma_f32_16x16x32_bf16 v[96:99], v[158:161], v[218:221], v[96:99]
	v_mfma_f32_16x16x32_bf16 v[124:127], v[132:135], v[186:189], v[124:127]
	v_mfma_f32_16x16x32_bf16 v[120:123], v[162:165], v[186:189], v[120:123]
	v_mfma_f32_16x16x32_bf16 v[116:119], v[132:135], v[194:197], v[116:119]
	v_mfma_f32_16x16x32_bf16 v[112:115], v[162:165], v[194:197], v[112:115]
	v_mfma_f32_16x16x32_bf16 v[108:111], v[132:135], v[202:205], v[108:111]
	v_mfma_f32_16x16x32_bf16 v[104:107], v[162:165], v[202:205], v[104:107]
	v_mfma_f32_16x16x32_bf16 v[100:103], v[132:135], v[222:225], v[100:103]
	v_mfma_f32_16x16x32_bf16 v[96:99], v[162:165], v[222:225], v[96:99]
	s_setprio 0
	s_setprio 1
	v_mfma_f32_16x16x32_bf16 v[60:63], v[166:169], v[182:185], v[60:63]
	v_mfma_f32_16x16x32_bf16 v[56:59], v[174:177], v[182:185], v[56:59]
	v_mfma_f32_16x16x32_bf16 v[52:55], v[166:169], v[190:193], v[52:55]
	v_mfma_f32_16x16x32_bf16 v[48:51], v[174:177], v[190:193], v[48:51]
	v_mfma_f32_16x16x32_bf16 v[44:47], v[166:169], v[198:201], v[44:47]
	v_mfma_f32_16x16x32_bf16 v[40:43], v[174:177], v[198:201], v[40:43]
	v_mfma_f32_16x16x32_bf16 v[36:39], v[166:169], v[218:221], v[36:39]
	v_mfma_f32_16x16x32_bf16 v[32:35], v[174:177], v[218:221], v[32:35]
	v_mfma_f32_16x16x32_bf16 v[60:63], v[170:173], v[186:189], v[60:63]
	v_mfma_f32_16x16x32_bf16 v[56:59], v[178:181], v[186:189], v[56:59]
	v_mfma_f32_16x16x32_bf16 v[52:55], v[170:173], v[194:197], v[52:55]
	v_mfma_f32_16x16x32_bf16 v[48:51], v[178:181], v[194:197], v[48:51]
	v_mfma_f32_16x16x32_bf16 v[44:47], v[170:173], v[202:205], v[44:47]
	v_mfma_f32_16x16x32_bf16 v[40:43], v[178:181], v[202:205], v[40:43]
	s_setprio 2
	s_barrier
	v_mfma_f32_16x16x32_bf16 v[36:39], v[170:173], v[222:225], v[36:39]
	v_mfma_f32_16x16x32_bf16 v[32:35], v[178:181], v[222:225], v[32:35]
	s_setprio 0
	s_add_i32 s52, s33, s82
	v_lshl_add_u64 v[226:227], s[76:77], 0, v[138:139]
	s_mov_b32 m0, s52
	ds_read_b128 v[182:185], v216 offset:16384
	ds_read_b128 v[186:189], v216 offset:17408
	ds_read_b128 v[190:193], v216 offset:18432
	ds_read_b128 v[194:197], v216 offset:19456
	ds_read_b128 v[198:201], v216 offset:20480
	ds_read_b128 v[202:205], v216 offset:21504
	ds_read_b128 v[218:221], v216 offset:22528
	ds_read_b128 v[222:225], v216 offset:23552
	global_load_lds_dwordx4 v[226:227], off
	s_add_i32 m0, s52, 0x2000
	s_add_u32 s52, s76, 0x200000
	v_lshl_add_u64 v[228:229], s[76:77], 0, v[142:143]
	s_addc_u32 s53, s77, 0
	s_add_i32 s56, s92, s82
	global_load_lds_dwordx4 v[228:229], off
	v_lshl_add_u64 v[230:231], s[52:53], 0, v[138:139]
	s_mov_b32 m0, s56
	v_lshl_add_u64 v[232:233], s[78:79], 0, v[140:141]
	global_load_lds_dwordx4 v[230:231], off
	v_lshl_add_u64 v[230:231], s[52:53], 0, v[142:143]
	s_add_i32 m0, s56, 0x2000
	s_nop 0
	global_load_lds_dwordx4 v[230:231], off
	v_lshl_add_u64 v[230:231], s[78:79], 0, v[136:137]
	s_mov_b32 m0, s83
	s_nop 0
	global_load_lds_dwordx4 v[230:231], off
	s_mov_b32 m0, s84
	s_nop 0
	global_load_lds_dwordx4 v[232:233], off
	s_waitcnt vmcnt(8)
	s_waitcnt lgkmcnt(0)
	s_barrier
; #define PG8_STAGE(bufoff, gbase, voff) do { _Pragma("unroll") for (int _i = 0; _i < 2; ++_i) \
;         __builtin_amdgcn_global_load_lds((const unsigned*)((const char*)(gbase) + (voff)[_i]), (PG8_LAS unsigned*)(lds + (bufoff) + ldsw + _i * 8192), 16, 0, 0); } while (0)
; #define PG8_LDA(dst, b, h) do { _Pragma("unroll") for (int m = 0; m < 4; ++m) _Pragma("unroll") for (int k = 0; k < 2; ++k) dst[m][k] = *(const PG8_LAS bf16x8*)(lds + PG8_SA(b, h) + aoff + m * 2048 + k * 1024); } while (0)
; #define PG8_LDB(dst, b, h) do { _Pragma("unroll") for (int n = 0; n < 2; ++n) _Pragma("unroll") for (int k = 0; k < 2; ++k) dst[n][k] = *(const PG8_LAS bf16x8*)(lds + PG8_SB(b, h) + boff + n * 2048 + k * 1024); } while (0)
; #define PG8_MMA(ai, bj, At, Bt) do { __builtin_amdgcn_s_setprio(1); _Pragma("unroll") for (int m = 0; m < 4; ++m) _Pragma("unroll") for (int n = 0; n < 2; ++n) _Pragma("unroll") for (int k = 0; k < 2; ++k) \
;         acc[ai][bj][m][n] = __builtin_amdgcn_mfma_f32_16x16x32_bf16(Bt[n][k], At[m][k], acc[ai][bj][m][n], 0, 0, 0); __builtin_amdgcn_s_setprio(0); } while (0)
; #define PG8_WAIT_V(n) asm volatile("s_waitcnt vmcnt(" #n ")" ::: "memory")
; #define PG8_WAIT_L(n) asm volatile("s_waitcnt lgkmcnt(" #n ")" ::: "memory")
; #define PG8_BAR __builtin_amdgcn_s_barrier()
; #define PG8_SCHED __builtin_amdgcn_sched_barrier(0)
; template <class Epi, class Sched, bool ALIGN_EPI = false, bool SP2 = false>
; __device__ __forceinline__ void gemm_phase(PG8_LAS unsigned char* lds, const Gemm g, const Sched& S, const Epi& E) {
;     ...
;             PG8_WAIT_V(8); PG8_WAIT_L(0); PG8_BAR; PG8_MMA(1, 0, At, B0); PG8_MMA(1, 1, At, B1); PG8_BAR; PG8_SCHED;
;             PG8_LDB(B0, 1, 0); PG8_LDB(B1, 1, 1); PG8_SCHED; PG8_LDA(At, 1, 0); PG8_STAGE(PG8_SA(0, 1), a2 + hstep, voffA);
;             PG8_WAIT_V(8); PG8_WAIT_L(0); PG8_BAR; PG8_MMA(0, 0, At, B0); PG8_MMA(0, 1, At, B1); PG8_BAR; PG8_SCHED;
	s_setprio 1
	s_waitcnt lgkmcnt(0)
	v_mfma_f32_16x16x32_bf16 v[92:95], v[128:131], v[182:185], v[92:95]
	v_mfma_f32_16x16x32_bf16 v[88:91], v[158:161], v[182:185], v[88:91]
	v_mfma_f32_16x16x32_bf16 v[84:87], v[128:131], v[190:193], v[84:87]
	v_mfma_f32_16x16x32_bf16 v[80:83], v[158:161], v[190:193], v[80:83]
	v_mfma_f32_16x16x32_bf16 v[76:79], v[128:131], v[198:201], v[76:79]
	v_mfma_f32_16x16x32_bf16 v[72:75], v[158:161], v[198:201], v[72:75]
	v_mfma_f32_16x16x32_bf16 v[68:71], v[128:131], v[218:221], v[68:71]
	v_mfma_f32_16x16x32_bf16 v[64:67], v[158:161], v[218:221], v[64:67]
	v_mfma_f32_16x16x32_bf16 v[92:95], v[132:135], v[186:189], v[92:95]
	v_mfma_f32_16x16x32_bf16 v[88:91], v[162:165], v[186:189], v[88:91]
	v_mfma_f32_16x16x32_bf16 v[84:87], v[132:135], v[194:197], v[84:87]
	v_mfma_f32_16x16x32_bf16 v[80:83], v[162:165], v[194:197], v[80:83]
	v_mfma_f32_16x16x32_bf16 v[76:79], v[132:135], v[202:205], v[76:79]
	v_mfma_f32_16x16x32_bf16 v[72:75], v[162:165], v[202:205], v[72:75]
	v_mfma_f32_16x16x32_bf16 v[68:71], v[132:135], v[222:225], v[68:71]
	v_mfma_f32_16x16x32_bf16 v[64:67], v[162:165], v[222:225], v[64:67]
	s_setprio 0
	s_setprio 1
	v_mfma_f32_16x16x32_bf16 v[28:31], v[166:169], v[182:185], v[28:31]
	v_mfma_f32_16x16x32_bf16 v[24:27], v[174:177], v[182:185], v[24:27]
	v_mfma_f32_16x16x32_bf16 v[20:23], v[166:169], v[190:193], v[20:23]
	v_mfma_f32_16x16x32_bf16 v[16:19], v[174:177], v[190:193], v[16:19]
	v_mfma_f32_16x16x32_bf16 v[12:15], v[166:169], v[198:201], v[12:15]
	v_mfma_f32_16x16x32_bf16 v[8:11], v[174:177], v[198:201], v[8:11]
	v_mfma_f32_16x16x32_bf16 v[4:7], v[166:169], v[218:221], v[4:7]
	v_mfma_f32_16x16x32_bf16 v[0:3], v[174:177], v[218:221], v[0:3]
	v_mfma_f32_16x16x32_bf16 v[28:31], v[170:173], v[186:189], v[28:31]
	v_mfma_f32_16x16x32_bf16 v[24:27], v[178:181], v[186:189], v[24:27]
	v_mfma_f32_16x16x32_bf16 v[20:23], v[170:173], v[194:197], v[20:23]
	v_mfma_f32_16x16x32_bf16 v[16:19], v[178:181], v[194:197], v[16:19]
	v_mfma_f32_16x16x32_bf16 v[12:15], v[170:173], v[202:205], v[12:15]
	v_mfma_f32_16x16x32_bf16 v[8:11], v[178:181], v[202:205], v[8:11]
	s_setprio 2
	s_barrier
	v_mfma_f32_16x16x32_bf16 v[4:7], v[170:173], v[222:225], v[4:7]
	v_mfma_f32_16x16x32_bf16 v[0:3], v[178:181], v[222:225], v[0:3]
	s_setprio 0
	s_add_i32 s56, 0, 0x18000
	s_add_i32 s57, 0, 0x1c000
	v_add_u32_e32 v162, s56, v212
	v_add_u32_e32 v178, s57, v212
	ds_read_b128 v[128:131], v162
	ds_read_b128 v[132:135], v162 offset:1024
	ds_read_b128 v[158:161], v162 offset:2048
	ds_read_b128 v[162:165], v162 offset:3072
	ds_read_b128 v[166:169], v178
	ds_read_b128 v[170:173], v178 offset:1024
	ds_read_b128 v[174:177], v178 offset:2048
	ds_read_b128 v[178:181], v178 offset:3072
	s_add_u32 s52, s78, 0x200000
	s_addc_u32 s53, s79, 0
	s_mov_b32 m0, s85
	v_lshl_add_u64 v[234:235], s[52:53], 0, v[136:137]
	ds_read_b128 v[182:185], v216 offset:32768
	ds_read_b128 v[186:189], v216 offset:33792
	ds_read_b128 v[190:193], v216 offset:34816
	ds_read_b128 v[194:197], v216 offset:35840
	ds_read_b128 v[198:201], v216 offset:36864
	ds_read_b128 v[202:205], v216 offset:37888
	ds_read_b128 v[218:221], v216 offset:38912
	ds_read_b128 v[222:225], v216 offset:39936
	global_load_lds_dwordx4 v[234:235], off
	v_lshl_add_u64 v[234:235], s[52:53], 0, v[140:141]
	s_mov_b32 m0, s86
	s_nop 0
	global_load_lds_dwordx4 v[234:235], off
	s_waitcnt vmcnt(8)
	s_waitcnt lgkmcnt(0)
	s_barrier
	s_setprio 1
	s_waitcnt lgkmcnt(0)
	v_mfma_f32_16x16x32_bf16 v[124:127], v[128:131], v[182:185], v[124:127]
	v_mfma_f32_16x16x32_bf16 v[120:123], v[158:161], v[182:185], v[120:123]
	v_mfma_f32_16x16x32_bf16 v[116:119], v[128:131], v[190:193], v[116:119]
	v_mfma_f32_16x16x32_bf16 v[112:115], v[158:161], v[190:193], v[112:115]
	v_mfma_f32_16x16x32_bf16 v[108:111], v[128:131], v[198:201], v[108:111]
	v_mfma_f32_16x16x32_bf16 v[104:107], v[158:161], v[198:201], v[104:107]
	v_mfma_f32_16x16x32_bf16 v[100:103], v[128:131], v[218:221], v[100:103]
	v_mfma_f32_16x16x32_bf16 v[96:99], v[158:161], v[218:221], v[96:99]
	v_mfma_f32_16x16x32_bf16 v[124:127], v[132:135], v[186:189], v[124:127]
	v_mfma_f32_16x16x32_bf16 v[120:123], v[162:165], v[186:189], v[120:123]
	v_mfma_f32_16x16x32_bf16 v[116:119], v[132:135], v[194:197], v[116:119]
	v_mfma_f32_16x16x32_bf16 v[112:115], v[162:165], v[194:197], v[112:115]
	v_mfma_f32_16x16x32_bf16 v[108:111], v[132:135], v[202:205], v[108:111]
	v_mfma_f32_16x16x32_bf16 v[104:107], v[162:165], v[202:205], v[104:107]
	v_mfma_f32_16x16x32_bf16 v[100:103], v[132:135], v[222:225], v[100:103]
	v_mfma_f32_16x16x32_bf16 v[96:99], v[162:165], v[222:225], v[96:99]
	s_setprio 0
	s_setprio 1
	v_mfma_f32_16x16x32_bf16 v[60:63], v[166:169], v[182:185], v[60:63]
	v_mfma_f32_16x16x32_bf16 v[56:59], v[174:177], v[182:185], v[56:59]
	v_mfma_f32_16x16x32_bf16 v[52:55], v[166:169], v[190:193], v[52:55]
	v_mfma_f32_16x16x32_bf16 v[48:51], v[174:177], v[190:193], v[48:51]
	v_mfma_f32_16x16x32_bf16 v[44:47], v[166:169], v[198:201], v[44:47]
	v_mfma_f32_16x16x32_bf16 v[40:43], v[174:177], v[198:201], v[40:43]
	v_mfma_f32_16x16x32_bf16 v[36:39], v[166:169], v[218:221], v[36:39]
	v_mfma_f32_16x16x32_bf16 v[32:35], v[174:177], v[218:221], v[32:35]
	v_mfma_f32_16x16x32_bf16 v[60:63], v[170:173], v[186:189], v[60:63]
	v_mfma_f32_16x16x32_bf16 v[56:59], v[178:181], v[186:189], v[56:59]
	v_mfma_f32_16x16x32_bf16 v[52:55], v[170:173], v[194:197], v[52:55]
	v_mfma_f32_16x16x32_bf16 v[48:51], v[178:181], v[194:197], v[48:51]
	v_mfma_f32_16x16x32_bf16 v[44:47], v[170:173], v[202:205], v[44:47]
	v_mfma_f32_16x16x32_bf16 v[40:43], v[178:181], v[202:205], v[40:43]
	s_setprio 2
	s_barrier
; #define PG8_STAGE(bufoff, gbase, voff) do { _Pragma("unroll") for (int _i = 0; _i < 2; ++_i) \
;         __builtin_amdgcn_global_load_lds((const unsigned*)((const char*)(gbase) + (voff)[_i]), (PG8_LAS unsigned*)(lds + (bufoff) + ldsw + _i * 8192), 16, 0, 0); } while (0)
; #define PG8_LDA(dst, b, h) do { _Pragma("unroll") for (int m = 0; m < 4; ++m) _Pragma("unroll") for (int k = 0; k < 2; ++k) dst[m][k] = *(const PG8_LAS bf16x8*)(lds + PG8_SA(b, h) + aoff + m * 2048 + k * 1024); } while (0)
; #define PG8_MMA(ai, bj, At, Bt) do { __builtin_amdgcn_s_setprio(1); _Pragma("unroll") for (int m = 0; m < 4; ++m) _Pragma("unroll") for (int n = 0; n < 2; ++n) _Pragma("unroll") for (int k = 0; k < 2; ++k) \
;         acc[ai][bj][m][n] = __builtin_amdgcn_mfma_f32_16x16x32_bf16(Bt[n][k], At[m][k], acc[ai][bj][m][n], 0, 0, 0); __builtin_amdgcn_s_setprio(0); } while (0)
; #define PG8_WAIT_V(n) asm volatile("s_waitcnt vmcnt(" #n ")" ::: "memory")
; #define PG8_WAIT_L(n) asm volatile("s_waitcnt lgkmcnt(" #n ")" ::: "memory")
; #define PG8_BAR __builtin_amdgcn_s_barrier()
; #define PG8_SCHED __builtin_amdgcn_sched_barrier(0)
; template <class Epi, class Sched, bool ALIGN_EPI = false, bool SP2 = false>
; __device__ __forceinline__ void gemm_phase(PG8_LAS unsigned char* lds, const Gemm g, const Sched& S, const Epi& E) {
;     ...
;             PG8_WAIT_V(8); PG8_WAIT_L(0); PG8_BAR; PG8_MMA(0, 0, At, B0); PG8_MMA(0, 1, At, B1); PG8_BAR; PG8_SCHED;
;             PG8_LDA(At, 1, 1); PG8_STAGE(PG8_SB(1, 0), b3, voffB); PG8_STAGE(PG8_SB(1, 1), b3 + hstep, voffB); PG8_STAGE(PG8_SA(1, 0), a3, voffA);
;             PG8_WAIT_V(8); PG8_WAIT_L(0); PG8_BAR; PG8_MMA(1, 0, At, B0); PG8_MMA(1, 1, At, B1); PG8_BAR; PG8_SCHED;
	v_mfma_f32_16x16x32_bf16 v[36:39], v[170:173], v[222:225], v[36:39]
	v_mfma_f32_16x16x32_bf16 v[32:35], v[178:181], v[222:225], v[32:35]
	s_setprio 0
	s_add_i32 s52, s56, s82
	v_lshl_add_u64 v[226:227], v[226:227], 0, s[36:37]
	s_mov_b32 m0, s52
	ds_read_b128 v[182:185], v216 offset:49152
	ds_read_b128 v[186:189], v216 offset:50176
	ds_read_b128 v[190:193], v216 offset:51200
	ds_read_b128 v[194:197], v216 offset:52224
	ds_read_b128 v[198:201], v216 offset:53248
	ds_read_b128 v[202:205], v216 offset:54272
	ds_read_b128 v[218:221], v216 offset:55296
	ds_read_b128 v[222:225], v216 offset:56320
	global_load_lds_dwordx4 v[226:227], off
	s_add_i32 m0, s52, 0x2000
	s_add_u32 s52, s76, 0x200080
	v_lshl_add_u64 v[226:227], v[228:229], 0, s[36:37]
	s_addc_u32 s53, s77, 0
	s_add_i32 s56, s57, s82
	global_load_lds_dwordx4 v[226:227], off
	v_lshl_add_u64 v[226:227], s[52:53], 0, v[138:139]
	s_mov_b32 m0, s56
	s_nop 0
	global_load_lds_dwordx4 v[226:227], off
	v_lshl_add_u64 v[226:227], s[52:53], 0, v[142:143]
	s_add_i32 m0, s56, 0x2000
	s_nop 0
	global_load_lds_dwordx4 v[226:227], off
	v_lshl_add_u64 v[226:227], v[230:231], 0, s[36:37]
	s_mov_b32 m0, s94
	s_nop 0
	global_load_lds_dwordx4 v[226:227], off
	v_lshl_add_u64 v[226:227], v[232:233], 0, s[36:37]
	s_mov_b32 m0, s95
	s_nop 0
	global_load_lds_dwordx4 v[226:227], off
	s_waitcnt vmcnt(8)
	s_waitcnt lgkmcnt(0)
	s_barrier
	s_setprio 1
	s_waitcnt lgkmcnt(0)
	v_mfma_f32_16x16x32_bf16 v[92:95], v[128:131], v[182:185], v[92:95]
	v_mfma_f32_16x16x32_bf16 v[88:91], v[158:161], v[182:185], v[88:91]
	v_mfma_f32_16x16x32_bf16 v[84:87], v[128:131], v[190:193], v[84:87]
	v_mfma_f32_16x16x32_bf16 v[80:83], v[158:161], v[190:193], v[80:83]
	v_mfma_f32_16x16x32_bf16 v[76:79], v[128:131], v[198:201], v[76:79]
	v_mfma_f32_16x16x32_bf16 v[72:75], v[158:161], v[198:201], v[72:75]
	v_mfma_f32_16x16x32_bf16 v[68:71], v[128:131], v[218:221], v[68:71]
	v_mfma_f32_16x16x32_bf16 v[64:67], v[158:161], v[218:221], v[64:67]
	v_mfma_f32_16x16x32_bf16 v[92:95], v[132:135], v[186:189], v[92:95]
	v_mfma_f32_16x16x32_bf16 v[88:91], v[162:165], v[186:189], v[88:91]
	v_mfma_f32_16x16x32_bf16 v[84:87], v[132:135], v[194:197], v[84:87]
	v_mfma_f32_16x16x32_bf16 v[80:83], v[162:165], v[194:197], v[80:83]
	v_mfma_f32_16x16x32_bf16 v[76:79], v[132:135], v[202:205], v[76:79]
	v_mfma_f32_16x16x32_bf16 v[72:75], v[162:165], v[202:205], v[72:75]
	v_mfma_f32_16x16x32_bf16 v[68:71], v[132:135], v[222:225], v[68:71]
	v_mfma_f32_16x16x32_bf16 v[64:67], v[162:165], v[222:225], v[64:67]
	s_setprio 0
	s_setprio 1
	v_mfma_f32_16x16x32_bf16 v[28:31], v[166:169], v[182:185], v[28:31]
	v_mfma_f32_16x16x32_bf16 v[24:27], v[174:177], v[182:185], v[24:27]
	v_mfma_f32_16x16x32_bf16 v[20:23], v[166:169], v[190:193], v[20:23]
	v_mfma_f32_16x16x32_bf16 v[16:19], v[174:177], v[190:193], v[16:19]
	v_mfma_f32_16x16x32_bf16 v[12:15], v[166:169], v[198:201], v[12:15]
	v_mfma_f32_16x16x32_bf16 v[8:11], v[174:177], v[198:201], v[8:11]
	v_mfma_f32_16x16x32_bf16 v[4:7], v[166:169], v[218:221], v[4:7]
	v_mfma_f32_16x16x32_bf16 v[0:3], v[174:177], v[218:221], v[0:3]
	v_mfma_f32_16x16x32_bf16 v[28:31], v[170:173], v[186:189], v[28:31]
	v_mfma_f32_16x16x32_bf16 v[24:27], v[178:181], v[186:189], v[24:27]
	v_mfma_f32_16x16x32_bf16 v[20:23], v[170:173], v[194:197], v[20:23]
	v_mfma_f32_16x16x32_bf16 v[16:19], v[178:181], v[194:197], v[16:19]
	v_mfma_f32_16x16x32_bf16 v[12:15], v[170:173], v[202:205], v[12:15]
	v_mfma_f32_16x16x32_bf16 v[8:11], v[178:181], v[202:205], v[8:11]
	s_setprio 2
	s_barrier
	v_mfma_f32_16x16x32_bf16 v[4:7], v[170:173], v[222:225], v[4:7]
	v_mfma_f32_16x16x32_bf16 v[0:3], v[178:181], v[222:225], v[0:3]
	s_setprio 0
	s_add_i32 vcc_hi, vcc_hi, 2
	s_add_u32 s74, s74, 0x100
	s_addc_u32 s75, s75, 0
	s_add_u32 s93, s93, 0x100
	s_addc_u32 vcc_lo, vcc_lo, 0
	s_cmpk_gt_u32 vcc_hi, 0x7d
	s_cbranch_scc0 .LBB0_624
	s_and_b64 vcc, exec, s[40:41]
	s_cbranch_vccz .LBB0_627
	s_barrier

; #define PG8_STAGE(bufoff, gbase, voff) do { _Pragma("unroll") for (int _i = 0; _i < 2; ++_i) \
;         __builtin_amdgcn_global_load_lds((const unsigned*)((const char*)(gbase) + (voff)[_i]), (PG8_LAS unsigned*)(lds + (bufoff) + ldsw + _i * 8192), 16, 0, 0); } while (0)
; #define PG8_LDA(dst, b, h) do { _Pragma("unroll") for (int m = 0; m < 4; ++m) _Pragma("unroll") for (int k = 0; k < 2; ++k) dst[m][k] = *(const PG8_LAS bf16x8*)(lds + PG8_SA(b, h) + aoff + m * 2048 + k * 1024); } while (0)
; #define PG8_LDB(dst, b, h) do { _Pragma("unroll") for (int n = 0; n < 2; ++n) _Pragma("unroll") for (int k = 0; k < 2; ++k) dst[n][k] = *(const PG8_LAS bf16x8*)(lds + PG8_SB(b, h) + boff + n * 2048 + k * 1024); } while (0)
; #define PG8_MMA(ai, bj, At, Bt) do { __builtin_amdgcn_s_setprio(1); _Pragma("unroll") for (int m = 0; m < 4; ++m) _Pragma("unroll") for (int n = 0; n < 2; ++n) _Pragma("unroll") for (int k = 0; k < 2; ++k) \
;         acc[ai][bj][m][n] = __builtin_amdgcn_mfma_f32_16x16x32_bf16(Bt[n][k], At[m][k], acc[ai][bj][m][n], 0, 0, 0); __builtin_amdgcn_s_setprio(0); } while (0)
; #define PG8_WAIT_V(n) asm volatile("s_waitcnt vmcnt(" #n ")" ::: "memory")
; #define PG8_WAIT_L(n) asm volatile("s_waitcnt lgkmcnt(" #n ")" ::: "memory")
; #define PG8_BAR __builtin_amdgcn_s_barrier()
; template <class Epi, class Sched, bool ALIGN_EPI = false, bool SP2 = false>
; __device__ __forceinline__ void gemm_phase(PG8_LAS unsigned char* lds, const Gemm g, const Sched& S, const Epi& E) {
;     ...
;         for (int t = 0; t < nt; t += 2) {
;             const bool last = (t == nt - 2);
;             const char* a1 = cA + (size_t)(t + 1) * kstep;
;             const char* a2 = last ? nA : cA + (size_t)(t + 2) * kstep; const char* b2 = last ? nB : cB + (size_t)(t + 2) * kstep;
;             const char* a3 = a2 + kstep; const char* b3 = b2 + kstep;
;             if constexpr (SP2) {
;             PG8_LDB(B0, 0, 0); PG8_LDB(B1, 0, 1); PG8_SCHED; PG8_LDA(At, 0, 0); PG8_STAGE(PG8_SA(1, 1), a1 + hstep, voffA);
;             PG8_WAIT_V(8); PG8_WAIT_L(0); PG8_BAR; PG8_MMA(0, 0, At, B0); PG8_MMA(0, 1, At, B1); PG8_BAR; PG8_SCHED;
;             PG8_LDA(At, 0, 1); PG8_STAGE(PG8_SB(0, 0), b2, voffB); PG8_STAGE(PG8_SB(0, 1), b2 + hstep, voffB); PG8_STAGE(PG8_SA(0, 0), a2, voffA);
;             PG8_WAIT_V(8); PG8_WAIT_L(0); PG8_BAR; PG8_MMA(1, 0, At, B0); PG8_MMA(1, 1, At, B1); PG8_BAR; PG8_SCHED;
.LBB0_660:
	ds_read_b128 v[166:169], v145
	ds_read_b128 v[170:173], v145 offset:1024
	ds_read_b128 v[174:177], v145 offset:2048
	ds_read_b128 v[178:181], v145 offset:3072
	ds_read_b128 v[182:185], v149
	ds_read_b128 v[186:189], v149 offset:1024
	ds_read_b128 v[190:193], v149 offset:2048
	ds_read_b128 v[194:197], v149 offset:3072
	s_add_u32 s52, s72, 0xffe00080
	s_addc_u32 s53, s73, -1
	s_cmp_eq_u32 s49, 28
	s_cselect_b32 s77, s51, s53
	s_cselect_b32 s76, s50, s52
	s_cselect_b32 s75, s55, s41
	s_cselect_b32 s74, s54, s37
	s_mov_b32 m0, s82
	v_lshl_add_u64 v[230:231], s[72:73], 0, v[160:161]
	ds_read_b128 v[198:201], v164
	ds_read_b128 v[202:205], v164 offset:1024
	ds_read_b128 v[206:209], v164 offset:2048
	ds_read_b128 v[210:213], v164 offset:3072
	ds_read_b128 v[214:217], v164 offset:4096
	ds_read_b128 v[218:221], v164 offset:5120
	ds_read_b128 v[222:225], v164 offset:6144
	ds_read_b128 v[226:229], v164 offset:7168
	global_load_lds_dwordx4 v[230:231], off
	v_lshl_add_u64 v[230:231], s[72:73], 0, v[162:163]
	s_mov_b32 m0, s83
	s_nop 0
	global_load_lds_dwordx4 v[230:231], off
	s_waitcnt vmcnt(8)
	s_waitcnt lgkmcnt(0)
	s_barrier
	s_setprio 1
	s_waitcnt lgkmcnt(0)
	v_mfma_f32_16x16x32_bf16 v[124:127], v[166:169], v[198:201], v[124:127]
	v_mfma_f32_16x16x32_bf16 v[120:123], v[174:177], v[198:201], v[120:123]
	v_mfma_f32_16x16x32_bf16 v[116:119], v[166:169], v[206:209], v[116:119]
	v_mfma_f32_16x16x32_bf16 v[108:111], v[174:177], v[206:209], v[108:111]
	v_mfma_f32_16x16x32_bf16 v[100:103], v[166:169], v[214:217], v[100:103]
	v_mfma_f32_16x16x32_bf16 v[92:95], v[174:177], v[214:217], v[92:95]
	v_mfma_f32_16x16x32_bf16 v[84:87], v[166:169], v[222:225], v[84:87]
	v_mfma_f32_16x16x32_bf16 v[76:79], v[174:177], v[222:225], v[76:79]
	v_mfma_f32_16x16x32_bf16 v[124:127], v[170:173], v[202:205], v[124:127]
	v_mfma_f32_16x16x32_bf16 v[120:123], v[178:181], v[202:205], v[120:123]
	v_mfma_f32_16x16x32_bf16 v[116:119], v[170:173], v[210:213], v[116:119]
	v_mfma_f32_16x16x32_bf16 v[108:111], v[178:181], v[210:213], v[108:111]
	v_mfma_f32_16x16x32_bf16 v[100:103], v[170:173], v[218:221], v[100:103]
	v_mfma_f32_16x16x32_bf16 v[92:95], v[178:181], v[218:221], v[92:95]
	v_mfma_f32_16x16x32_bf16 v[84:87], v[170:173], v[226:229], v[84:87]
	v_mfma_f32_16x16x32_bf16 v[76:79], v[178:181], v[226:229], v[76:79]
	s_setprio 0
	s_setprio 1
	v_mfma_f32_16x16x32_bf16 v[112:115], v[182:185], v[198:201], v[112:115]
	v_mfma_f32_16x16x32_bf16 v[104:107], v[190:193], v[198:201], v[104:107]
	v_mfma_f32_16x16x32_bf16 v[96:99], v[182:185], v[206:209], v[96:99]
	v_mfma_f32_16x16x32_bf16 v[88:91], v[190:193], v[206:209], v[88:91]
	v_mfma_f32_16x16x32_bf16 v[80:83], v[182:185], v[214:217], v[80:83]
	v_mfma_f32_16x16x32_bf16 v[72:75], v[190:193], v[214:217], v[72:75]
	v_mfma_f32_16x16x32_bf16 v[68:71], v[182:185], v[222:225], v[68:71]
	v_mfma_f32_16x16x32_bf16 v[64:67], v[190:193], v[222:225], v[64:67]
	v_mfma_f32_16x16x32_bf16 v[112:115], v[186:189], v[202:205], v[112:115]
	v_mfma_f32_16x16x32_bf16 v[104:107], v[194:197], v[202:205], v[104:107]
	v_mfma_f32_16x16x32_bf16 v[96:99], v[186:189], v[210:213], v[96:99]
	v_mfma_f32_16x16x32_bf16 v[88:91], v[194:197], v[210:213], v[88:91]
	v_mfma_f32_16x16x32_bf16 v[80:83], v[186:189], v[218:221], v[80:83]
	v_mfma_f32_16x16x32_bf16 v[72:75], v[194:197], v[218:221], v[72:75]
	s_setprio 2
	s_barrier
	v_mfma_f32_16x16x32_bf16 v[68:71], v[186:189], v[226:229], v[68:71]
	v_mfma_f32_16x16x32_bf16 v[64:67], v[194:197], v[226:229], v[64:67]
	s_setprio 0
	s_mov_b32 m0, s84
	v_lshl_add_u64 v[230:231], s[74:75], 0, v[138:139]
	s_add_u32 s52, s74, 0x200000
	ds_read_b128 v[198:201], v164 offset:16384
	ds_read_b128 v[202:205], v164 offset:17408
	ds_read_b128 v[206:209], v164 offset:18432
	ds_read_b128 v[210:213], v164 offset:19456
	ds_read_b128 v[214:217], v164 offset:20480
	ds_read_b128 v[218:221], v164 offset:21504
	ds_read_b128 v[222:225], v164 offset:22528
	ds_read_b128 v[226:229], v164 offset:23552
	global_load_lds_dwordx4 v[230:231], off
	v_lshl_add_u64 v[232:233], s[74:75], 0, v[142:143]
	s_mov_b32 m0, s85
	s_addc_u32 s53, s75, 0
	global_load_lds_dwordx4 v[232:233], off
	v_lshl_add_u64 v[234:235], s[52:53], 0, v[138:139]
	s_mov_b32 m0, s86
	v_lshl_add_u64 v[236:237], s[76:77], 0, v[140:141]
	global_load_lds_dwordx4 v[234:235], off
	v_lshl_add_u64 v[234:235], s[52:53], 0, v[142:143]
	s_mov_b32 m0, s87
	s_nop 0
	global_load_lds_dwordx4 v[234:235], off
	v_lshl_add_u64 v[234:235], s[76:77], 0, v[136:137]
	s_mov_b32 m0, s28
	s_nop 0
	global_load_lds_dwordx4 v[234:235], off
	s_mov_b32 m0, s29
	s_nop 0
	global_load_lds_dwordx4 v[236:237], off
	s_waitcnt vmcnt(8)
	s_waitcnt lgkmcnt(0)
	s_barrier
; #define PG8_STAGE(bufoff, gbase, voff) do { _Pragma("unroll") for (int _i = 0; _i < 2; ++_i) \
;         __builtin_amdgcn_global_load_lds((const unsigned*)((const char*)(gbase) + (voff)[_i]), (PG8_LAS unsigned*)(lds + (bufoff) + ldsw + _i * 8192), 16, 0, 0); } while (0)
; #define PG8_LDA(dst, b, h) do { _Pragma("unroll") for (int m = 0; m < 4; ++m) _Pragma("unroll") for (int k = 0; k < 2; ++k) dst[m][k] = *(const PG8_LAS bf16x8*)(lds + PG8_SA(b, h) + aoff + m * 2048 + k * 1024); } while (0)
; #define PG8_LDB(dst, b, h) do { _Pragma("unroll") for (int n = 0; n < 2; ++n) _Pragma("unroll") for (int k = 0; k < 2; ++k) dst[n][k] = *(const PG8_LAS bf16x8*)(lds + PG8_SB(b, h) + boff + n * 2048 + k * 1024); } while (0)
; #define PG8_MMA(ai, bj, At, Bt) do { __builtin_amdgcn_s_setprio(1); _Pragma("unroll") for (int m = 0; m < 4; ++m) _Pragma("unroll") for (int n = 0; n < 2; ++n) _Pragma("unroll") for (int k = 0; k < 2; ++k) \
;         acc[ai][bj][m][n] = __builtin_amdgcn_mfma_f32_16x16x32_bf16(Bt[n][k], At[m][k], acc[ai][bj][m][n], 0, 0, 0); __builtin_amdgcn_s_setprio(0); } while (0)
; #define PG8_WAIT_V(n) asm volatile("s_waitcnt vmcnt(" #n ")" ::: "memory")
; #define PG8_WAIT_L(n) asm volatile("s_waitcnt lgkmcnt(" #n ")" ::: "memory")
; #define PG8_BAR __builtin_amdgcn_s_barrier()
; #define PG8_SCHED __builtin_amdgcn_sched_barrier(0)
; template <class Epi, class Sched, bool ALIGN_EPI = false, bool SP2 = false>
; __device__ __forceinline__ void gemm_phase(PG8_LAS unsigned char* lds, const Gemm g, const Sched& S, const Epi& E) {
;     ...
;             PG8_WAIT_V(8); PG8_WAIT_L(0); PG8_BAR; PG8_MMA(1, 0, At, B0); PG8_MMA(1, 1, At, B1); PG8_BAR; PG8_SCHED;
;             PG8_LDB(B0, 1, 0); PG8_LDB(B1, 1, 1); PG8_SCHED; PG8_LDA(At, 1, 0); PG8_STAGE(PG8_SA(0, 1), a2 + hstep, voffA);
;             PG8_WAIT_V(8); PG8_WAIT_L(0); PG8_BAR; PG8_MMA(0, 0, At, B0); PG8_MMA(0, 1, At, B1); PG8_BAR; PG8_SCHED;
	s_setprio 1
	s_waitcnt lgkmcnt(0)
	v_mfma_f32_16x16x32_bf16 v[60:63], v[166:169], v[198:201], v[60:63]
	v_mfma_f32_16x16x32_bf16 v[56:59], v[174:177], v[198:201], v[56:59]
	v_mfma_f32_16x16x32_bf16 v[52:55], v[166:169], v[206:209], v[52:55]
	v_mfma_f32_16x16x32_bf16 v[44:47], v[174:177], v[206:209], v[44:47]
	v_mfma_f32_16x16x32_bf16 v[36:39], v[166:169], v[214:217], v[36:39]
	v_mfma_f32_16x16x32_bf16 v[28:31], v[174:177], v[214:217], v[28:31]
	v_mfma_f32_16x16x32_bf16 v[20:23], v[166:169], v[222:225], v[20:23]
	v_mfma_f32_16x16x32_bf16 v[12:15], v[174:177], v[222:225], v[12:15]
	v_mfma_f32_16x16x32_bf16 v[60:63], v[170:173], v[202:205], v[60:63]
	v_mfma_f32_16x16x32_bf16 v[56:59], v[178:181], v[202:205], v[56:59]
	v_mfma_f32_16x16x32_bf16 v[52:55], v[170:173], v[210:213], v[52:55]
	v_mfma_f32_16x16x32_bf16 v[44:47], v[178:181], v[210:213], v[44:47]
	v_mfma_f32_16x16x32_bf16 v[36:39], v[170:173], v[218:221], v[36:39]
	v_mfma_f32_16x16x32_bf16 v[28:31], v[178:181], v[218:221], v[28:31]
	v_mfma_f32_16x16x32_bf16 v[20:23], v[170:173], v[226:229], v[20:23]
	v_mfma_f32_16x16x32_bf16 v[12:15], v[178:181], v[226:229], v[12:15]
	s_setprio 0
	s_setprio 1
	v_mfma_f32_16x16x32_bf16 v[48:51], v[182:185], v[198:201], v[48:51]
	v_mfma_f32_16x16x32_bf16 v[40:43], v[190:193], v[198:201], v[40:43]
	v_mfma_f32_16x16x32_bf16 v[32:35], v[182:185], v[206:209], v[32:35]
	v_mfma_f32_16x16x32_bf16 v[24:27], v[190:193], v[206:209], v[24:27]
	v_mfma_f32_16x16x32_bf16 v[16:19], v[182:185], v[214:217], v[16:19]
	v_mfma_f32_16x16x32_bf16 v[8:11], v[190:193], v[214:217], v[8:11]
	v_mfma_f32_16x16x32_bf16 v[4:7], v[182:185], v[222:225], v[4:7]
	v_mfma_f32_16x16x32_bf16 v[0:3], v[190:193], v[222:225], v[0:3]
	v_mfma_f32_16x16x32_bf16 v[48:51], v[186:189], v[202:205], v[48:51]
	v_mfma_f32_16x16x32_bf16 v[40:43], v[194:197], v[202:205], v[40:43]
	v_mfma_f32_16x16x32_bf16 v[32:35], v[186:189], v[210:213], v[32:35]
	v_mfma_f32_16x16x32_bf16 v[24:27], v[194:197], v[210:213], v[24:27]
	v_mfma_f32_16x16x32_bf16 v[16:19], v[186:189], v[218:221], v[16:19]
	v_mfma_f32_16x16x32_bf16 v[8:11], v[194:197], v[218:221], v[8:11]
	s_setprio 2
	s_barrier
	v_mfma_f32_16x16x32_bf16 v[4:7], v[186:189], v[226:229], v[4:7]
	v_mfma_f32_16x16x32_bf16 v[0:3], v[194:197], v[226:229], v[0:3]
	s_setprio 0
	ds_read_b128 v[166:169], v148
	ds_read_b128 v[170:173], v148 offset:1024
	ds_read_b128 v[174:177], v148 offset:2048
	ds_read_b128 v[178:181], v148 offset:3072
	ds_read_b128 v[182:185], v165
	ds_read_b128 v[186:189], v165 offset:1024
	ds_read_b128 v[190:193], v165 offset:2048
	ds_read_b128 v[194:197], v165 offset:3072
	s_add_u32 s52, s76, 0x200000
	s_addc_u32 s53, s77, 0
	s_mov_b32 m0, s33
	v_lshl_add_u64 v[238:239], s[52:53], 0, v[136:137]
	ds_read_b128 v[198:201], v164 offset:32768
	ds_read_b128 v[202:205], v164 offset:33792
	ds_read_b128 v[206:209], v164 offset:34816
	ds_read_b128 v[210:213], v164 offset:35840
	ds_read_b128 v[214:217], v164 offset:36864
	ds_read_b128 v[218:221], v164 offset:37888
	ds_read_b128 v[222:225], v164 offset:38912
	ds_read_b128 v[226:229], v164 offset:39936
	global_load_lds_dwordx4 v[238:239], off
	v_lshl_add_u64 v[238:239], s[52:53], 0, v[140:141]
	s_mov_b32 m0, s38
	s_nop 0
	global_load_lds_dwordx4 v[238:239], off
	s_waitcnt vmcnt(8)
	s_waitcnt lgkmcnt(0)
	s_barrier
	s_setprio 1
	s_waitcnt lgkmcnt(0)
	v_mfma_f32_16x16x32_bf16 v[124:127], v[166:169], v[198:201], v[124:127]
	v_mfma_f32_16x16x32_bf16 v[120:123], v[174:177], v[198:201], v[120:123]
	v_mfma_f32_16x16x32_bf16 v[116:119], v[166:169], v[206:209], v[116:119]
	v_mfma_f32_16x16x32_bf16 v[108:111], v[174:177], v[206:209], v[108:111]
	v_mfma_f32_16x16x32_bf16 v[100:103], v[166:169], v[214:217], v[100:103]
	v_mfma_f32_16x16x32_bf16 v[92:95], v[174:177], v[214:217], v[92:95]
	v_mfma_f32_16x16x32_bf16 v[84:87], v[166:169], v[222:225], v[84:87]
	v_mfma_f32_16x16x32_bf16 v[76:79], v[174:177], v[222:225], v[76:79]
	v_mfma_f32_16x16x32_bf16 v[124:127], v[170:173], v[202:205], v[124:127]
	v_mfma_f32_16x16x32_bf16 v[120:123], v[178:181], v[202:205], v[120:123]
	v_mfma_f32_16x16x32_bf16 v[116:119], v[170:173], v[210:213], v[116:119]
	v_mfma_f32_16x16x32_bf16 v[108:111], v[178:181], v[210:213], v[108:111]
	v_mfma_f32_16x16x32_bf16 v[100:103], v[170:173], v[218:221], v[100:103]
	v_mfma_f32_16x16x32_bf16 v[92:95], v[178:181], v[218:221], v[92:95]
	v_mfma_f32_16x16x32_bf16 v[84:87], v[170:173], v[226:229], v[84:87]
	v_mfma_f32_16x16x32_bf16 v[76:79], v[178:181], v[226:229], v[76:79]
	s_setprio 0
	s_setprio 1
	v_mfma_f32_16x16x32_bf16 v[112:115], v[182:185], v[198:201], v[112:115]
	v_mfma_f32_16x16x32_bf16 v[104:107], v[190:193], v[198:201], v[104:107]
	v_mfma_f32_16x16x32_bf16 v[96:99], v[182:185], v[206:209], v[96:99]
	v_mfma_f32_16x16x32_bf16 v[88:91], v[190:193], v[206:209], v[88:91]
	v_mfma_f32_16x16x32_bf16 v[80:83], v[182:185], v[214:217], v[80:83]
	v_mfma_f32_16x16x32_bf16 v[72:75], v[190:193], v[214:217], v[72:75]
	v_mfma_f32_16x16x32_bf16 v[68:71], v[182:185], v[222:225], v[68:71]
	v_mfma_f32_16x16x32_bf16 v[64:67], v[190:193], v[222:225], v[64:67]
	v_mfma_f32_16x16x32_bf16 v[112:115], v[186:189], v[202:205], v[112:115]
	v_mfma_f32_16x16x32_bf16 v[104:107], v[194:197], v[202:205], v[104:107]
	v_mfma_f32_16x16x32_bf16 v[96:99], v[186:189], v[210:213], v[96:99]
	v_mfma_f32_16x16x32_bf16 v[88:91], v[194:197], v[210:213], v[88:91]
	v_mfma_f32_16x16x32_bf16 v[80:83], v[186:189], v[218:221], v[80:83]
	v_mfma_f32_16x16x32_bf16 v[72:75], v[194:197], v[218:221], v[72:75]
	s_setprio 2
	s_barrier
; #define PG8_STAGE(bufoff, gbase, voff) do { _Pragma("unroll") for (int _i = 0; _i < 2; ++_i) \
;         __builtin_amdgcn_global_load_lds((const unsigned*)((const char*)(gbase) + (voff)[_i]), (PG8_LAS unsigned*)(lds + (bufoff) + ldsw + _i * 8192), 16, 0, 0); } while (0)
; #define PG8_LDA(dst, b, h) do { _Pragma("unroll") for (int m = 0; m < 4; ++m) _Pragma("unroll") for (int k = 0; k < 2; ++k) dst[m][k] = *(const PG8_LAS bf16x8*)(lds + PG8_SA(b, h) + aoff + m * 2048 + k * 1024); } while (0)
; #define PG8_MMA(ai, bj, At, Bt) do { __builtin_amdgcn_s_setprio(1); _Pragma("unroll") for (int m = 0; m < 4; ++m) _Pragma("unroll") for (int n = 0; n < 2; ++n) _Pragma("unroll") for (int k = 0; k < 2; ++k) \
;         acc[ai][bj][m][n] = __builtin_amdgcn_mfma_f32_16x16x32_bf16(Bt[n][k], At[m][k], acc[ai][bj][m][n], 0, 0, 0); __builtin_amdgcn_s_setprio(0); } while (0)
; #define PG8_WAIT_V(n) asm volatile("s_waitcnt vmcnt(" #n ")" ::: "memory")
; #define PG8_WAIT_L(n) asm volatile("s_waitcnt lgkmcnt(" #n ")" ::: "memory")
; #define PG8_BAR __builtin_amdgcn_s_barrier()
; #define PG8_SCHED __builtin_amdgcn_sched_barrier(0)
; template <class Epi, class Sched, bool ALIGN_EPI = false, bool SP2 = false>
; __device__ __forceinline__ void gemm_phase(PG8_LAS unsigned char* lds, const Gemm g, const Sched& S, const Epi& E) {
;     ...
;             PG8_WAIT_V(8); PG8_WAIT_L(0); PG8_BAR; PG8_MMA(0, 0, At, B0); PG8_MMA(0, 1, At, B1); PG8_BAR; PG8_SCHED;
;             PG8_LDA(At, 1, 1); PG8_STAGE(PG8_SB(1, 0), b3, voffB); PG8_STAGE(PG8_SB(1, 1), b3 + hstep, voffB); PG8_STAGE(PG8_SA(1, 0), a3, voffA);
;             PG8_WAIT_V(8); PG8_WAIT_L(0); PG8_BAR; PG8_MMA(1, 0, At, B0); PG8_MMA(1, 1, At, B1); PG8_BAR; PG8_SCHED;
	v_mfma_f32_16x16x32_bf16 v[68:71], v[186:189], v[226:229], v[68:71]
	v_mfma_f32_16x16x32_bf16 v[64:67], v[194:197], v[226:229], v[64:67]
	s_setprio 0
	s_mov_b32 m0, s89
	v_lshl_add_u64 v[230:231], v[230:231], 0, s[12:13]
	ds_read_b128 v[198:201], v164 offset:49152
	ds_read_b128 v[202:205], v164 offset:50176
	ds_read_b128 v[206:209], v164 offset:51200
	ds_read_b128 v[210:213], v164 offset:52224
	ds_read_b128 v[214:217], v164 offset:53248
	ds_read_b128 v[218:221], v164 offset:54272
	ds_read_b128 v[222:225], v164 offset:55296
	ds_read_b128 v[226:229], v164 offset:56320
	global_load_lds_dwordx4 v[230:231], off
	s_add_i32 m0, s89, 0x2000
	s_add_u32 s52, s74, 0x200080
	v_lshl_add_u64 v[230:231], v[232:233], 0, s[12:13]
	s_addc_u32 s53, s75, 0
	s_add_i32 s56, s88, s3
	global_load_lds_dwordx4 v[230:231], off
	v_lshl_add_u64 v[230:231], s[52:53], 0, v[138:139]
	s_mov_b32 m0, s56
	s_nop 0
	global_load_lds_dwordx4 v[230:231], off
	v_lshl_add_u64 v[230:231], s[52:53], 0, v[142:143]
	s_add_i32 m0, s56, 0x2000
	s_nop 0
	global_load_lds_dwordx4 v[230:231], off
	v_lshl_add_u64 v[230:231], v[234:235], 0, s[12:13]
	s_mov_b32 m0, s71
	s_nop 0
	global_load_lds_dwordx4 v[230:231], off
	v_lshl_add_u64 v[230:231], v[236:237], 0, s[12:13]
	s_mov_b32 m0, s78
	s_nop 0
	global_load_lds_dwordx4 v[230:231], off
	s_waitcnt vmcnt(8)
	s_waitcnt lgkmcnt(0)
	s_barrier
	s_setprio 1
	s_waitcnt lgkmcnt(0)
	v_mfma_f32_16x16x32_bf16 v[60:63], v[166:169], v[198:201], v[60:63]
	v_mfma_f32_16x16x32_bf16 v[56:59], v[174:177], v[198:201], v[56:59]
	v_mfma_f32_16x16x32_bf16 v[52:55], v[166:169], v[206:209], v[52:55]
	v_mfma_f32_16x16x32_bf16 v[44:47], v[174:177], v[206:209], v[44:47]
	v_mfma_f32_16x16x32_bf16 v[36:39], v[166:169], v[214:217], v[36:39]
	v_mfma_f32_16x16x32_bf16 v[28:31], v[174:177], v[214:217], v[28:31]
	v_mfma_f32_16x16x32_bf16 v[20:23], v[166:169], v[222:225], v[20:23]
	v_mfma_f32_16x16x32_bf16 v[12:15], v[174:177], v[222:225], v[12:15]
	v_mfma_f32_16x16x32_bf16 v[60:63], v[170:173], v[202:205], v[60:63]
	v_mfma_f32_16x16x32_bf16 v[56:59], v[178:181], v[202:205], v[56:59]
	v_mfma_f32_16x16x32_bf16 v[52:55], v[170:173], v[210:213], v[52:55]
	v_mfma_f32_16x16x32_bf16 v[44:47], v[178:181], v[210:213], v[44:47]
	v_mfma_f32_16x16x32_bf16 v[36:39], v[170:173], v[218:221], v[36:39]
	v_mfma_f32_16x16x32_bf16 v[28:31], v[178:181], v[218:221], v[28:31]
	v_mfma_f32_16x16x32_bf16 v[20:23], v[170:173], v[226:229], v[20:23]
	v_mfma_f32_16x16x32_bf16 v[12:15], v[178:181], v[226:229], v[12:15]
	s_setprio 0
	s_setprio 1
	v_mfma_f32_16x16x32_bf16 v[48:51], v[182:185], v[198:201], v[48:51]
	v_mfma_f32_16x16x32_bf16 v[40:43], v[190:193], v[198:201], v[40:43]
	v_mfma_f32_16x16x32_bf16 v[32:35], v[182:185], v[206:209], v[32:35]
	v_mfma_f32_16x16x32_bf16 v[24:27], v[190:193], v[206:209], v[24:27]
	v_mfma_f32_16x16x32_bf16 v[16:19], v[182:185], v[214:217], v[16:19]
	v_mfma_f32_16x16x32_bf16 v[8:11], v[190:193], v[214:217], v[8:11]
	v_mfma_f32_16x16x32_bf16 v[4:7], v[182:185], v[222:225], v[4:7]
	v_mfma_f32_16x16x32_bf16 v[0:3], v[190:193], v[222:225], v[0:3]
	v_mfma_f32_16x16x32_bf16 v[48:51], v[186:189], v[202:205], v[48:51]
	v_mfma_f32_16x16x32_bf16 v[40:43], v[194:197], v[202:205], v[40:43]
	v_mfma_f32_16x16x32_bf16 v[32:35], v[186:189], v[210:213], v[32:35]
	v_mfma_f32_16x16x32_bf16 v[24:27], v[194:197], v[210:213], v[24:27]
	v_mfma_f32_16x16x32_bf16 v[16:19], v[186:189], v[218:221], v[16:19]
	v_mfma_f32_16x16x32_bf16 v[8:11], v[194:197], v[218:221], v[8:11]
	s_setprio 2
	s_barrier
	v_mfma_f32_16x16x32_bf16 v[4:7], v[186:189], v[226:229], v[4:7]
	v_mfma_f32_16x16x32_bf16 v[0:3], v[194:197], v[226:229], v[0:3]
	s_setprio 0
	s_add_i32 s49, s49, 2
	s_add_u32 s72, s72, 0x100
	s_addc_u32 s73, s73, 0
	s_add_u32 s37, s37, 0x100
	s_addc_u32 s41, s41, 0
	s_cmp_gt_u32 s49, 29
	s_cbranch_scc0 .LBB0_660
	s_and_b64 vcc, exec, s[14:15]
	s_cbranch_vccz .LBB0_663
	s_barrier

; #define PG8_STAGE(bufoff, gbase, voff) do { _Pragma("unroll") for (int _i = 0; _i < 2; ++_i) \
;         __builtin_amdgcn_global_load_lds((const unsigned*)((const char*)(gbase) + (voff)[_i]), (PG8_LAS unsigned*)(lds + (bufoff) + ldsw + _i * 8192), 16, 0, 0); } while (0)
; #define PG8_LDA(dst, b, h) do { _Pragma("unroll") for (int m = 0; m < 4; ++m) _Pragma("unroll") for (int k = 0; k < 2; ++k) dst[m][k] = *(const PG8_LAS bf16x8*)(lds + PG8_SA(b, h) + aoff + m * 2048 + k * 1024); } while (0)
; #define PG8_LDB(dst, b, h) do { _Pragma("unroll") for (int n = 0; n < 2; ++n) _Pragma("unroll") for (int k = 0; k < 2; ++k) dst[n][k] = *(const PG8_LAS bf16x8*)(lds + PG8_SB(b, h) + boff + n * 2048 + k * 1024); } while (0)
; #define PG8_MMA(ai, bj, At, Bt) do { __builtin_amdgcn_s_setprio(1); _Pragma("unroll") for (int m = 0; m < 4; ++m) _Pragma("unroll") for (int n = 0; n < 2; ++n) _Pragma("unroll") for (int k = 0; k < 2; ++k) \
;         acc[ai][bj][m][n] = __builtin_amdgcn_mfma_f32_16x16x32_bf16(Bt[n][k], At[m][k], acc[ai][bj][m][n], 0, 0, 0); __builtin_amdgcn_s_setprio(0); } while (0)
; #define PG8_WAIT_V(n) asm volatile("s_waitcnt vmcnt(" #n ")" ::: "memory")
; #define PG8_WAIT_L(n) asm volatile("s_waitcnt lgkmcnt(" #n ")" ::: "memory")
; #define PG8_BAR __builtin_amdgcn_s_barrier()
; template <class Epi, class Sched, bool ALIGN_EPI = false, bool SP2 = false>
; __device__ __forceinline__ void gemm_phase(PG8_LAS unsigned char* lds, const Gemm g, const Sched& S, const Epi& E) {
;     ...
;         for (int t = 0; t < nt; t += 2) {
;             const bool last = (t == nt - 2);
;             const char* a1 = cA + (size_t)(t + 1) * kstep;
;             const char* a2 = last ? nA : cA + (size_t)(t + 2) * kstep; const char* b2 = last ? nB : cB + (size_t)(t + 2) * kstep;
;             const char* a3 = a2 + kstep; const char* b3 = b2 + kstep;
;             if constexpr (SP2) {
;             PG8_LDB(B0, 0, 0); PG8_LDB(B1, 0, 1); PG8_SCHED; PG8_LDA(At, 0, 0); PG8_STAGE(PG8_SA(1, 1), a1 + hstep, voffA);
;             PG8_WAIT_V(8); PG8_WAIT_L(0); PG8_BAR; PG8_MMA(0, 0, At, B0); PG8_MMA(0, 1, At, B1); PG8_BAR; PG8_SCHED;
;             PG8_LDA(At, 0, 1); PG8_STAGE(PG8_SB(0, 0), b2, voffB); PG8_STAGE(PG8_SB(0, 1), b2 + hstep, voffB); PG8_STAGE(PG8_SA(0, 0), a2, voffA);
;             PG8_WAIT_V(8); PG8_WAIT_L(0); PG8_BAR; PG8_MMA(1, 0, At, B0); PG8_MMA(1, 1, At, B1); PG8_BAR; PG8_SCHED;
.LBB0_809:
	ds_read_b128 v[128:131], v180
	ds_read_b128 v[132:135], v180 offset:1024
	ds_read_b128 v[136:139], v180 offset:2048
	ds_read_b128 v[140:143], v180 offset:3072
	ds_read_b128 v[160:163], v181
	ds_read_b128 v[164:167], v181 offset:1024
	ds_read_b128 v[184:187], v181 offset:2048
	ds_read_b128 v[188:191], v181 offset:3072
	s_add_u32 s52, s72, 0xfff80080
	s_addc_u32 s53, s73, -1
	s_cmp_eq_u32 s92, 28
	s_cselect_b32 s77, s5, s53
	s_cselect_b32 s76, s49, s52
	s_cselect_b32 s75, s45, s91
	s_cselect_b32 s74, s89, s90
	v_lshl_add_u64 v[168:169], s[72:73], 0, v[154:155]
	s_add_i32 m0, s71, 0xc000
	ds_read_b128 v[192:195], v182
	ds_read_b128 v[196:199], v182 offset:1024
	ds_read_b128 v[200:203], v182 offset:2048
	ds_read_b128 v[204:207], v182 offset:3072
	ds_read_b128 v[208:211], v182 offset:4096
	ds_read_b128 v[212:215], v182 offset:5120
	ds_read_b128 v[216:219], v182 offset:6144
	ds_read_b128 v[220:223], v182 offset:7168
	global_load_lds_dwordx4 v[168:169], off
	v_lshl_add_u64 v[168:169], s[72:73], 0, v[156:157]
	s_add_i32 m0, s71, 0xe000
	s_nop 0
	global_load_lds_dwordx4 v[168:169], off
	s_waitcnt vmcnt(8)
	s_waitcnt lgkmcnt(0)
	s_barrier
	s_setprio 1
	s_waitcnt lgkmcnt(0)
	v_mfma_f32_16x16x32_bf16 v[124:127], v[128:131], v[192:195], v[124:127]
	v_mfma_f32_16x16x32_bf16 v[120:123], v[136:139], v[192:195], v[120:123]
	v_mfma_f32_16x16x32_bf16 v[108:111], v[128:131], v[200:203], v[108:111]
	v_mfma_f32_16x16x32_bf16 v[104:107], v[136:139], v[200:203], v[104:107]
	v_mfma_f32_16x16x32_bf16 v[92:95], v[128:131], v[208:211], v[92:95]
	v_mfma_f32_16x16x32_bf16 v[88:91], v[136:139], v[208:211], v[88:91]
	v_mfma_f32_16x16x32_bf16 v[76:79], v[128:131], v[216:219], v[76:79]
	v_mfma_f32_16x16x32_bf16 v[72:75], v[136:139], v[216:219], v[72:75]
	v_mfma_f32_16x16x32_bf16 v[124:127], v[132:135], v[196:199], v[124:127]
	v_mfma_f32_16x16x32_bf16 v[120:123], v[140:143], v[196:199], v[120:123]
	v_mfma_f32_16x16x32_bf16 v[108:111], v[132:135], v[204:207], v[108:111]
	v_mfma_f32_16x16x32_bf16 v[104:107], v[140:143], v[204:207], v[104:107]
	v_mfma_f32_16x16x32_bf16 v[92:95], v[132:135], v[212:215], v[92:95]
	v_mfma_f32_16x16x32_bf16 v[88:91], v[140:143], v[212:215], v[88:91]
	v_mfma_f32_16x16x32_bf16 v[76:79], v[132:135], v[220:223], v[76:79]
	v_mfma_f32_16x16x32_bf16 v[72:75], v[140:143], v[220:223], v[72:75]
	s_setprio 0
	s_setprio 1
	v_mfma_f32_16x16x32_bf16 v[116:119], v[160:163], v[192:195], v[116:119]
	v_mfma_f32_16x16x32_bf16 v[112:115], v[184:187], v[192:195], v[112:115]
	v_mfma_f32_16x16x32_bf16 v[100:103], v[160:163], v[200:203], v[100:103]
	v_mfma_f32_16x16x32_bf16 v[96:99], v[184:187], v[200:203], v[96:99]
	v_mfma_f32_16x16x32_bf16 v[84:87], v[160:163], v[208:211], v[84:87]
	v_mfma_f32_16x16x32_bf16 v[80:83], v[184:187], v[208:211], v[80:83]
	v_mfma_f32_16x16x32_bf16 v[68:71], v[160:163], v[216:219], v[68:71]
	v_mfma_f32_16x16x32_bf16 v[64:67], v[184:187], v[216:219], v[64:67]
	v_mfma_f32_16x16x32_bf16 v[116:119], v[164:167], v[196:199], v[116:119]
	v_mfma_f32_16x16x32_bf16 v[112:115], v[188:191], v[196:199], v[112:115]
	v_mfma_f32_16x16x32_bf16 v[100:103], v[164:167], v[204:207], v[100:103]
	v_mfma_f32_16x16x32_bf16 v[96:99], v[188:191], v[204:207], v[96:99]
	v_mfma_f32_16x16x32_bf16 v[84:87], v[164:167], v[212:215], v[84:87]
	v_mfma_f32_16x16x32_bf16 v[80:83], v[188:191], v[212:215], v[80:83]
	s_setprio 2
	s_barrier
	v_mfma_f32_16x16x32_bf16 v[68:71], v[164:167], v[220:223], v[68:71]
	v_mfma_f32_16x16x32_bf16 v[64:67], v[188:191], v[220:223], v[64:67]
	s_setprio 0
	s_add_i32 s52, s83, s78
	v_lshl_add_u64 v[168:169], s[74:75], 0, v[148:149]
	s_mov_b32 m0, s52
	ds_read_b128 v[192:195], v182 offset:16384
	ds_read_b128 v[196:199], v182 offset:17408
	ds_read_b128 v[200:203], v182 offset:18432
	ds_read_b128 v[204:207], v182 offset:19456
	ds_read_b128 v[208:211], v182 offset:20480
	ds_read_b128 v[212:215], v182 offset:21504
	ds_read_b128 v[216:219], v182 offset:22528
	ds_read_b128 v[220:223], v182 offset:23552
	global_load_lds_dwordx4 v[168:169], off
	s_add_i32 m0, s52, 0x2000
	s_add_u32 s52, s74, 0x80000
	v_lshl_add_u64 v[224:225], s[74:75], 0, v[152:153]
	s_addc_u32 s53, s75, 0
	s_add_i32 s56, s84, s78
	global_load_lds_dwordx4 v[224:225], off
	v_lshl_add_u64 v[226:227], s[52:53], 0, v[148:149]
	s_mov_b32 m0, s56
	v_lshl_add_u64 v[228:229], s[76:77], 0, v[150:151]
	global_load_lds_dwordx4 v[226:227], off
	v_lshl_add_u64 v[226:227], s[52:53], 0, v[152:153]
	s_add_i32 m0, s56, 0x2000
	s_nop 0
	global_load_lds_dwordx4 v[226:227], off
	v_lshl_add_u64 v[226:227], s[76:77], 0, v[144:145]
	s_mov_b32 m0, s71
	s_nop 0
	global_load_lds_dwordx4 v[226:227], off
	s_mov_b32 m0, s79
	s_nop 0
	global_load_lds_dwordx4 v[228:229], off
	s_waitcnt vmcnt(8)
	s_waitcnt lgkmcnt(0)
	s_barrier
; #define PG8_STAGE(bufoff, gbase, voff) do { _Pragma("unroll") for (int _i = 0; _i < 2; ++_i) \
;         __builtin_amdgcn_global_load_lds((const unsigned*)((const char*)(gbase) + (voff)[_i]), (PG8_LAS unsigned*)(lds + (bufoff) + ldsw + _i * 8192), 16, 0, 0); } while (0)
; #define PG8_LDA(dst, b, h) do { _Pragma("unroll") for (int m = 0; m < 4; ++m) _Pragma("unroll") for (int k = 0; k < 2; ++k) dst[m][k] = *(const PG8_LAS bf16x8*)(lds + PG8_SA(b, h) + aoff + m * 2048 + k * 1024); } while (0)
; #define PG8_LDB(dst, b, h) do { _Pragma("unroll") for (int n = 0; n < 2; ++n) _Pragma("unroll") for (int k = 0; k < 2; ++k) dst[n][k] = *(const PG8_LAS bf16x8*)(lds + PG8_SB(b, h) + boff + n * 2048 + k * 1024); } while (0)
; #define PG8_MMA(ai, bj, At, Bt) do { __builtin_amdgcn_s_setprio(1); _Pragma("unroll") for (int m = 0; m < 4; ++m) _Pragma("unroll") for (int n = 0; n < 2; ++n) _Pragma("unroll") for (int k = 0; k < 2; ++k) \
;         acc[ai][bj][m][n] = __builtin_amdgcn_mfma_f32_16x16x32_bf16(Bt[n][k], At[m][k], acc[ai][bj][m][n], 0, 0, 0); __builtin_amdgcn_s_setprio(0); } while (0)
; #define PG8_WAIT_V(n) asm volatile("s_waitcnt vmcnt(" #n ")" ::: "memory")
; #define PG8_WAIT_L(n) asm volatile("s_waitcnt lgkmcnt(" #n ")" ::: "memory")
; #define PG8_BAR __builtin_amdgcn_s_barrier()
; #define PG8_SCHED __builtin_amdgcn_sched_barrier(0)
; template <class Epi, class Sched, bool ALIGN_EPI = false, bool SP2 = false>
; __device__ __forceinline__ void gemm_phase(PG8_LAS unsigned char* lds, const Gemm g, const Sched& S, const Epi& E) {
;     ...
;             PG8_WAIT_V(8); PG8_WAIT_L(0); PG8_BAR; PG8_MMA(1, 0, At, B0); PG8_MMA(1, 1, At, B1); PG8_BAR; PG8_SCHED;
;             PG8_LDB(B0, 1, 0); PG8_LDB(B1, 1, 1); PG8_SCHED; PG8_LDA(At, 1, 0); PG8_STAGE(PG8_SA(0, 1), a2 + hstep, voffA);
;             PG8_WAIT_V(8); PG8_WAIT_L(0); PG8_BAR; PG8_MMA(0, 0, At, B0); PG8_MMA(0, 1, At, B1); PG8_BAR; PG8_SCHED;
	s_setprio 1
	s_waitcnt lgkmcnt(0)
	v_mfma_f32_16x16x32_bf16 v[60:63], v[128:131], v[192:195], v[60:63]
	v_mfma_f32_16x16x32_bf16 v[56:59], v[136:139], v[192:195], v[56:59]
	v_mfma_f32_16x16x32_bf16 v[44:47], v[128:131], v[200:203], v[44:47]
	v_mfma_f32_16x16x32_bf16 v[40:43], v[136:139], v[200:203], v[40:43]
	v_mfma_f32_16x16x32_bf16 v[28:31], v[128:131], v[208:211], v[28:31]
	v_mfma_f32_16x16x32_bf16 v[24:27], v[136:139], v[208:211], v[24:27]
	v_mfma_f32_16x16x32_bf16 v[12:15], v[128:131], v[216:219], v[12:15]
	v_mfma_f32_16x16x32_bf16 v[8:11], v[136:139], v[216:219], v[8:11]
	v_mfma_f32_16x16x32_bf16 v[60:63], v[132:135], v[196:199], v[60:63]
	v_mfma_f32_16x16x32_bf16 v[56:59], v[140:143], v[196:199], v[56:59]
	v_mfma_f32_16x16x32_bf16 v[44:47], v[132:135], v[204:207], v[44:47]
	v_mfma_f32_16x16x32_bf16 v[40:43], v[140:143], v[204:207], v[40:43]
	v_mfma_f32_16x16x32_bf16 v[28:31], v[132:135], v[212:215], v[28:31]
	v_mfma_f32_16x16x32_bf16 v[24:27], v[140:143], v[212:215], v[24:27]
	v_mfma_f32_16x16x32_bf16 v[12:15], v[132:135], v[220:223], v[12:15]
	v_mfma_f32_16x16x32_bf16 v[8:11], v[140:143], v[220:223], v[8:11]
	s_setprio 0
	s_setprio 1
	v_mfma_f32_16x16x32_bf16 v[52:55], v[160:163], v[192:195], v[52:55]
	v_mfma_f32_16x16x32_bf16 v[48:51], v[184:187], v[192:195], v[48:51]
	v_mfma_f32_16x16x32_bf16 v[36:39], v[160:163], v[200:203], v[36:39]
	v_mfma_f32_16x16x32_bf16 v[32:35], v[184:187], v[200:203], v[32:35]
	v_mfma_f32_16x16x32_bf16 v[20:23], v[160:163], v[208:211], v[20:23]
	v_mfma_f32_16x16x32_bf16 v[16:19], v[184:187], v[208:211], v[16:19]
	v_mfma_f32_16x16x32_bf16 v[4:7], v[160:163], v[216:219], v[4:7]
	v_mfma_f32_16x16x32_bf16 v[0:3], v[184:187], v[216:219], v[0:3]
	v_mfma_f32_16x16x32_bf16 v[52:55], v[164:167], v[196:199], v[52:55]
	v_mfma_f32_16x16x32_bf16 v[48:51], v[188:191], v[196:199], v[48:51]
	v_mfma_f32_16x16x32_bf16 v[36:39], v[164:167], v[204:207], v[36:39]
	v_mfma_f32_16x16x32_bf16 v[32:35], v[188:191], v[204:207], v[32:35]
	v_mfma_f32_16x16x32_bf16 v[20:23], v[164:167], v[212:215], v[20:23]
	v_mfma_f32_16x16x32_bf16 v[16:19], v[188:191], v[212:215], v[16:19]
	s_setprio 2
	s_barrier
	v_mfma_f32_16x16x32_bf16 v[4:7], v[164:167], v[220:223], v[4:7]
	v_mfma_f32_16x16x32_bf16 v[0:3], v[188:191], v[220:223], v[0:3]
	s_setprio 0
	s_add_i32 s56, 0, 0x18000
	s_add_i32 s57, 0, 0x1c000
	v_add_u32_e32 v140, s56, v171
	v_add_u32_e32 v188, s57, v171
	ds_read_b128 v[128:131], v140
	ds_read_b128 v[132:135], v140 offset:1024
	ds_read_b128 v[136:139], v140 offset:2048
	ds_read_b128 v[140:143], v140 offset:3072
	ds_read_b128 v[160:163], v188
	ds_read_b128 v[164:167], v188 offset:1024
	ds_read_b128 v[184:187], v188 offset:2048
	ds_read_b128 v[188:191], v188 offset:3072
	s_add_u32 s52, s76, 0x80000
	s_addc_u32 s53, s77, 0
	s_mov_b32 m0, s80
	v_lshl_add_u64 v[230:231], s[52:53], 0, v[144:145]
	ds_read_b128 v[192:195], v182 offset:32768
	ds_read_b128 v[196:199], v182 offset:33792
	ds_read_b128 v[200:203], v182 offset:34816
	ds_read_b128 v[204:207], v182 offset:35840
	ds_read_b128 v[208:211], v182 offset:36864
	ds_read_b128 v[212:215], v182 offset:37888
	ds_read_b128 v[216:219], v182 offset:38912
	ds_read_b128 v[220:223], v182 offset:39936
	global_load_lds_dwordx4 v[230:231], off
	v_lshl_add_u64 v[230:231], s[52:53], 0, v[150:151]
	s_mov_b32 m0, s81
	s_nop 0
	global_load_lds_dwordx4 v[230:231], off
	s_waitcnt vmcnt(8)
	s_waitcnt lgkmcnt(0)
	s_barrier
	s_setprio 1
	s_waitcnt lgkmcnt(0)
	v_mfma_f32_16x16x32_bf16 v[124:127], v[128:131], v[192:195], v[124:127]
	v_mfma_f32_16x16x32_bf16 v[120:123], v[136:139], v[192:195], v[120:123]
	v_mfma_f32_16x16x32_bf16 v[108:111], v[128:131], v[200:203], v[108:111]
	v_mfma_f32_16x16x32_bf16 v[104:107], v[136:139], v[200:203], v[104:107]
	v_mfma_f32_16x16x32_bf16 v[92:95], v[128:131], v[208:211], v[92:95]
	v_mfma_f32_16x16x32_bf16 v[88:91], v[136:139], v[208:211], v[88:91]
	v_mfma_f32_16x16x32_bf16 v[76:79], v[128:131], v[216:219], v[76:79]
	v_mfma_f32_16x16x32_bf16 v[72:75], v[136:139], v[216:219], v[72:75]
	v_mfma_f32_16x16x32_bf16 v[124:127], v[132:135], v[196:199], v[124:127]
	v_mfma_f32_16x16x32_bf16 v[120:123], v[140:143], v[196:199], v[120:123]
	v_mfma_f32_16x16x32_bf16 v[108:111], v[132:135], v[204:207], v[108:111]
	v_mfma_f32_16x16x32_bf16 v[104:107], v[140:143], v[204:207], v[104:107]
	v_mfma_f32_16x16x32_bf16 v[92:95], v[132:135], v[212:215], v[92:95]
	v_mfma_f32_16x16x32_bf16 v[88:91], v[140:143], v[212:215], v[88:91]
	v_mfma_f32_16x16x32_bf16 v[76:79], v[132:135], v[220:223], v[76:79]
	v_mfma_f32_16x16x32_bf16 v[72:75], v[140:143], v[220:223], v[72:75]
	s_setprio 0
	s_setprio 1
	v_mfma_f32_16x16x32_bf16 v[116:119], v[160:163], v[192:195], v[116:119]
	v_mfma_f32_16x16x32_bf16 v[112:115], v[184:187], v[192:195], v[112:115]
	v_mfma_f32_16x16x32_bf16 v[100:103], v[160:163], v[200:203], v[100:103]
	v_mfma_f32_16x16x32_bf16 v[96:99], v[184:187], v[200:203], v[96:99]
	v_mfma_f32_16x16x32_bf16 v[84:87], v[160:163], v[208:211], v[84:87]
	v_mfma_f32_16x16x32_bf16 v[80:83], v[184:187], v[208:211], v[80:83]
	v_mfma_f32_16x16x32_bf16 v[68:71], v[160:163], v[216:219], v[68:71]
	v_mfma_f32_16x16x32_bf16 v[64:67], v[184:187], v[216:219], v[64:67]
	v_mfma_f32_16x16x32_bf16 v[116:119], v[164:167], v[196:199], v[116:119]
	v_mfma_f32_16x16x32_bf16 v[112:115], v[188:191], v[196:199], v[112:115]
	v_mfma_f32_16x16x32_bf16 v[100:103], v[164:167], v[204:207], v[100:103]
	v_mfma_f32_16x16x32_bf16 v[96:99], v[188:191], v[204:207], v[96:99]
	v_mfma_f32_16x16x32_bf16 v[84:87], v[164:167], v[212:215], v[84:87]
	v_mfma_f32_16x16x32_bf16 v[80:83], v[188:191], v[212:215], v[80:83]
	s_setprio 2
	s_barrier
; #define PG8_STAGE(bufoff, gbase, voff) do { _Pragma("unroll") for (int _i = 0; _i < 2; ++_i) \
;         __builtin_amdgcn_global_load_lds((const unsigned*)((const char*)(gbase) + (voff)[_i]), (PG8_LAS unsigned*)(lds + (bufoff) + ldsw + _i * 8192), 16, 0, 0); } while (0)
; #define PG8_LDA(dst, b, h) do { _Pragma("unroll") for (int m = 0; m < 4; ++m) _Pragma("unroll") for (int k = 0; k < 2; ++k) dst[m][k] = *(const PG8_LAS bf16x8*)(lds + PG8_SA(b, h) + aoff + m * 2048 + k * 1024); } while (0)
; #define PG8_MMA(ai, bj, At, Bt) do { __builtin_amdgcn_s_setprio(1); _Pragma("unroll") for (int m = 0; m < 4; ++m) _Pragma("unroll") for (int n = 0; n < 2; ++n) _Pragma("unroll") for (int k = 0; k < 2; ++k) \
;         acc[ai][bj][m][n] = __builtin_amdgcn_mfma_f32_16x16x32_bf16(Bt[n][k], At[m][k], acc[ai][bj][m][n], 0, 0, 0); __builtin_amdgcn_s_setprio(0); } while (0)
; #define PG8_WAIT_V(n) asm volatile("s_waitcnt vmcnt(" #n ")" ::: "memory")
; #define PG8_WAIT_L(n) asm volatile("s_waitcnt lgkmcnt(" #n ")" ::: "memory")
; #define PG8_BAR __builtin_amdgcn_s_barrier()
; #define PG8_SCHED __builtin_amdgcn_sched_barrier(0)
; template <class Epi, class Sched, bool ALIGN_EPI = false, bool SP2 = false>
; __device__ __forceinline__ void gemm_phase(PG8_LAS unsigned char* lds, const Gemm g, const Sched& S, const Epi& E) {
;     ...
;             PG8_WAIT_V(8); PG8_WAIT_L(0); PG8_BAR; PG8_MMA(0, 0, At, B0); PG8_MMA(0, 1, At, B1); PG8_BAR; PG8_SCHED;
;             PG8_LDA(At, 1, 1); PG8_STAGE(PG8_SB(1, 0), b3, voffB); PG8_STAGE(PG8_SB(1, 1), b3 + hstep, voffB); PG8_STAGE(PG8_SA(1, 0), a3, voffA);
;             PG8_WAIT_V(8); PG8_WAIT_L(0); PG8_BAR; PG8_MMA(1, 0, At, B0); PG8_MMA(1, 1, At, B1); PG8_BAR; PG8_SCHED;
	v_mfma_f32_16x16x32_bf16 v[68:71], v[164:167], v[220:223], v[68:71]
	v_mfma_f32_16x16x32_bf16 v[64:67], v[188:191], v[220:223], v[64:67]
	s_setprio 0
	s_add_i32 s52, s56, s78
	v_lshl_add_u64 v[168:169], v[168:169], 0, s[40:41]
	s_mov_b32 m0, s52
	ds_read_b128 v[192:195], v182 offset:49152
	ds_read_b128 v[196:199], v182 offset:50176
	ds_read_b128 v[200:203], v182 offset:51200
	ds_read_b128 v[204:207], v182 offset:52224
	ds_read_b128 v[208:211], v182 offset:53248
	ds_read_b128 v[212:215], v182 offset:54272
	ds_read_b128 v[216:219], v182 offset:55296
	ds_read_b128 v[220:223], v182 offset:56320
	global_load_lds_dwordx4 v[168:169], off
	s_add_i32 m0, s52, 0x2000
	s_add_u32 s52, s74, 0x80080
	v_lshl_add_u64 v[168:169], v[224:225], 0, s[40:41]
	s_addc_u32 s53, s75, 0
	s_add_i32 s56, s57, s78
	global_load_lds_dwordx4 v[168:169], off
	v_lshl_add_u64 v[168:169], s[52:53], 0, v[148:149]
	s_mov_b32 m0, s56
	s_nop 0
	global_load_lds_dwordx4 v[168:169], off
	v_lshl_add_u64 v[168:169], s[52:53], 0, v[152:153]
	s_add_i32 m0, s56, 0x2000
	s_nop 0
	global_load_lds_dwordx4 v[168:169], off
	v_lshl_add_u64 v[168:169], v[226:227], 0, s[40:41]
	s_mov_b32 m0, s3
	s_nop 0
	global_load_lds_dwordx4 v[168:169], off
	v_lshl_add_u64 v[168:169], v[228:229], 0, s[40:41]
	s_mov_b32 m0, s28
	s_nop 0
	global_load_lds_dwordx4 v[168:169], off
	s_waitcnt vmcnt(8)
	s_waitcnt lgkmcnt(0)
	s_barrier
	s_setprio 1
	s_waitcnt lgkmcnt(0)
	v_mfma_f32_16x16x32_bf16 v[60:63], v[128:131], v[192:195], v[60:63]
	v_mfma_f32_16x16x32_bf16 v[56:59], v[136:139], v[192:195], v[56:59]
	v_mfma_f32_16x16x32_bf16 v[44:47], v[128:131], v[200:203], v[44:47]
	v_mfma_f32_16x16x32_bf16 v[40:43], v[136:139], v[200:203], v[40:43]
	v_mfma_f32_16x16x32_bf16 v[28:31], v[128:131], v[208:211], v[28:31]
	v_mfma_f32_16x16x32_bf16 v[24:27], v[136:139], v[208:211], v[24:27]
	v_mfma_f32_16x16x32_bf16 v[12:15], v[128:131], v[216:219], v[12:15]
	v_mfma_f32_16x16x32_bf16 v[8:11], v[136:139], v[216:219], v[8:11]
	v_mfma_f32_16x16x32_bf16 v[60:63], v[132:135], v[196:199], v[60:63]
	v_mfma_f32_16x16x32_bf16 v[56:59], v[140:143], v[196:199], v[56:59]
	v_mfma_f32_16x16x32_bf16 v[44:47], v[132:135], v[204:207], v[44:47]
	v_mfma_f32_16x16x32_bf16 v[40:43], v[140:143], v[204:207], v[40:43]
	v_mfma_f32_16x16x32_bf16 v[28:31], v[132:135], v[212:215], v[28:31]
	v_mfma_f32_16x16x32_bf16 v[24:27], v[140:143], v[212:215], v[24:27]
	v_mfma_f32_16x16x32_bf16 v[12:15], v[132:135], v[220:223], v[12:15]
	v_mfma_f32_16x16x32_bf16 v[8:11], v[140:143], v[220:223], v[8:11]
	s_setprio 0
	s_setprio 1
	v_mfma_f32_16x16x32_bf16 v[52:55], v[160:163], v[192:195], v[52:55]
	v_mfma_f32_16x16x32_bf16 v[48:51], v[184:187], v[192:195], v[48:51]
	v_mfma_f32_16x16x32_bf16 v[36:39], v[160:163], v[200:203], v[36:39]
	v_mfma_f32_16x16x32_bf16 v[32:35], v[184:187], v[200:203], v[32:35]
	v_mfma_f32_16x16x32_bf16 v[20:23], v[160:163], v[208:211], v[20:23]
	v_mfma_f32_16x16x32_bf16 v[16:19], v[184:187], v[208:211], v[16:19]
	v_mfma_f32_16x16x32_bf16 v[4:7], v[160:163], v[216:219], v[4:7]
	v_mfma_f32_16x16x32_bf16 v[0:3], v[184:187], v[216:219], v[0:3]
	v_mfma_f32_16x16x32_bf16 v[52:55], v[164:167], v[196:199], v[52:55]
	v_mfma_f32_16x16x32_bf16 v[48:51], v[188:191], v[196:199], v[48:51]
	v_mfma_f32_16x16x32_bf16 v[36:39], v[164:167], v[204:207], v[36:39]
	v_mfma_f32_16x16x32_bf16 v[32:35], v[188:191], v[204:207], v[32:35]
	v_mfma_f32_16x16x32_bf16 v[20:23], v[164:167], v[212:215], v[20:23]
	v_mfma_f32_16x16x32_bf16 v[16:19], v[188:191], v[212:215], v[16:19]
	s_setprio 2
	s_barrier
	v_mfma_f32_16x16x32_bf16 v[4:7], v[164:167], v[220:223], v[4:7]
	v_mfma_f32_16x16x32_bf16 v[0:3], v[188:191], v[220:223], v[0:3]
	s_setprio 0
	s_add_i32 s92, s92, 2
	s_add_u32 s72, s72, 0x100
	s_addc_u32 s73, s73, 0
	s_add_u32 s90, s90, 0x100
	s_addc_u32 s91, s91, 0
	s_cmp_gt_u32 s92, 29
	s_cbranch_scc0 .LBB0_809
	s_and_b64 vcc, exec, s[42:43]
	s_cbranch_vccz .LBB0_812
	s_barrier

; #define PG8_STAGE(bufoff, gbase, voff) do { _Pragma("unroll") for (int _i = 0; _i < 2; ++_i) \
;         __builtin_amdgcn_global_load_lds((const unsigned*)((const char*)(gbase) + (voff)[_i]), (PG8_LAS unsigned*)(lds + (bufoff) + ldsw + _i * 8192), 16, 0, 0); } while (0)
; #define PG8_LDA(dst, b, h) do { _Pragma("unroll") for (int m = 0; m < 4; ++m) _Pragma("unroll") for (int k = 0; k < 2; ++k) dst[m][k] = *(const PG8_LAS bf16x8*)(lds + PG8_SA(b, h) + aoff + m * 2048 + k * 1024); } while (0)
; #define PG8_LDB(dst, b, h) do { _Pragma("unroll") for (int n = 0; n < 2; ++n) _Pragma("unroll") for (int k = 0; k < 2; ++k) dst[n][k] = *(const PG8_LAS bf16x8*)(lds + PG8_SB(b, h) + boff + n * 2048 + k * 1024); } while (0)
; #define PG8_MMA(ai, bj, At, Bt) do { __builtin_amdgcn_s_setprio(1); _Pragma("unroll") for (int m = 0; m < 4; ++m) _Pragma("unroll") for (int n = 0; n < 2; ++n) _Pragma("unroll") for (int k = 0; k < 2; ++k) \
;         acc[ai][bj][m][n] = __builtin_amdgcn_mfma_f32_16x16x32_bf16(Bt[n][k], At[m][k], acc[ai][bj][m][n], 0, 0, 0); __builtin_amdgcn_s_setprio(0); } while (0)
; #define PG8_WAIT_V(n) asm volatile("s_waitcnt vmcnt(" #n ")" ::: "memory")
; #define PG8_WAIT_L(n) asm volatile("s_waitcnt lgkmcnt(" #n ")" ::: "memory")
; #define PG8_BAR __builtin_amdgcn_s_barrier()
; template <class Epi, class Sched, bool ALIGN_EPI = false, bool SP2 = false>
; __device__ __forceinline__ void gemm_phase(PG8_LAS unsigned char* lds, const Gemm g, const Sched& S, const Epi& E) {
;     ...
;             const bool last = (t == nt - 2);
;             const char* a1 = cA + (size_t)(t + 1) * kstep;
;             const char* a2 = last ? nA : cA + (size_t)(t + 2) * kstep; const char* b2 = last ? nB : cB + (size_t)(t + 2) * kstep;
;             const char* a3 = a2 + kstep; const char* b3 = b2 + kstep;
;             if constexpr (SP2) {
;             PG8_LDB(B0, 0, 0); PG8_LDB(B1, 0, 1); PG8_SCHED; PG8_LDA(At, 0, 0); PG8_STAGE(PG8_SA(1, 1), a1 + hstep, voffA);
;             PG8_WAIT_V(8); PG8_WAIT_L(0); PG8_BAR; PG8_MMA(0, 0, At, B0); PG8_MMA(0, 1, At, B1); PG8_BAR; PG8_SCHED;
;             PG8_LDA(At, 0, 1); PG8_STAGE(PG8_SB(0, 0), b2, voffB); PG8_STAGE(PG8_SB(0, 1), b2 + hstep, voffB); PG8_STAGE(PG8_SA(0, 0), a2, voffA);
;             PG8_WAIT_V(8); PG8_WAIT_L(0); PG8_BAR; PG8_MMA(1, 0, At, B0); PG8_MMA(1, 1, At, B1); PG8_BAR; PG8_SCHED;
.LBB0_1051:
	ds_read_b128 v[128:131], v205
	ds_read_b128 v[132:135], v205 offset:1024
	ds_read_b128 v[154:157], v205 offset:2048
	ds_read_b128 v[158:161], v205 offset:3072
	ds_read_b128 v[162:165], v206
	ds_read_b128 v[166:169], v206 offset:1024
	ds_read_b128 v[170:173], v206 offset:2048
	ds_read_b128 v[174:177], v206 offset:3072
	s_add_u32 s54, s52, 0xfff80080
	s_addc_u32 s55, s53, -1
	s_cmp_eq_u32 s77, 28
	s_cselect_b32 s57, s43, s55
	s_cselect_b32 s56, s49, s54
	s_cselect_b32 s55, s37, s76
	s_cselect_b32 s54, s51, s75
	v_lshl_add_u64 v[218:219], s[52:53], 0, v[144:145]
	s_add_i32 m0, s61, 0xc000
	ds_read_b128 v[178:181], v207
	ds_read_b128 v[182:185], v207 offset:1024
	ds_read_b128 v[186:189], v207 offset:2048
	ds_read_b128 v[190:193], v207 offset:3072
	ds_read_b128 v[194:197], v207 offset:4096
	ds_read_b128 v[198:201], v207 offset:5120
	ds_read_b128 v[210:213], v207 offset:6144
	ds_read_b128 v[214:217], v207 offset:7168
	global_load_lds_dwordx4 v[218:219], off
	v_lshl_add_u64 v[218:219], s[52:53], 0, v[148:149]
	s_add_i32 m0, s61, 0xe000
	s_nop 0
	global_load_lds_dwordx4 v[218:219], off
	s_waitcnt vmcnt(8)
	s_waitcnt lgkmcnt(0)
	s_barrier
	s_setprio 1
	s_waitcnt lgkmcnt(0)
	v_mfma_f32_16x16x32_bf16 v[124:127], v[128:131], v[178:181], v[124:127]
	v_mfma_f32_16x16x32_bf16 v[120:123], v[154:157], v[178:181], v[120:123]
	v_mfma_f32_16x16x32_bf16 v[116:119], v[128:131], v[186:189], v[116:119]
	v_mfma_f32_16x16x32_bf16 v[112:115], v[154:157], v[186:189], v[112:115]
	v_mfma_f32_16x16x32_bf16 v[108:111], v[128:131], v[194:197], v[108:111]
	v_mfma_f32_16x16x32_bf16 v[104:107], v[154:157], v[194:197], v[104:107]
	v_mfma_f32_16x16x32_bf16 v[100:103], v[128:131], v[210:213], v[100:103]
	v_mfma_f32_16x16x32_bf16 v[96:99], v[154:157], v[210:213], v[96:99]
	v_mfma_f32_16x16x32_bf16 v[124:127], v[132:135], v[182:185], v[124:127]
	v_mfma_f32_16x16x32_bf16 v[120:123], v[158:161], v[182:185], v[120:123]
	v_mfma_f32_16x16x32_bf16 v[116:119], v[132:135], v[190:193], v[116:119]
	v_mfma_f32_16x16x32_bf16 v[112:115], v[158:161], v[190:193], v[112:115]
	v_mfma_f32_16x16x32_bf16 v[108:111], v[132:135], v[198:201], v[108:111]
	v_mfma_f32_16x16x32_bf16 v[104:107], v[158:161], v[198:201], v[104:107]
	v_mfma_f32_16x16x32_bf16 v[100:103], v[132:135], v[214:217], v[100:103]
	v_mfma_f32_16x16x32_bf16 v[96:99], v[158:161], v[214:217], v[96:99]
	s_setprio 0
	s_setprio 1
	v_mfma_f32_16x16x32_bf16 v[60:63], v[162:165], v[178:181], v[60:63]
	v_mfma_f32_16x16x32_bf16 v[56:59], v[170:173], v[178:181], v[56:59]
	v_mfma_f32_16x16x32_bf16 v[52:55], v[162:165], v[186:189], v[52:55]
	v_mfma_f32_16x16x32_bf16 v[48:51], v[170:173], v[186:189], v[48:51]
	v_mfma_f32_16x16x32_bf16 v[44:47], v[162:165], v[194:197], v[44:47]
	v_mfma_f32_16x16x32_bf16 v[40:43], v[170:173], v[194:197], v[40:43]
	v_mfma_f32_16x16x32_bf16 v[36:39], v[162:165], v[210:213], v[36:39]
	v_mfma_f32_16x16x32_bf16 v[32:35], v[170:173], v[210:213], v[32:35]
	v_mfma_f32_16x16x32_bf16 v[60:63], v[166:169], v[182:185], v[60:63]
	v_mfma_f32_16x16x32_bf16 v[56:59], v[174:177], v[182:185], v[56:59]
	v_mfma_f32_16x16x32_bf16 v[52:55], v[166:169], v[190:193], v[52:55]
	v_mfma_f32_16x16x32_bf16 v[48:51], v[174:177], v[190:193], v[48:51]
	v_mfma_f32_16x16x32_bf16 v[44:47], v[166:169], v[198:201], v[44:47]
	v_mfma_f32_16x16x32_bf16 v[40:43], v[174:177], v[198:201], v[40:43]
	s_setprio 2
	s_barrier
	v_mfma_f32_16x16x32_bf16 v[36:39], v[166:169], v[214:217], v[36:39]
	v_mfma_f32_16x16x32_bf16 v[32:35], v[174:177], v[214:217], v[32:35]
	s_setprio 0
	s_add_i32 s78, s33, s60
	v_lshl_add_u64 v[218:219], s[54:55], 0, v[138:139]
	s_mov_b32 m0, s78
	ds_read_b128 v[178:181], v207 offset:16384
	ds_read_b128 v[182:185], v207 offset:17408
	ds_read_b128 v[186:189], v207 offset:18432
	ds_read_b128 v[190:193], v207 offset:19456
	ds_read_b128 v[194:197], v207 offset:20480
	ds_read_b128 v[198:201], v207 offset:21504
	ds_read_b128 v[210:213], v207 offset:22528
	ds_read_b128 v[214:217], v207 offset:23552
	global_load_lds_dwordx4 v[218:219], off
	s_add_i32 m0, s78, 0x2000
	s_add_u32 s78, s54, 0x80000
	v_lshl_add_u64 v[220:221], s[54:55], 0, v[142:143]
	s_addc_u32 s79, s55, 0
	s_add_i32 s80, s74, s60
	global_load_lds_dwordx4 v[220:221], off
	v_lshl_add_u64 v[222:223], s[78:79], 0, v[138:139]
	s_mov_b32 m0, s80
	v_lshl_add_u64 v[224:225], s[56:57], 0, v[140:141]
	global_load_lds_dwordx4 v[222:223], off
	v_lshl_add_u64 v[222:223], s[78:79], 0, v[142:143]
	s_add_i32 m0, s80, 0x2000
	s_nop 0
	global_load_lds_dwordx4 v[222:223], off
	v_lshl_add_u64 v[222:223], s[56:57], 0, v[136:137]
	s_mov_b32 m0, s61
	s_nop 0
	global_load_lds_dwordx4 v[222:223], off
	s_mov_b32 m0, s62
	s_nop 0
	global_load_lds_dwordx4 v[224:225], off
	s_waitcnt vmcnt(8)
	s_waitcnt lgkmcnt(0)
	s_barrier
; #define PG8_STAGE(bufoff, gbase, voff) do { _Pragma("unroll") for (int _i = 0; _i < 2; ++_i) \
;         __builtin_amdgcn_global_load_lds((const unsigned*)((const char*)(gbase) + (voff)[_i]), (PG8_LAS unsigned*)(lds + (bufoff) + ldsw + _i * 8192), 16, 0, 0); } while (0)
; #define PG8_LDA(dst, b, h) do { _Pragma("unroll") for (int m = 0; m < 4; ++m) _Pragma("unroll") for (int k = 0; k < 2; ++k) dst[m][k] = *(const PG8_LAS bf16x8*)(lds + PG8_SA(b, h) + aoff + m * 2048 + k * 1024); } while (0)
; #define PG8_LDB(dst, b, h) do { _Pragma("unroll") for (int n = 0; n < 2; ++n) _Pragma("unroll") for (int k = 0; k < 2; ++k) dst[n][k] = *(const PG8_LAS bf16x8*)(lds + PG8_SB(b, h) + boff + n * 2048 + k * 1024); } while (0)
; #define PG8_MMA(ai, bj, At, Bt) do { __builtin_amdgcn_s_setprio(1); _Pragma("unroll") for (int m = 0; m < 4; ++m) _Pragma("unroll") for (int n = 0; n < 2; ++n) _Pragma("unroll") for (int k = 0; k < 2; ++k) \
;         acc[ai][bj][m][n] = __builtin_amdgcn_mfma_f32_16x16x32_bf16(Bt[n][k], At[m][k], acc[ai][bj][m][n], 0, 0, 0); __builtin_amdgcn_s_setprio(0); } while (0)
; #define PG8_WAIT_V(n) asm volatile("s_waitcnt vmcnt(" #n ")" ::: "memory")
; #define PG8_WAIT_L(n) asm volatile("s_waitcnt lgkmcnt(" #n ")" ::: "memory")
; #define PG8_BAR __builtin_amdgcn_s_barrier()
; #define PG8_SCHED __builtin_amdgcn_sched_barrier(0)
; template <class Epi, class Sched, bool ALIGN_EPI = false, bool SP2 = false>
; __device__ __forceinline__ void gemm_phase(PG8_LAS unsigned char* lds, const Gemm g, const Sched& S, const Epi& E) {
;     ...
;             PG8_WAIT_V(8); PG8_WAIT_L(0); PG8_BAR; PG8_MMA(1, 0, At, B0); PG8_MMA(1, 1, At, B1); PG8_BAR; PG8_SCHED;
;             PG8_LDB(B0, 1, 0); PG8_LDB(B1, 1, 1); PG8_SCHED; PG8_LDA(At, 1, 0); PG8_STAGE(PG8_SA(0, 1), a2 + hstep, voffA);
;             PG8_WAIT_V(8); PG8_WAIT_L(0); PG8_BAR; PG8_MMA(0, 0, At, B0); PG8_MMA(0, 1, At, B1); PG8_BAR; PG8_SCHED;
;             PG8_LDA(At, 1, 1); PG8_STAGE(PG8_SB(1, 0), b3, voffB); PG8_STAGE(PG8_SB(1, 1), b3 + hstep, voffB); PG8_STAGE(PG8_SA(1, 0), a3, voffA);
;             PG8_WAIT_V(8); PG8_WAIT_L(0); PG8_BAR; PG8_MMA(1, 0, At, B0); PG8_MMA(1, 1, At, B1); PG8_BAR; PG8_SCHED;
	s_setprio 1
	s_waitcnt lgkmcnt(0)
	v_mfma_f32_16x16x32_bf16 v[92:95], v[128:131], v[178:181], v[92:95]
	v_mfma_f32_16x16x32_bf16 v[88:91], v[154:157], v[178:181], v[88:91]
	v_mfma_f32_16x16x32_bf16 v[84:87], v[128:131], v[186:189], v[84:87]
	v_mfma_f32_16x16x32_bf16 v[80:83], v[154:157], v[186:189], v[80:83]
	v_mfma_f32_16x16x32_bf16 v[76:79], v[128:131], v[194:197], v[76:79]
	v_mfma_f32_16x16x32_bf16 v[72:75], v[154:157], v[194:197], v[72:75]
	v_mfma_f32_16x16x32_bf16 v[68:71], v[128:131], v[210:213], v[68:71]
	v_mfma_f32_16x16x32_bf16 v[64:67], v[154:157], v[210:213], v[64:67]
	v_mfma_f32_16x16x32_bf16 v[92:95], v[132:135], v[182:185], v[92:95]
	v_mfma_f32_16x16x32_bf16 v[88:91], v[158:161], v[182:185], v[88:91]
	v_mfma_f32_16x16x32_bf16 v[84:87], v[132:135], v[190:193], v[84:87]
	v_mfma_f32_16x16x32_bf16 v[80:83], v[158:161], v[190:193], v[80:83]
	v_mfma_f32_16x16x32_bf16 v[76:79], v[132:135], v[198:201], v[76:79]
	v_mfma_f32_16x16x32_bf16 v[72:75], v[158:161], v[198:201], v[72:75]
	v_mfma_f32_16x16x32_bf16 v[68:71], v[132:135], v[214:217], v[68:71]
	v_mfma_f32_16x16x32_bf16 v[64:67], v[158:161], v[214:217], v[64:67]
	s_setprio 0
	s_setprio 1
	v_mfma_f32_16x16x32_bf16 v[28:31], v[162:165], v[178:181], v[28:31]
	v_mfma_f32_16x16x32_bf16 v[24:27], v[170:173], v[178:181], v[24:27]
	v_mfma_f32_16x16x32_bf16 v[20:23], v[162:165], v[186:189], v[20:23]
	v_mfma_f32_16x16x32_bf16 v[16:19], v[170:173], v[186:189], v[16:19]
	v_mfma_f32_16x16x32_bf16 v[12:15], v[162:165], v[194:197], v[12:15]
	v_mfma_f32_16x16x32_bf16 v[8:11], v[170:173], v[194:197], v[8:11]
	v_mfma_f32_16x16x32_bf16 v[4:7], v[162:165], v[210:213], v[4:7]
	v_mfma_f32_16x16x32_bf16 v[0:3], v[170:173], v[210:213], v[0:3]
	v_mfma_f32_16x16x32_bf16 v[28:31], v[166:169], v[182:185], v[28:31]
	v_mfma_f32_16x16x32_bf16 v[24:27], v[174:177], v[182:185], v[24:27]
	v_mfma_f32_16x16x32_bf16 v[20:23], v[166:169], v[190:193], v[20:23]
	v_mfma_f32_16x16x32_bf16 v[16:19], v[174:177], v[190:193], v[16:19]
	v_mfma_f32_16x16x32_bf16 v[12:15], v[166:169], v[198:201], v[12:15]
	v_mfma_f32_16x16x32_bf16 v[8:11], v[174:177], v[198:201], v[8:11]
	s_setprio 2
	s_barrier
	v_mfma_f32_16x16x32_bf16 v[4:7], v[166:169], v[214:217], v[4:7]
	v_mfma_f32_16x16x32_bf16 v[0:3], v[174:177], v[214:217], v[0:3]
	s_setprio 0
	s_add_i32 s78, 0, 0x18000
	s_add_i32 s79, 0, 0x1c000
	v_add_u32_e32 v158, s78, v203
	v_add_u32_e32 v174, s79, v203
	ds_read_b128 v[128:131], v158
	ds_read_b128 v[132:135], v158 offset:1024
	ds_read_b128 v[154:157], v158 offset:2048
	ds_read_b128 v[158:161], v158 offset:3072
	ds_read_b128 v[162:165], v174
	ds_read_b128 v[166:169], v174 offset:1024
	ds_read_b128 v[170:173], v174 offset:2048
	ds_read_b128 v[174:177], v174 offset:3072
	s_add_u32 s56, s56, 0x80000
	s_addc_u32 s57, s57, 0
	s_mov_b32 m0, s63
	v_lshl_add_u64 v[226:227], s[56:57], 0, v[136:137]
	ds_read_b128 v[178:181], v207 offset:32768
	ds_read_b128 v[182:185], v207 offset:33792
	ds_read_b128 v[186:189], v207 offset:34816
	ds_read_b128 v[190:193], v207 offset:35840
	ds_read_b128 v[194:197], v207 offset:36864
	ds_read_b128 v[198:201], v207 offset:37888
	ds_read_b128 v[210:213], v207 offset:38912
	ds_read_b128 v[214:217], v207 offset:39936
	global_load_lds_dwordx4 v[226:227], off
	v_lshl_add_u64 v[226:227], s[56:57], 0, v[140:141]
	s_mov_b32 m0, s64
	s_nop 0
	global_load_lds_dwordx4 v[226:227], off
	s_waitcnt vmcnt(8)
	s_waitcnt lgkmcnt(0)
	s_barrier
	s_setprio 1
	s_waitcnt lgkmcnt(0)
	v_mfma_f32_16x16x32_bf16 v[124:127], v[128:131], v[178:181], v[124:127]
	v_mfma_f32_16x16x32_bf16 v[120:123], v[154:157], v[178:181], v[120:123]
	v_mfma_f32_16x16x32_bf16 v[116:119], v[128:131], v[186:189], v[116:119]
	v_mfma_f32_16x16x32_bf16 v[112:115], v[154:157], v[186:189], v[112:115]
	v_mfma_f32_16x16x32_bf16 v[108:111], v[128:131], v[194:197], v[108:111]
	v_mfma_f32_16x16x32_bf16 v[104:107], v[154:157], v[194:197], v[104:107]
	v_mfma_f32_16x16x32_bf16 v[100:103], v[128:131], v[210:213], v[100:103]
	v_mfma_f32_16x16x32_bf16 v[96:99], v[154:157], v[210:213], v[96:99]
	v_mfma_f32_16x16x32_bf16 v[124:127], v[132:135], v[182:185], v[124:127]
	v_mfma_f32_16x16x32_bf16 v[120:123], v[158:161], v[182:185], v[120:123]
	v_mfma_f32_16x16x32_bf16 v[116:119], v[132:135], v[190:193], v[116:119]
	v_mfma_f32_16x16x32_bf16 v[112:115], v[158:161], v[190:193], v[112:115]
	v_mfma_f32_16x16x32_bf16 v[108:111], v[132:135], v[198:201], v[108:111]
	v_mfma_f32_16x16x32_bf16 v[104:107], v[158:161], v[198:201], v[104:107]
	v_mfma_f32_16x16x32_bf16 v[100:103], v[132:135], v[214:217], v[100:103]
	v_mfma_f32_16x16x32_bf16 v[96:99], v[158:161], v[214:217], v[96:99]
	s_setprio 0
	s_setprio 1
	v_mfma_f32_16x16x32_bf16 v[60:63], v[162:165], v[178:181], v[60:63]
	v_mfma_f32_16x16x32_bf16 v[56:59], v[170:173], v[178:181], v[56:59]
	v_mfma_f32_16x16x32_bf16 v[52:55], v[162:165], v[186:189], v[52:55]
	v_mfma_f32_16x16x32_bf16 v[48:51], v[170:173], v[186:189], v[48:51]
	v_mfma_f32_16x16x32_bf16 v[44:47], v[162:165], v[194:197], v[44:47]
	v_mfma_f32_16x16x32_bf16 v[40:43], v[170:173], v[194:197], v[40:43]
	v_mfma_f32_16x16x32_bf16 v[36:39], v[162:165], v[210:213], v[36:39]
	v_mfma_f32_16x16x32_bf16 v[32:35], v[170:173], v[210:213], v[32:35]
	v_mfma_f32_16x16x32_bf16 v[60:63], v[166:169], v[182:185], v[60:63]
	v_mfma_f32_16x16x32_bf16 v[56:59], v[174:177], v[182:185], v[56:59]
	v_mfma_f32_16x16x32_bf16 v[52:55], v[166:169], v[190:193], v[52:55]
	v_mfma_f32_16x16x32_bf16 v[48:51], v[174:177], v[190:193], v[48:51]
	v_mfma_f32_16x16x32_bf16 v[44:47], v[166:169], v[198:201], v[44:47]
	v_mfma_f32_16x16x32_bf16 v[40:43], v[174:177], v[198:201], v[40:43]
	s_setprio 2
	s_barrier
; #define PG8_STAGE(bufoff, gbase, voff) do { _Pragma("unroll") for (int _i = 0; _i < 2; ++_i) \
;         __builtin_amdgcn_global_load_lds((const unsigned*)((const char*)(gbase) + (voff)[_i]), (PG8_LAS unsigned*)(lds + (bufoff) + ldsw + _i * 8192), 16, 0, 0); } while (0)
; #define PG8_LDA(dst, b, h) do { _Pragma("unroll") for (int m = 0; m < 4; ++m) _Pragma("unroll") for (int k = 0; k < 2; ++k) dst[m][k] = *(const PG8_LAS bf16x8*)(lds + PG8_SA(b, h) + aoff + m * 2048 + k * 1024); } while (0)
; #define PG8_MMA(ai, bj, At, Bt) do { __builtin_amdgcn_s_setprio(1); _Pragma("unroll") for (int m = 0; m < 4; ++m) _Pragma("unroll") for (int n = 0; n < 2; ++n) _Pragma("unroll") for (int k = 0; k < 2; ++k) \
;         acc[ai][bj][m][n] = __builtin_amdgcn_mfma_f32_16x16x32_bf16(Bt[n][k], At[m][k], acc[ai][bj][m][n], 0, 0, 0); __builtin_amdgcn_s_setprio(0); } while (0)
; #define PG8_WAIT_V(n) asm volatile("s_waitcnt vmcnt(" #n ")" ::: "memory")
; #define PG8_WAIT_L(n) asm volatile("s_waitcnt lgkmcnt(" #n ")" ::: "memory")
; #define PG8_BAR __builtin_amdgcn_s_barrier()
; #define PG8_SCHED __builtin_amdgcn_sched_barrier(0)
; template <class Epi, class Sched, bool ALIGN_EPI = false, bool SP2 = false>
; __device__ __forceinline__ void gemm_phase(PG8_LAS unsigned char* lds, const Gemm g, const Sched& S, const Epi& E) {
;     ...
;         for (int t = 0; t < nt; t += 2) {
;             const bool last = (t == nt - 2);
;             const char* a1 = cA + (size_t)(t + 1) * kstep;
;             const char* a2 = last ? nA : cA + (size_t)(t + 2) * kstep; const char* b2 = last ? nB : cB + (size_t)(t + 2) * kstep;
;             const char* a3 = a2 + kstep; const char* b3 = b2 + kstep;
;     ...
;             PG8_WAIT_V(8); PG8_WAIT_L(0); PG8_BAR; PG8_MMA(0, 0, At, B0); PG8_MMA(0, 1, At, B1); PG8_BAR; PG8_SCHED;
;             PG8_LDA(At, 1, 1); PG8_STAGE(PG8_SB(1, 0), b3, voffB); PG8_STAGE(PG8_SB(1, 1), b3 + hstep, voffB); PG8_STAGE(PG8_SA(1, 0), a3, voffA);
;             PG8_WAIT_V(8); PG8_WAIT_L(0); PG8_BAR; PG8_MMA(1, 0, At, B0); PG8_MMA(1, 1, At, B1); PG8_BAR; PG8_SCHED;
	v_mfma_f32_16x16x32_bf16 v[36:39], v[166:169], v[214:217], v[36:39]
	v_mfma_f32_16x16x32_bf16 v[32:35], v[174:177], v[214:217], v[32:35]
	s_setprio 0
	s_add_i32 s56, s78, s60
	v_lshl_add_u64 v[218:219], v[218:219], 0, s[12:13]
	s_mov_b32 m0, s56
	ds_read_b128 v[178:181], v207 offset:49152
	ds_read_b128 v[182:185], v207 offset:50176
	ds_read_b128 v[186:189], v207 offset:51200
	ds_read_b128 v[190:193], v207 offset:52224
	ds_read_b128 v[194:197], v207 offset:53248
	ds_read_b128 v[198:201], v207 offset:54272
	ds_read_b128 v[210:213], v207 offset:55296
	ds_read_b128 v[214:217], v207 offset:56320
	global_load_lds_dwordx4 v[218:219], off
	s_add_i32 m0, s56, 0x2000
	s_add_u32 s54, s54, 0x80080
	v_lshl_add_u64 v[218:219], v[220:221], 0, s[12:13]
	s_addc_u32 s55, s55, 0
	s_add_i32 s56, s79, s60
	global_load_lds_dwordx4 v[218:219], off
	v_lshl_add_u64 v[218:219], s[54:55], 0, v[138:139]
	s_mov_b32 m0, s56
	s_nop 0
	global_load_lds_dwordx4 v[218:219], off
	v_lshl_add_u64 v[218:219], s[54:55], 0, v[142:143]
	s_add_i32 m0, s56, 0x2000
	s_nop 0
	global_load_lds_dwordx4 v[218:219], off
	v_lshl_add_u64 v[218:219], v[222:223], 0, s[12:13]
	s_mov_b32 m0, s70
	s_nop 0
	global_load_lds_dwordx4 v[218:219], off
	v_lshl_add_u64 v[218:219], v[224:225], 0, s[12:13]
	s_mov_b32 m0, s71
	s_nop 0
	global_load_lds_dwordx4 v[218:219], off
	s_waitcnt vmcnt(8)
	s_waitcnt lgkmcnt(0)
	s_barrier
	s_setprio 1
	s_waitcnt lgkmcnt(0)
	v_mfma_f32_16x16x32_bf16 v[92:95], v[128:131], v[178:181], v[92:95]
	v_mfma_f32_16x16x32_bf16 v[88:91], v[154:157], v[178:181], v[88:91]
	v_mfma_f32_16x16x32_bf16 v[84:87], v[128:131], v[186:189], v[84:87]
	v_mfma_f32_16x16x32_bf16 v[80:83], v[154:157], v[186:189], v[80:83]
	v_mfma_f32_16x16x32_bf16 v[76:79], v[128:131], v[194:197], v[76:79]
	v_mfma_f32_16x16x32_bf16 v[72:75], v[154:157], v[194:197], v[72:75]
	v_mfma_f32_16x16x32_bf16 v[68:71], v[128:131], v[210:213], v[68:71]
	v_mfma_f32_16x16x32_bf16 v[64:67], v[154:157], v[210:213], v[64:67]
	v_mfma_f32_16x16x32_bf16 v[92:95], v[132:135], v[182:185], v[92:95]
	v_mfma_f32_16x16x32_bf16 v[88:91], v[158:161], v[182:185], v[88:91]
	v_mfma_f32_16x16x32_bf16 v[84:87], v[132:135], v[190:193], v[84:87]
	v_mfma_f32_16x16x32_bf16 v[80:83], v[158:161], v[190:193], v[80:83]
	v_mfma_f32_16x16x32_bf16 v[76:79], v[132:135], v[198:201], v[76:79]
	v_mfma_f32_16x16x32_bf16 v[72:75], v[158:161], v[198:201], v[72:75]
	v_mfma_f32_16x16x32_bf16 v[68:71], v[132:135], v[214:217], v[68:71]
	v_mfma_f32_16x16x32_bf16 v[64:67], v[158:161], v[214:217], v[64:67]
	s_setprio 0
	s_setprio 1
	v_mfma_f32_16x16x32_bf16 v[28:31], v[162:165], v[178:181], v[28:31]
	v_mfma_f32_16x16x32_bf16 v[24:27], v[170:173], v[178:181], v[24:27]
	v_mfma_f32_16x16x32_bf16 v[20:23], v[162:165], v[186:189], v[20:23]
	v_mfma_f32_16x16x32_bf16 v[16:19], v[170:173], v[186:189], v[16:19]
	v_mfma_f32_16x16x32_bf16 v[12:15], v[162:165], v[194:197], v[12:15]
	v_mfma_f32_16x16x32_bf16 v[8:11], v[170:173], v[194:197], v[8:11]
	v_mfma_f32_16x16x32_bf16 v[4:7], v[162:165], v[210:213], v[4:7]
	v_mfma_f32_16x16x32_bf16 v[0:3], v[170:173], v[210:213], v[0:3]
	v_mfma_f32_16x16x32_bf16 v[28:31], v[166:169], v[182:185], v[28:31]
	v_mfma_f32_16x16x32_bf16 v[24:27], v[174:177], v[182:185], v[24:27]
	v_mfma_f32_16x16x32_bf16 v[20:23], v[166:169], v[190:193], v[20:23]
	v_mfma_f32_16x16x32_bf16 v[16:19], v[174:177], v[190:193], v[16:19]
	v_mfma_f32_16x16x32_bf16 v[12:15], v[166:169], v[198:201], v[12:15]
	v_mfma_f32_16x16x32_bf16 v[8:11], v[174:177], v[198:201], v[8:11]
	s_setprio 2
	s_barrier
	v_mfma_f32_16x16x32_bf16 v[4:7], v[166:169], v[214:217], v[4:7]
	v_mfma_f32_16x16x32_bf16 v[0:3], v[174:177], v[214:217], v[0:3]
	s_setprio 0
	s_add_i32 s77, s77, 2
	s_add_u32 s52, s52, 0x100
	s_addc_u32 s53, s53, 0
	s_add_u32 s75, s75, 0x100
	s_addc_u32 s76, s76, 0
	s_cmp_gt_u32 s77, 29
	s_cbranch_scc0 .LBB0_1051
	s_and_b64 vcc, exec, s[14:15]
	s_cbranch_vccz .LBB0_1054
	s_barrier

; #define PG8_STAGE(bufoff, gbase, voff) do { _Pragma("unroll") for (int _i = 0; _i < 2; ++_i) \
;         __builtin_amdgcn_global_load_lds((const unsigned*)((const char*)(gbase) + (voff)[_i]), (PG8_LAS unsigned*)(lds + (bufoff) + ldsw + _i * 8192), 16, 0, 0); } while (0)
; #define PG8_LDA(dst, b, h) do { _Pragma("unroll") for (int m = 0; m < 4; ++m) _Pragma("unroll") for (int k = 0; k < 2; ++k) dst[m][k] = *(const PG8_LAS bf16x8*)(lds + PG8_SA(b, h) + aoff + m * 2048 + k * 1024); } while (0)
; #define PG8_LDB(dst, b, h) do { _Pragma("unroll") for (int n = 0; n < 2; ++n) _Pragma("unroll") for (int k = 0; k < 2; ++k) dst[n][k] = *(const PG8_LAS bf16x8*)(lds + PG8_SB(b, h) + boff + n * 2048 + k * 1024); } while (0)
; #define PG8_MMA(ai, bj, At, Bt) do { __builtin_amdgcn_s_setprio(1); _Pragma("unroll") for (int m = 0; m < 4; ++m) _Pragma("unroll") for (int n = 0; n < 2; ++n) _Pragma("unroll") for (int k = 0; k < 2; ++k) \
;         acc[ai][bj][m][n] = __builtin_amdgcn_mfma_f32_16x16x32_bf16(Bt[n][k], At[m][k], acc[ai][bj][m][n], 0, 0, 0); __builtin_amdgcn_s_setprio(0); } while (0)
; #define PG8_WAIT_V(n) asm volatile("s_waitcnt vmcnt(" #n ")" ::: "memory")
; #define PG8_WAIT_L(n) asm volatile("s_waitcnt lgkmcnt(" #n ")" ::: "memory")
; #define PG8_BAR __builtin_amdgcn_s_barrier()
; template <class Epi, class Sched, bool ALIGN_EPI = false, bool SP2 = false>
; __device__ __forceinline__ void gemm_phase(PG8_LAS unsigned char* lds, const Gemm g, const Sched& S, const Epi& E) {
;     ...
;             const bool last = (t == nt - 2);
;             const char* a1 = cA + (size_t)(t + 1) * kstep;
;             const char* a2 = last ? nA : cA + (size_t)(t + 2) * kstep; const char* b2 = last ? nB : cB + (size_t)(t + 2) * kstep;
;             const char* a3 = a2 + kstep; const char* b3 = b2 + kstep;
;             if constexpr (SP2) {
;             PG8_LDB(B0, 0, 0); PG8_LDB(B1, 0, 1); PG8_SCHED; PG8_LDA(At, 0, 0); PG8_STAGE(PG8_SA(1, 1), a1 + hstep, voffA);
;             PG8_WAIT_V(8); PG8_WAIT_L(0); PG8_BAR; PG8_MMA(0, 0, At, B0); PG8_MMA(0, 1, At, B1); PG8_BAR; PG8_SCHED;
;             PG8_LDA(At, 0, 1); PG8_STAGE(PG8_SB(0, 0), b2, voffB); PG8_STAGE(PG8_SB(0, 1), b2 + hstep, voffB); PG8_STAGE(PG8_SA(0, 0), a2, voffA);
;             PG8_WAIT_V(8); PG8_WAIT_L(0); PG8_BAR; PG8_MMA(1, 0, At, B0); PG8_MMA(1, 1, At, B1); PG8_BAR; PG8_SCHED;
.LBB0_1142:
	ds_read_b128 v[80:83], v171
	ds_read_b128 v[84:87], v171 offset:1024
	ds_read_b128 v[88:91], v171 offset:2048
	ds_read_b128 v[92:95], v171 offset:3072
	ds_read_b128 v[164:167], v172
	ds_read_b128 v[176:179], v172 offset:1024
	ds_read_b128 v[180:183], v172 offset:2048
	ds_read_b128 v[184:187], v172 offset:3072
	s_add_u32 s44, s42, 0xfff80080
	s_addc_u32 s45, s43, -1
	s_cmp_eq_u32 s64, 28
	s_cselect_b32 s47, s15, s45
	s_cselect_b32 s46, s60, s44
	s_cselect_b32 s45, s13, s63
	s_cselect_b32 s44, s61, s62
	v_lshl_add_u64 v[220:221], s[42:43], 0, v[156:157]
	s_add_i32 m0, s41, 0xc000
	ds_read_b128 v[188:191], v173
	ds_read_b128 v[192:195], v173 offset:1024
	ds_read_b128 v[196:199], v173 offset:2048
	ds_read_b128 v[200:203], v173 offset:3072
	ds_read_b128 v[204:207], v173 offset:4096
	ds_read_b128 v[208:211], v173 offset:5120
	ds_read_b128 v[212:215], v173 offset:6144
	ds_read_b128 v[216:219], v173 offset:7168
	global_load_lds_dwordx4 v[220:221], off
	v_lshl_add_u64 v[220:221], s[42:43], 0, v[158:159]
	s_add_i32 m0, s41, 0xe000
	s_nop 0
	global_load_lds_dwordx4 v[220:221], off
	s_waitcnt vmcnt(8)
	s_waitcnt lgkmcnt(0)
	s_barrier
	s_setprio 1
	s_waitcnt lgkmcnt(0)
	v_mfma_f32_16x16x32_bf16 v[140:143], v[80:83], v[188:191], v[140:143]
	v_mfma_f32_16x16x32_bf16 v[136:139], v[88:91], v[188:191], v[136:139]
	v_mfma_f32_16x16x32_bf16 v[124:127], v[80:83], v[196:199], v[124:127]
	v_mfma_f32_16x16x32_bf16 v[120:123], v[88:91], v[196:199], v[120:123]
	v_mfma_f32_16x16x32_bf16 v[108:111], v[80:83], v[204:207], v[108:111]
	v_mfma_f32_16x16x32_bf16 v[104:107], v[88:91], v[204:207], v[104:107]
	v_mfma_f32_16x16x32_bf16 v[76:79], v[80:83], v[212:215], v[76:79]
	v_mfma_f32_16x16x32_bf16 v[72:75], v[88:91], v[212:215], v[72:75]
	v_mfma_f32_16x16x32_bf16 v[140:143], v[84:87], v[192:195], v[140:143]
	v_mfma_f32_16x16x32_bf16 v[136:139], v[92:95], v[192:195], v[136:139]
	v_mfma_f32_16x16x32_bf16 v[124:127], v[84:87], v[200:203], v[124:127]
	v_mfma_f32_16x16x32_bf16 v[120:123], v[92:95], v[200:203], v[120:123]
	v_mfma_f32_16x16x32_bf16 v[108:111], v[84:87], v[208:211], v[108:111]
	v_mfma_f32_16x16x32_bf16 v[104:107], v[92:95], v[208:211], v[104:107]
	v_mfma_f32_16x16x32_bf16 v[76:79], v[84:87], v[216:219], v[76:79]
	v_mfma_f32_16x16x32_bf16 v[72:75], v[92:95], v[216:219], v[72:75]
	s_setprio 0
	s_setprio 1
	v_mfma_f32_16x16x32_bf16 v[132:135], v[164:167], v[188:191], v[132:135]
	v_mfma_f32_16x16x32_bf16 v[128:131], v[180:183], v[188:191], v[128:131]
	v_mfma_f32_16x16x32_bf16 v[116:119], v[164:167], v[196:199], v[116:119]
	v_mfma_f32_16x16x32_bf16 v[112:115], v[180:183], v[196:199], v[112:115]
	v_mfma_f32_16x16x32_bf16 v[100:103], v[164:167], v[204:207], v[100:103]
	v_mfma_f32_16x16x32_bf16 v[96:99], v[180:183], v[204:207], v[96:99]
	v_mfma_f32_16x16x32_bf16 v[68:71], v[164:167], v[212:215], v[68:71]
	v_mfma_f32_16x16x32_bf16 v[64:67], v[180:183], v[212:215], v[64:67]
	v_mfma_f32_16x16x32_bf16 v[132:135], v[176:179], v[192:195], v[132:135]
	v_mfma_f32_16x16x32_bf16 v[128:131], v[184:187], v[192:195], v[128:131]
	v_mfma_f32_16x16x32_bf16 v[116:119], v[176:179], v[200:203], v[116:119]
	v_mfma_f32_16x16x32_bf16 v[112:115], v[184:187], v[200:203], v[112:115]
	v_mfma_f32_16x16x32_bf16 v[100:103], v[176:179], v[208:211], v[100:103]
	v_mfma_f32_16x16x32_bf16 v[96:99], v[184:187], v[208:211], v[96:99]
	s_setprio 2
	s_barrier
	v_mfma_f32_16x16x32_bf16 v[68:71], v[176:179], v[216:219], v[68:71]
	v_mfma_f32_16x16x32_bf16 v[64:67], v[184:187], v[216:219], v[64:67]
	s_setprio 0
	s_add_i32 s65, s56, s33
	v_lshl_add_u64 v[220:221], s[44:45], 0, v[148:149]
	s_mov_b32 m0, s65
	ds_read_b128 v[188:191], v173 offset:16384
	ds_read_b128 v[192:195], v173 offset:17408
	ds_read_b128 v[196:199], v173 offset:18432
	ds_read_b128 v[200:203], v173 offset:19456
	ds_read_b128 v[204:207], v173 offset:20480
	ds_read_b128 v[208:211], v173 offset:21504
	ds_read_b128 v[212:215], v173 offset:22528
	ds_read_b128 v[216:219], v173 offset:23552
	global_load_lds_dwordx4 v[220:221], off
	s_add_i32 m0, s65, 0x2000
	s_add_u32 s66, s44, 0x80000
	v_lshl_add_u64 v[222:223], s[44:45], 0, v[152:153]
	s_addc_u32 s67, s45, 0
	s_add_i32 s65, s57, s33
	global_load_lds_dwordx4 v[222:223], off
	v_lshl_add_u64 v[224:225], s[66:67], 0, v[148:149]
	s_mov_b32 m0, s65
	v_lshl_add_u64 v[226:227], s[46:47], 0, v[150:151]
	global_load_lds_dwordx4 v[224:225], off
	v_lshl_add_u64 v[224:225], s[66:67], 0, v[152:153]
	s_add_i32 m0, s65, 0x2000
	s_nop 0
	global_load_lds_dwordx4 v[224:225], off
	v_lshl_add_u64 v[224:225], s[46:47], 0, v[144:145]
	s_mov_b32 m0, s41
	s_nop 0
	global_load_lds_dwordx4 v[224:225], off
	s_mov_b32 m0, s48
	s_nop 0
	global_load_lds_dwordx4 v[226:227], off
	s_waitcnt vmcnt(8)
	s_waitcnt lgkmcnt(0)
	s_barrier
; #define PG8_STAGE(bufoff, gbase, voff) do { _Pragma("unroll") for (int _i = 0; _i < 2; ++_i) \
;         __builtin_amdgcn_global_load_lds((const unsigned*)((const char*)(gbase) + (voff)[_i]), (PG8_LAS unsigned*)(lds + (bufoff) + ldsw + _i * 8192), 16, 0, 0); } while (0)
; #define PG8_LDA(dst, b, h) do { _Pragma("unroll") for (int m = 0; m < 4; ++m) _Pragma("unroll") for (int k = 0; k < 2; ++k) dst[m][k] = *(const PG8_LAS bf16x8*)(lds + PG8_SA(b, h) + aoff + m * 2048 + k * 1024); } while (0)
; #define PG8_LDB(dst, b, h) do { _Pragma("unroll") for (int n = 0; n < 2; ++n) _Pragma("unroll") for (int k = 0; k < 2; ++k) dst[n][k] = *(const PG8_LAS bf16x8*)(lds + PG8_SB(b, h) + boff + n * 2048 + k * 1024); } while (0)
; #define PG8_MMA(ai, bj, At, Bt) do { __builtin_amdgcn_s_setprio(1); _Pragma("unroll") for (int m = 0; m < 4; ++m) _Pragma("unroll") for (int n = 0; n < 2; ++n) _Pragma("unroll") for (int k = 0; k < 2; ++k) \
;         acc[ai][bj][m][n] = __builtin_amdgcn_mfma_f32_16x16x32_bf16(Bt[n][k], At[m][k], acc[ai][bj][m][n], 0, 0, 0); __builtin_amdgcn_s_setprio(0); } while (0)
; #define PG8_WAIT_V(n) asm volatile("s_waitcnt vmcnt(" #n ")" ::: "memory")
; #define PG8_WAIT_L(n) asm volatile("s_waitcnt lgkmcnt(" #n ")" ::: "memory")
; #define PG8_BAR __builtin_amdgcn_s_barrier()
; #define PG8_SCHED __builtin_amdgcn_sched_barrier(0)
; template <class Epi, class Sched, bool ALIGN_EPI = false, bool SP2 = false>
; __device__ __forceinline__ void gemm_phase(PG8_LAS unsigned char* lds, const Gemm g, const Sched& S, const Epi& E) {
;     ...
;             PG8_WAIT_V(8); PG8_WAIT_L(0); PG8_BAR; PG8_MMA(1, 0, At, B0); PG8_MMA(1, 1, At, B1); PG8_BAR; PG8_SCHED;
;             PG8_LDB(B0, 1, 0); PG8_LDB(B1, 1, 1); PG8_SCHED; PG8_LDA(At, 1, 0); PG8_STAGE(PG8_SA(0, 1), a2 + hstep, voffA);
;             PG8_WAIT_V(8); PG8_WAIT_L(0); PG8_BAR; PG8_MMA(0, 0, At, B0); PG8_MMA(0, 1, At, B1); PG8_BAR; PG8_SCHED;
;             PG8_LDA(At, 1, 1); PG8_STAGE(PG8_SB(1, 0), b3, voffB); PG8_STAGE(PG8_SB(1, 1), b3 + hstep, voffB); PG8_STAGE(PG8_SA(1, 0), a3, voffA);
;             PG8_WAIT_V(8); PG8_WAIT_L(0); PG8_BAR; PG8_MMA(1, 0, At, B0); PG8_MMA(1, 1, At, B1); PG8_BAR; PG8_SCHED;
	s_setprio 1
	s_waitcnt lgkmcnt(0)
	v_mfma_f32_16x16x32_bf16 v[60:63], v[80:83], v[188:191], v[60:63]
	v_mfma_f32_16x16x32_bf16 v[56:59], v[88:91], v[188:191], v[56:59]
	v_mfma_f32_16x16x32_bf16 v[44:47], v[80:83], v[196:199], v[44:47]
	v_mfma_f32_16x16x32_bf16 v[40:43], v[88:91], v[196:199], v[40:43]
	v_mfma_f32_16x16x32_bf16 v[28:31], v[80:83], v[204:207], v[28:31]
	v_mfma_f32_16x16x32_bf16 v[24:27], v[88:91], v[204:207], v[24:27]
	v_mfma_f32_16x16x32_bf16 v[12:15], v[80:83], v[212:215], v[12:15]
	v_mfma_f32_16x16x32_bf16 v[8:11], v[88:91], v[212:215], v[8:11]
	v_mfma_f32_16x16x32_bf16 v[60:63], v[84:87], v[192:195], v[60:63]
	v_mfma_f32_16x16x32_bf16 v[56:59], v[92:95], v[192:195], v[56:59]
	v_mfma_f32_16x16x32_bf16 v[44:47], v[84:87], v[200:203], v[44:47]
	v_mfma_f32_16x16x32_bf16 v[40:43], v[92:95], v[200:203], v[40:43]
	v_mfma_f32_16x16x32_bf16 v[28:31], v[84:87], v[208:211], v[28:31]
	v_mfma_f32_16x16x32_bf16 v[24:27], v[92:95], v[208:211], v[24:27]
	v_mfma_f32_16x16x32_bf16 v[12:15], v[84:87], v[216:219], v[12:15]
	v_mfma_f32_16x16x32_bf16 v[8:11], v[92:95], v[216:219], v[8:11]
	s_setprio 0
	s_setprio 1
	v_mfma_f32_16x16x32_bf16 v[52:55], v[164:167], v[188:191], v[52:55]
	v_mfma_f32_16x16x32_bf16 v[48:51], v[180:183], v[188:191], v[48:51]
	v_mfma_f32_16x16x32_bf16 v[36:39], v[164:167], v[196:199], v[36:39]
	v_mfma_f32_16x16x32_bf16 v[32:35], v[180:183], v[196:199], v[32:35]
	v_mfma_f32_16x16x32_bf16 v[20:23], v[164:167], v[204:207], v[20:23]
	v_mfma_f32_16x16x32_bf16 v[16:19], v[180:183], v[204:207], v[16:19]
	v_mfma_f32_16x16x32_bf16 v[4:7], v[164:167], v[212:215], v[4:7]
	v_mfma_f32_16x16x32_bf16 v[0:3], v[180:183], v[212:215], v[0:3]
	v_mfma_f32_16x16x32_bf16 v[52:55], v[176:179], v[192:195], v[52:55]
	v_mfma_f32_16x16x32_bf16 v[48:51], v[184:187], v[192:195], v[48:51]
	v_mfma_f32_16x16x32_bf16 v[36:39], v[176:179], v[200:203], v[36:39]
	v_mfma_f32_16x16x32_bf16 v[32:35], v[184:187], v[200:203], v[32:35]
	v_mfma_f32_16x16x32_bf16 v[20:23], v[176:179], v[208:211], v[20:23]
	v_mfma_f32_16x16x32_bf16 v[16:19], v[184:187], v[208:211], v[16:19]
	s_setprio 2
	s_barrier
	v_mfma_f32_16x16x32_bf16 v[4:7], v[176:179], v[216:219], v[4:7]
	v_mfma_f32_16x16x32_bf16 v[0:3], v[184:187], v[216:219], v[0:3]
	s_setprio 0
	s_add_i32 s65, 0, 0x18000
	s_add_i32 s66, 0, 0x1c000
	v_add_u32_e32 v92, s65, v169
	v_add_u32_e32 v184, s66, v169
	ds_read_b128 v[80:83], v92
	ds_read_b128 v[84:87], v92 offset:1024
	ds_read_b128 v[88:91], v92 offset:2048
	ds_read_b128 v[92:95], v92 offset:3072
	ds_read_b128 v[164:167], v184
	ds_read_b128 v[176:179], v184 offset:1024
	ds_read_b128 v[180:183], v184 offset:2048
	ds_read_b128 v[184:187], v184 offset:3072
	s_add_u32 s46, s46, 0x80000
	s_addc_u32 s47, s47, 0
	s_mov_b32 m0, s49
	v_lshl_add_u64 v[228:229], s[46:47], 0, v[144:145]
	ds_read_b128 v[188:191], v173 offset:32768
	ds_read_b128 v[192:195], v173 offset:33792
	ds_read_b128 v[196:199], v173 offset:34816
	ds_read_b128 v[200:203], v173 offset:35840
	ds_read_b128 v[204:207], v173 offset:36864
	ds_read_b128 v[208:211], v173 offset:37888
	ds_read_b128 v[212:215], v173 offset:38912
	ds_read_b128 v[216:219], v173 offset:39936
	global_load_lds_dwordx4 v[228:229], off
	v_lshl_add_u64 v[228:229], s[46:47], 0, v[150:151]
	s_mov_b32 m0, s50
	s_nop 0
	global_load_lds_dwordx4 v[228:229], off
	s_waitcnt vmcnt(8)
	s_waitcnt lgkmcnt(0)
	s_barrier
	s_setprio 1
	s_waitcnt lgkmcnt(0)
	v_mfma_f32_16x16x32_bf16 v[140:143], v[80:83], v[188:191], v[140:143]
	v_mfma_f32_16x16x32_bf16 v[136:139], v[88:91], v[188:191], v[136:139]
	v_mfma_f32_16x16x32_bf16 v[124:127], v[80:83], v[196:199], v[124:127]
	v_mfma_f32_16x16x32_bf16 v[120:123], v[88:91], v[196:199], v[120:123]
	v_mfma_f32_16x16x32_bf16 v[108:111], v[80:83], v[204:207], v[108:111]
	v_mfma_f32_16x16x32_bf16 v[104:107], v[88:91], v[204:207], v[104:107]
	v_mfma_f32_16x16x32_bf16 v[76:79], v[80:83], v[212:215], v[76:79]
	v_mfma_f32_16x16x32_bf16 v[72:75], v[88:91], v[212:215], v[72:75]
	v_mfma_f32_16x16x32_bf16 v[140:143], v[84:87], v[192:195], v[140:143]
	v_mfma_f32_16x16x32_bf16 v[136:139], v[92:95], v[192:195], v[136:139]
	v_mfma_f32_16x16x32_bf16 v[124:127], v[84:87], v[200:203], v[124:127]
	v_mfma_f32_16x16x32_bf16 v[120:123], v[92:95], v[200:203], v[120:123]
	v_mfma_f32_16x16x32_bf16 v[108:111], v[84:87], v[208:211], v[108:111]
	v_mfma_f32_16x16x32_bf16 v[104:107], v[92:95], v[208:211], v[104:107]
	v_mfma_f32_16x16x32_bf16 v[76:79], v[84:87], v[216:219], v[76:79]
	v_mfma_f32_16x16x32_bf16 v[72:75], v[92:95], v[216:219], v[72:75]
	s_setprio 0
	s_setprio 1
	v_mfma_f32_16x16x32_bf16 v[132:135], v[164:167], v[188:191], v[132:135]
	v_mfma_f32_16x16x32_bf16 v[128:131], v[180:183], v[188:191], v[128:131]
	v_mfma_f32_16x16x32_bf16 v[116:119], v[164:167], v[196:199], v[116:119]
	v_mfma_f32_16x16x32_bf16 v[112:115], v[180:183], v[196:199], v[112:115]
	v_mfma_f32_16x16x32_bf16 v[100:103], v[164:167], v[204:207], v[100:103]
	v_mfma_f32_16x16x32_bf16 v[96:99], v[180:183], v[204:207], v[96:99]
	v_mfma_f32_16x16x32_bf16 v[68:71], v[164:167], v[212:215], v[68:71]
	v_mfma_f32_16x16x32_bf16 v[64:67], v[180:183], v[212:215], v[64:67]
	v_mfma_f32_16x16x32_bf16 v[132:135], v[176:179], v[192:195], v[132:135]
	v_mfma_f32_16x16x32_bf16 v[128:131], v[184:187], v[192:195], v[128:131]
	v_mfma_f32_16x16x32_bf16 v[116:119], v[176:179], v[200:203], v[116:119]
	v_mfma_f32_16x16x32_bf16 v[112:115], v[184:187], v[200:203], v[112:115]
	v_mfma_f32_16x16x32_bf16 v[100:103], v[176:179], v[208:211], v[100:103]
	v_mfma_f32_16x16x32_bf16 v[96:99], v[184:187], v[208:211], v[96:99]
	s_setprio 2
	s_barrier
; #define PG8_STAGE(bufoff, gbase, voff) do { _Pragma("unroll") for (int _i = 0; _i < 2; ++_i) \
;         __builtin_amdgcn_global_load_lds((const unsigned*)((const char*)(gbase) + (voff)[_i]), (PG8_LAS unsigned*)(lds + (bufoff) + ldsw + _i * 8192), 16, 0, 0); } while (0)
; #define PG8_LDA(dst, b, h) do { _Pragma("unroll") for (int m = 0; m < 4; ++m) _Pragma("unroll") for (int k = 0; k < 2; ++k) dst[m][k] = *(const PG8_LAS bf16x8*)(lds + PG8_SA(b, h) + aoff + m * 2048 + k * 1024); } while (0)
; #define PG8_MMA(ai, bj, At, Bt) do { __builtin_amdgcn_s_setprio(1); _Pragma("unroll") for (int m = 0; m < 4; ++m) _Pragma("unroll") for (int n = 0; n < 2; ++n) _Pragma("unroll") for (int k = 0; k < 2; ++k) \
;         acc[ai][bj][m][n] = __builtin_amdgcn_mfma_f32_16x16x32_bf16(Bt[n][k], At[m][k], acc[ai][bj][m][n], 0, 0, 0); __builtin_amdgcn_s_setprio(0); } while (0)
; #define PG8_WAIT_V(n) asm volatile("s_waitcnt vmcnt(" #n ")" ::: "memory")
; #define PG8_WAIT_L(n) asm volatile("s_waitcnt lgkmcnt(" #n ")" ::: "memory")
; #define PG8_BAR __builtin_amdgcn_s_barrier()
; #define PG8_SCHED __builtin_amdgcn_sched_barrier(0)
; template <class Epi, class Sched, bool ALIGN_EPI = false, bool SP2 = false>
; __device__ __forceinline__ void gemm_phase(PG8_LAS unsigned char* lds, const Gemm g, const Sched& S, const Epi& E) {
;     ...
;         for (int t = 0; t < nt; t += 2) {
;             const bool last = (t == nt - 2);
;             const char* a1 = cA + (size_t)(t + 1) * kstep;
;             const char* a2 = last ? nA : cA + (size_t)(t + 2) * kstep; const char* b2 = last ? nB : cB + (size_t)(t + 2) * kstep;
;             const char* a3 = a2 + kstep; const char* b3 = b2 + kstep;
;     ...
;             PG8_WAIT_V(8); PG8_WAIT_L(0); PG8_BAR; PG8_MMA(0, 0, At, B0); PG8_MMA(0, 1, At, B1); PG8_BAR; PG8_SCHED;
;             PG8_LDA(At, 1, 1); PG8_STAGE(PG8_SB(1, 0), b3, voffB); PG8_STAGE(PG8_SB(1, 1), b3 + hstep, voffB); PG8_STAGE(PG8_SA(1, 0), a3, voffA);
;             PG8_WAIT_V(8); PG8_WAIT_L(0); PG8_BAR; PG8_MMA(1, 0, At, B0); PG8_MMA(1, 1, At, B1); PG8_BAR; PG8_SCHED;
	v_mfma_f32_16x16x32_bf16 v[68:71], v[176:179], v[216:219], v[68:71]
	v_mfma_f32_16x16x32_bf16 v[64:67], v[184:187], v[216:219], v[64:67]
	s_setprio 0
	s_add_i32 s46, s65, s33
	v_lshl_add_u64 v[220:221], v[220:221], 0, s[8:9]
	s_mov_b32 m0, s46
	ds_read_b128 v[188:191], v173 offset:49152
	ds_read_b128 v[192:195], v173 offset:50176
	ds_read_b128 v[196:199], v173 offset:51200
	ds_read_b128 v[200:203], v173 offset:52224
	ds_read_b128 v[204:207], v173 offset:53248
	ds_read_b128 v[208:211], v173 offset:54272
	ds_read_b128 v[212:215], v173 offset:55296
	ds_read_b128 v[216:219], v173 offset:56320
	global_load_lds_dwordx4 v[220:221], off
	s_add_i32 m0, s46, 0x2000
	s_add_u32 s44, s44, 0x80080
	v_lshl_add_u64 v[220:221], v[222:223], 0, s[8:9]
	s_addc_u32 s45, s45, 0
	s_add_i32 s46, s66, s33
	global_load_lds_dwordx4 v[220:221], off
	v_lshl_add_u64 v[220:221], s[44:45], 0, v[148:149]
	s_mov_b32 m0, s46
	s_nop 0
	global_load_lds_dwordx4 v[220:221], off
	v_lshl_add_u64 v[220:221], s[44:45], 0, v[152:153]
	s_add_i32 m0, s46, 0x2000
	s_nop 0
	global_load_lds_dwordx4 v[220:221], off
	v_lshl_add_u64 v[220:221], v[224:225], 0, s[8:9]
	s_mov_b32 m0, s52
	s_nop 0
	global_load_lds_dwordx4 v[220:221], off
	v_lshl_add_u64 v[220:221], v[226:227], 0, s[8:9]
	s_mov_b32 m0, s53
	s_nop 0
	global_load_lds_dwordx4 v[220:221], off
	s_waitcnt vmcnt(8)
	s_waitcnt lgkmcnt(0)
	s_barrier
	s_setprio 1
	s_waitcnt lgkmcnt(0)
	v_mfma_f32_16x16x32_bf16 v[60:63], v[80:83], v[188:191], v[60:63]
	v_mfma_f32_16x16x32_bf16 v[56:59], v[88:91], v[188:191], v[56:59]
	v_mfma_f32_16x16x32_bf16 v[44:47], v[80:83], v[196:199], v[44:47]
	v_mfma_f32_16x16x32_bf16 v[40:43], v[88:91], v[196:199], v[40:43]
	v_mfma_f32_16x16x32_bf16 v[28:31], v[80:83], v[204:207], v[28:31]
	v_mfma_f32_16x16x32_bf16 v[24:27], v[88:91], v[204:207], v[24:27]
	v_mfma_f32_16x16x32_bf16 v[12:15], v[80:83], v[212:215], v[12:15]
	v_mfma_f32_16x16x32_bf16 v[8:11], v[88:91], v[212:215], v[8:11]
	v_mfma_f32_16x16x32_bf16 v[60:63], v[84:87], v[192:195], v[60:63]
	v_mfma_f32_16x16x32_bf16 v[56:59], v[92:95], v[192:195], v[56:59]
	v_mfma_f32_16x16x32_bf16 v[44:47], v[84:87], v[200:203], v[44:47]
	v_mfma_f32_16x16x32_bf16 v[40:43], v[92:95], v[200:203], v[40:43]
	v_mfma_f32_16x16x32_bf16 v[28:31], v[84:87], v[208:211], v[28:31]
	v_mfma_f32_16x16x32_bf16 v[24:27], v[92:95], v[208:211], v[24:27]
	v_mfma_f32_16x16x32_bf16 v[12:15], v[84:87], v[216:219], v[12:15]
	v_mfma_f32_16x16x32_bf16 v[8:11], v[92:95], v[216:219], v[8:11]
	s_setprio 0
	s_setprio 1
	v_mfma_f32_16x16x32_bf16 v[52:55], v[164:167], v[188:191], v[52:55]
	v_mfma_f32_16x16x32_bf16 v[48:51], v[180:183], v[188:191], v[48:51]
	v_mfma_f32_16x16x32_bf16 v[36:39], v[164:167], v[196:199], v[36:39]
	v_mfma_f32_16x16x32_bf16 v[32:35], v[180:183], v[196:199], v[32:35]
	v_mfma_f32_16x16x32_bf16 v[20:23], v[164:167], v[204:207], v[20:23]
	v_mfma_f32_16x16x32_bf16 v[16:19], v[180:183], v[204:207], v[16:19]
	v_mfma_f32_16x16x32_bf16 v[4:7], v[164:167], v[212:215], v[4:7]
	v_mfma_f32_16x16x32_bf16 v[0:3], v[180:183], v[212:215], v[0:3]
	v_mfma_f32_16x16x32_bf16 v[52:55], v[176:179], v[192:195], v[52:55]
	v_mfma_f32_16x16x32_bf16 v[48:51], v[184:187], v[192:195], v[48:51]
	v_mfma_f32_16x16x32_bf16 v[36:39], v[176:179], v[200:203], v[36:39]
	v_mfma_f32_16x16x32_bf16 v[32:35], v[184:187], v[200:203], v[32:35]
	v_mfma_f32_16x16x32_bf16 v[20:23], v[176:179], v[208:211], v[20:23]
	v_mfma_f32_16x16x32_bf16 v[16:19], v[184:187], v[208:211], v[16:19]
	s_setprio 2
	s_barrier
	v_mfma_f32_16x16x32_bf16 v[4:7], v[176:179], v[216:219], v[4:7]
	v_mfma_f32_16x16x32_bf16 v[0:3], v[184:187], v[216:219], v[0:3]
	s_setprio 0
	s_add_i32 s64, s64, 2
	s_add_u32 s42, s42, 0x100
	s_addc_u32 s43, s43, 0
	s_add_u32 s62, s62, 0x100
	s_addc_u32 s63, s63, 0
	s_cmp_gt_u32 s64, 29
	s_cbranch_scc0 .LBB0_1142
	s_and_b64 vcc, exec, s[10:11]
	s_cbranch_vccz .LBB0_1145
	s_barrier

; #define PG8_STAGE(bufoff, gbase, voff) do { _Pragma("unroll") for (int _i = 0; _i < 2; ++_i) \
;         __builtin_amdgcn_global_load_lds((const unsigned*)((const char*)(gbase) + (voff)[_i]), (PG8_LAS unsigned*)(lds + (bufoff) + ldsw + _i * 8192), 16, 0, 0); } while (0)
; #define PG8_LDA(dst, b, h) do { _Pragma("unroll") for (int m = 0; m < 4; ++m) _Pragma("unroll") for (int k = 0; k < 2; ++k) dst[m][k] = *(const PG8_LAS bf16x8*)(lds + PG8_SA(b, h) + aoff + m * 2048 + k * 1024); } while (0)
; #define PG8_LDB(dst, b, h) do { _Pragma("unroll") for (int n = 0; n < 2; ++n) _Pragma("unroll") for (int k = 0; k < 2; ++k) dst[n][k] = *(const PG8_LAS bf16x8*)(lds + PG8_SB(b, h) + boff + n * 2048 + k * 1024); } while (0)
; #define PG8_MMA(ai, bj, At, Bt) do { __builtin_amdgcn_s_setprio(1); _Pragma("unroll") for (int m = 0; m < 4; ++m) _Pragma("unroll") for (int n = 0; n < 2; ++n) _Pragma("unroll") for (int k = 0; k < 2; ++k) \
;         acc[ai][bj][m][n] = __builtin_amdgcn_mfma_f32_16x16x32_bf16(Bt[n][k], At[m][k], acc[ai][bj][m][n], 0, 0, 0); __builtin_amdgcn_s_setprio(0); } while (0)
; #define PG8_WAIT_V(n) asm volatile("s_waitcnt vmcnt(" #n ")" ::: "memory")
; #define PG8_WAIT_L(n) asm volatile("s_waitcnt lgkmcnt(" #n ")" ::: "memory")
; #define PG8_BAR __builtin_amdgcn_s_barrier()
; template <class Epi, class Sched, bool ALIGN_EPI = false, bool SP2 = false>
; __device__ __forceinline__ void gemm_phase(PG8_LAS unsigned char* lds, const Gemm g, const Sched& S, const Epi& E) {
;     ...
;             const bool last = (t == nt - 2);
;             const char* a1 = cA + (size_t)(t + 1) * kstep;
;             const char* a2 = last ? nA : cA + (size_t)(t + 2) * kstep; const char* b2 = last ? nB : cB + (size_t)(t + 2) * kstep;
;             const char* a3 = a2 + kstep; const char* b3 = b2 + kstep;
;             if constexpr (SP2) {
;             PG8_LDB(B0, 0, 0); PG8_LDB(B1, 0, 1); PG8_SCHED; PG8_LDA(At, 0, 0); PG8_STAGE(PG8_SA(1, 1), a1 + hstep, voffA);
;             PG8_WAIT_V(8); PG8_WAIT_L(0); PG8_BAR; PG8_MMA(0, 0, At, B0); PG8_MMA(0, 1, At, B1); PG8_BAR; PG8_SCHED;
;             PG8_LDA(At, 0, 1); PG8_STAGE(PG8_SB(0, 0), b2, voffB); PG8_STAGE(PG8_SB(0, 1), b2 + hstep, voffB); PG8_STAGE(PG8_SA(0, 0), a2, voffA);
;             PG8_WAIT_V(8); PG8_WAIT_L(0); PG8_BAR; PG8_MMA(1, 0, At, B0); PG8_MMA(1, 1, At, B1); PG8_BAR; PG8_SCHED;
.LBB0_1219:
	ds_read_b128 v[128:131], v167
	ds_read_b128 v[132:135], v167 offset:1024
	ds_read_b128 v[154:157], v167 offset:2048
	ds_read_b128 v[158:161], v167 offset:3072
	ds_read_b128 v[170:173], v168
	ds_read_b128 v[174:177], v168 offset:1024
	ds_read_b128 v[178:181], v168 offset:2048
	ds_read_b128 v[182:185], v168 offset:3072
	s_add_u32 s42, s40, 0xffe00080
	s_addc_u32 s43, s41, -1
	s_cmpk_eq_i32 s63, 0x7c
	s_cselect_b32 s45, s15, s43
	s_cselect_b32 s44, s59, s42
	s_cselect_b32 s43, s13, s62
	s_cselect_b32 s42, s60, s61
	v_lshl_add_u64 v[162:163], s[40:41], 0, v[144:145]
	s_add_i32 m0, s39, 0xc000
	ds_read_b128 v[186:189], v169
	ds_read_b128 v[190:193], v169 offset:1024
	ds_read_b128 v[194:197], v169 offset:2048
	ds_read_b128 v[198:201], v169 offset:3072
	ds_read_b128 v[202:205], v169 offset:4096
	ds_read_b128 v[206:209], v169 offset:5120
	ds_read_b128 v[210:213], v169 offset:6144
	ds_read_b128 v[214:217], v169 offset:7168
	global_load_lds_dwordx4 v[162:163], off
	v_lshl_add_u64 v[162:163], s[40:41], 0, v[148:149]
	s_add_i32 m0, s39, 0xe000
	s_nop 0
	global_load_lds_dwordx4 v[162:163], off
	s_waitcnt vmcnt(8)
	s_waitcnt lgkmcnt(0)
	s_barrier
	s_setprio 1
	s_waitcnt lgkmcnt(0)
	v_mfma_f32_16x16x32_bf16 v[124:127], v[128:131], v[186:189], v[124:127]
	v_mfma_f32_16x16x32_bf16 v[120:123], v[154:157], v[186:189], v[120:123]
	v_mfma_f32_16x16x32_bf16 v[116:119], v[128:131], v[194:197], v[116:119]
	v_mfma_f32_16x16x32_bf16 v[112:115], v[154:157], v[194:197], v[112:115]
	v_mfma_f32_16x16x32_bf16 v[108:111], v[128:131], v[202:205], v[108:111]
	v_mfma_f32_16x16x32_bf16 v[104:107], v[154:157], v[202:205], v[104:107]
	v_mfma_f32_16x16x32_bf16 v[100:103], v[128:131], v[210:213], v[100:103]
	v_mfma_f32_16x16x32_bf16 v[96:99], v[154:157], v[210:213], v[96:99]
	v_mfma_f32_16x16x32_bf16 v[124:127], v[132:135], v[190:193], v[124:127]
	v_mfma_f32_16x16x32_bf16 v[120:123], v[158:161], v[190:193], v[120:123]
	v_mfma_f32_16x16x32_bf16 v[116:119], v[132:135], v[198:201], v[116:119]
	v_mfma_f32_16x16x32_bf16 v[112:115], v[158:161], v[198:201], v[112:115]
	v_mfma_f32_16x16x32_bf16 v[108:111], v[132:135], v[206:209], v[108:111]
	v_mfma_f32_16x16x32_bf16 v[104:107], v[158:161], v[206:209], v[104:107]
	v_mfma_f32_16x16x32_bf16 v[100:103], v[132:135], v[214:217], v[100:103]
	v_mfma_f32_16x16x32_bf16 v[96:99], v[158:161], v[214:217], v[96:99]
	s_setprio 0
	s_setprio 1
	v_mfma_f32_16x16x32_bf16 v[68:71], v[170:173], v[186:189], v[68:71]
	v_mfma_f32_16x16x32_bf16 v[60:63], v[178:181], v[186:189], v[60:63]
	v_mfma_f32_16x16x32_bf16 v[52:55], v[170:173], v[194:197], v[52:55]
	v_mfma_f32_16x16x32_bf16 v[48:51], v[178:181], v[194:197], v[48:51]
	v_mfma_f32_16x16x32_bf16 v[44:47], v[170:173], v[202:205], v[44:47]
	v_mfma_f32_16x16x32_bf16 v[40:43], v[178:181], v[202:205], v[40:43]
	v_mfma_f32_16x16x32_bf16 v[36:39], v[170:173], v[210:213], v[36:39]
	v_mfma_f32_16x16x32_bf16 v[32:35], v[178:181], v[210:213], v[32:35]
	v_mfma_f32_16x16x32_bf16 v[68:71], v[174:177], v[190:193], v[68:71]
	v_mfma_f32_16x16x32_bf16 v[60:63], v[182:185], v[190:193], v[60:63]
	v_mfma_f32_16x16x32_bf16 v[52:55], v[174:177], v[198:201], v[52:55]
	v_mfma_f32_16x16x32_bf16 v[48:51], v[182:185], v[198:201], v[48:51]
	v_mfma_f32_16x16x32_bf16 v[44:47], v[174:177], v[206:209], v[44:47]
	v_mfma_f32_16x16x32_bf16 v[40:43], v[182:185], v[206:209], v[40:43]
	s_setprio 2
	s_barrier
	v_mfma_f32_16x16x32_bf16 v[36:39], v[174:177], v[214:217], v[36:39]
	v_mfma_f32_16x16x32_bf16 v[32:35], v[182:185], v[214:217], v[32:35]
	s_setprio 0
	s_add_i32 s64, s56, s33
	v_lshl_add_u64 v[162:163], s[42:43], 0, v[138:139]
	s_mov_b32 m0, s64
	ds_read_b128 v[186:189], v169 offset:16384
	ds_read_b128 v[190:193], v169 offset:17408
	ds_read_b128 v[194:197], v169 offset:18432
	ds_read_b128 v[198:201], v169 offset:19456
	ds_read_b128 v[202:205], v169 offset:20480
	ds_read_b128 v[206:209], v169 offset:21504
	ds_read_b128 v[210:213], v169 offset:22528
	ds_read_b128 v[214:217], v169 offset:23552
	global_load_lds_dwordx4 v[162:163], off
	s_add_i32 m0, s64, 0x2000
	s_add_u32 s64, s42, 0x200000
	v_lshl_add_u64 v[218:219], s[42:43], 0, v[142:143]
	s_addc_u32 s65, s43, 0
	s_add_i32 s66, s57, s33
	global_load_lds_dwordx4 v[218:219], off
	v_lshl_add_u64 v[220:221], s[64:65], 0, v[138:139]
	s_mov_b32 m0, s66
	v_lshl_add_u64 v[222:223], s[44:45], 0, v[140:141]
	global_load_lds_dwordx4 v[220:221], off
	v_lshl_add_u64 v[220:221], s[64:65], 0, v[142:143]
	s_add_i32 m0, s66, 0x2000
	s_nop 0
	global_load_lds_dwordx4 v[220:221], off
	v_lshl_add_u64 v[220:221], s[44:45], 0, v[136:137]
	s_mov_b32 m0, s39
	s_nop 0
	global_load_lds_dwordx4 v[220:221], off
	s_mov_b32 m0, s46
	s_nop 0
	global_load_lds_dwordx4 v[222:223], off
	s_waitcnt vmcnt(8)
	s_waitcnt lgkmcnt(0)
	s_barrier
; #define PG8_STAGE(bufoff, gbase, voff) do { _Pragma("unroll") for (int _i = 0; _i < 2; ++_i) \
;         __builtin_amdgcn_global_load_lds((const unsigned*)((const char*)(gbase) + (voff)[_i]), (PG8_LAS unsigned*)(lds + (bufoff) + ldsw + _i * 8192), 16, 0, 0); } while (0)
; #define PG8_LDA(dst, b, h) do { _Pragma("unroll") for (int m = 0; m < 4; ++m) _Pragma("unroll") for (int k = 0; k < 2; ++k) dst[m][k] = *(const PG8_LAS bf16x8*)(lds + PG8_SA(b, h) + aoff + m * 2048 + k * 1024); } while (0)
; #define PG8_LDB(dst, b, h) do { _Pragma("unroll") for (int n = 0; n < 2; ++n) _Pragma("unroll") for (int k = 0; k < 2; ++k) dst[n][k] = *(const PG8_LAS bf16x8*)(lds + PG8_SB(b, h) + boff + n * 2048 + k * 1024); } while (0)
; #define PG8_MMA(ai, bj, At, Bt) do { __builtin_amdgcn_s_setprio(1); _Pragma("unroll") for (int m = 0; m < 4; ++m) _Pragma("unroll") for (int n = 0; n < 2; ++n) _Pragma("unroll") for (int k = 0; k < 2; ++k) \
;         acc[ai][bj][m][n] = __builtin_amdgcn_mfma_f32_16x16x32_bf16(Bt[n][k], At[m][k], acc[ai][bj][m][n], 0, 0, 0); __builtin_amdgcn_s_setprio(0); } while (0)
; #define PG8_WAIT_V(n) asm volatile("s_waitcnt vmcnt(" #n ")" ::: "memory")
; #define PG8_WAIT_L(n) asm volatile("s_waitcnt lgkmcnt(" #n ")" ::: "memory")
; #define PG8_BAR __builtin_amdgcn_s_barrier()
; #define PG8_SCHED __builtin_amdgcn_sched_barrier(0)
; template <class Epi, class Sched, bool ALIGN_EPI = false, bool SP2 = false>
; __device__ __forceinline__ void gemm_phase(PG8_LAS unsigned char* lds, const Gemm g, const Sched& S, const Epi& E) {
;     ...
;             PG8_WAIT_V(8); PG8_WAIT_L(0); PG8_BAR; PG8_MMA(1, 0, At, B0); PG8_MMA(1, 1, At, B1); PG8_BAR; PG8_SCHED;
;             PG8_LDB(B0, 1, 0); PG8_LDB(B1, 1, 1); PG8_SCHED; PG8_LDA(At, 1, 0); PG8_STAGE(PG8_SA(0, 1), a2 + hstep, voffA);
;             PG8_WAIT_V(8); PG8_WAIT_L(0); PG8_BAR; PG8_MMA(0, 0, At, B0); PG8_MMA(0, 1, At, B1); PG8_BAR; PG8_SCHED;
;             PG8_LDA(At, 1, 1); PG8_STAGE(PG8_SB(1, 0), b3, voffB); PG8_STAGE(PG8_SB(1, 1), b3 + hstep, voffB); PG8_STAGE(PG8_SA(1, 0), a3, voffA);
;             PG8_WAIT_V(8); PG8_WAIT_L(0); PG8_BAR; PG8_MMA(1, 0, At, B0); PG8_MMA(1, 1, At, B1); PG8_BAR; PG8_SCHED;
	s_setprio 1
	s_waitcnt lgkmcnt(0)
	v_mfma_f32_16x16x32_bf16 v[92:95], v[128:131], v[186:189], v[92:95]
	v_mfma_f32_16x16x32_bf16 v[88:91], v[154:157], v[186:189], v[88:91]
	v_mfma_f32_16x16x32_bf16 v[84:87], v[128:131], v[194:197], v[84:87]
	v_mfma_f32_16x16x32_bf16 v[80:83], v[154:157], v[194:197], v[80:83]
	v_mfma_f32_16x16x32_bf16 v[76:79], v[128:131], v[202:205], v[76:79]
	v_mfma_f32_16x16x32_bf16 v[72:75], v[154:157], v[202:205], v[72:75]
	v_mfma_f32_16x16x32_bf16 v[64:67], v[128:131], v[210:213], v[64:67]
	v_mfma_f32_16x16x32_bf16 v[56:59], v[154:157], v[210:213], v[56:59]
	v_mfma_f32_16x16x32_bf16 v[92:95], v[132:135], v[190:193], v[92:95]
	v_mfma_f32_16x16x32_bf16 v[88:91], v[158:161], v[190:193], v[88:91]
	v_mfma_f32_16x16x32_bf16 v[84:87], v[132:135], v[198:201], v[84:87]
	v_mfma_f32_16x16x32_bf16 v[80:83], v[158:161], v[198:201], v[80:83]
	v_mfma_f32_16x16x32_bf16 v[76:79], v[132:135], v[206:209], v[76:79]
	v_mfma_f32_16x16x32_bf16 v[72:75], v[158:161], v[206:209], v[72:75]
	v_mfma_f32_16x16x32_bf16 v[64:67], v[132:135], v[214:217], v[64:67]
	v_mfma_f32_16x16x32_bf16 v[56:59], v[158:161], v[214:217], v[56:59]
	s_setprio 0
	s_setprio 1
	v_mfma_f32_16x16x32_bf16 v[28:31], v[170:173], v[186:189], v[28:31]
	v_mfma_f32_16x16x32_bf16 v[24:27], v[178:181], v[186:189], v[24:27]
	v_mfma_f32_16x16x32_bf16 v[20:23], v[170:173], v[194:197], v[20:23]
	v_mfma_f32_16x16x32_bf16 v[16:19], v[178:181], v[194:197], v[16:19]
	v_mfma_f32_16x16x32_bf16 v[12:15], v[170:173], v[202:205], v[12:15]
	v_mfma_f32_16x16x32_bf16 v[8:11], v[178:181], v[202:205], v[8:11]
	v_mfma_f32_16x16x32_bf16 v[4:7], v[170:173], v[210:213], v[4:7]
	v_mfma_f32_16x16x32_bf16 v[0:3], v[178:181], v[210:213], v[0:3]
	v_mfma_f32_16x16x32_bf16 v[28:31], v[174:177], v[190:193], v[28:31]
	v_mfma_f32_16x16x32_bf16 v[24:27], v[182:185], v[190:193], v[24:27]
	v_mfma_f32_16x16x32_bf16 v[20:23], v[174:177], v[198:201], v[20:23]
	v_mfma_f32_16x16x32_bf16 v[16:19], v[182:185], v[198:201], v[16:19]
	v_mfma_f32_16x16x32_bf16 v[12:15], v[174:177], v[206:209], v[12:15]
	v_mfma_f32_16x16x32_bf16 v[8:11], v[182:185], v[206:209], v[8:11]
	s_setprio 2
	s_barrier
	v_mfma_f32_16x16x32_bf16 v[4:7], v[174:177], v[214:217], v[4:7]
	v_mfma_f32_16x16x32_bf16 v[0:3], v[182:185], v[214:217], v[0:3]
	s_setprio 0
	s_add_i32 s64, 0, 0x18000
	s_add_i32 s65, 0, 0x1c000
	v_add_u32_e32 v158, s64, v165
	v_add_u32_e32 v182, s65, v165
	ds_read_b128 v[128:131], v158
	ds_read_b128 v[132:135], v158 offset:1024
	ds_read_b128 v[154:157], v158 offset:2048
	ds_read_b128 v[158:161], v158 offset:3072
	ds_read_b128 v[170:173], v182
	ds_read_b128 v[174:177], v182 offset:1024
	ds_read_b128 v[178:181], v182 offset:2048
	ds_read_b128 v[182:185], v182 offset:3072
	s_add_u32 s44, s44, 0x200000
	s_addc_u32 s45, s45, 0
	s_mov_b32 m0, s47
	v_lshl_add_u64 v[224:225], s[44:45], 0, v[136:137]
	ds_read_b128 v[186:189], v169 offset:32768
	ds_read_b128 v[190:193], v169 offset:33792
	ds_read_b128 v[194:197], v169 offset:34816
	ds_read_b128 v[198:201], v169 offset:35840
	ds_read_b128 v[202:205], v169 offset:36864
	ds_read_b128 v[206:209], v169 offset:37888
	ds_read_b128 v[210:213], v169 offset:38912
	ds_read_b128 v[214:217], v169 offset:39936
	global_load_lds_dwordx4 v[224:225], off
	v_lshl_add_u64 v[224:225], s[44:45], 0, v[140:141]
	s_mov_b32 m0, s48
	s_nop 0
	global_load_lds_dwordx4 v[224:225], off
	s_waitcnt vmcnt(8)
	s_waitcnt lgkmcnt(0)
	s_barrier
	s_setprio 1
	s_waitcnt lgkmcnt(0)
	v_mfma_f32_16x16x32_bf16 v[124:127], v[128:131], v[186:189], v[124:127]
	v_mfma_f32_16x16x32_bf16 v[120:123], v[154:157], v[186:189], v[120:123]
	v_mfma_f32_16x16x32_bf16 v[116:119], v[128:131], v[194:197], v[116:119]
	v_mfma_f32_16x16x32_bf16 v[112:115], v[154:157], v[194:197], v[112:115]
	v_mfma_f32_16x16x32_bf16 v[108:111], v[128:131], v[202:205], v[108:111]
	v_mfma_f32_16x16x32_bf16 v[104:107], v[154:157], v[202:205], v[104:107]
	v_mfma_f32_16x16x32_bf16 v[100:103], v[128:131], v[210:213], v[100:103]
	v_mfma_f32_16x16x32_bf16 v[96:99], v[154:157], v[210:213], v[96:99]
	v_mfma_f32_16x16x32_bf16 v[124:127], v[132:135], v[190:193], v[124:127]
	v_mfma_f32_16x16x32_bf16 v[120:123], v[158:161], v[190:193], v[120:123]
	v_mfma_f32_16x16x32_bf16 v[116:119], v[132:135], v[198:201], v[116:119]
	v_mfma_f32_16x16x32_bf16 v[112:115], v[158:161], v[198:201], v[112:115]
	v_mfma_f32_16x16x32_bf16 v[108:111], v[132:135], v[206:209], v[108:111]
	v_mfma_f32_16x16x32_bf16 v[104:107], v[158:161], v[206:209], v[104:107]
	v_mfma_f32_16x16x32_bf16 v[100:103], v[132:135], v[214:217], v[100:103]
	v_mfma_f32_16x16x32_bf16 v[96:99], v[158:161], v[214:217], v[96:99]
	s_setprio 0
	s_setprio 1
	v_mfma_f32_16x16x32_bf16 v[68:71], v[170:173], v[186:189], v[68:71]
	v_mfma_f32_16x16x32_bf16 v[60:63], v[178:181], v[186:189], v[60:63]
	v_mfma_f32_16x16x32_bf16 v[52:55], v[170:173], v[194:197], v[52:55]
	v_mfma_f32_16x16x32_bf16 v[48:51], v[178:181], v[194:197], v[48:51]
	v_mfma_f32_16x16x32_bf16 v[44:47], v[170:173], v[202:205], v[44:47]
	v_mfma_f32_16x16x32_bf16 v[40:43], v[178:181], v[202:205], v[40:43]
	v_mfma_f32_16x16x32_bf16 v[36:39], v[170:173], v[210:213], v[36:39]
	v_mfma_f32_16x16x32_bf16 v[32:35], v[178:181], v[210:213], v[32:35]
	v_mfma_f32_16x16x32_bf16 v[68:71], v[174:177], v[190:193], v[68:71]
	v_mfma_f32_16x16x32_bf16 v[60:63], v[182:185], v[190:193], v[60:63]
	v_mfma_f32_16x16x32_bf16 v[52:55], v[174:177], v[198:201], v[52:55]
	v_mfma_f32_16x16x32_bf16 v[48:51], v[182:185], v[198:201], v[48:51]
	v_mfma_f32_16x16x32_bf16 v[44:47], v[174:177], v[206:209], v[44:47]
	v_mfma_f32_16x16x32_bf16 v[40:43], v[182:185], v[206:209], v[40:43]
	s_setprio 2
	s_barrier
; #define PG8_STAGE(bufoff, gbase, voff) do { _Pragma("unroll") for (int _i = 0; _i < 2; ++_i) \
;         __builtin_amdgcn_global_load_lds((const unsigned*)((const char*)(gbase) + (voff)[_i]), (PG8_LAS unsigned*)(lds + (bufoff) + ldsw + _i * 8192), 16, 0, 0); } while (0)
; #define PG8_LDA(dst, b, h) do { _Pragma("unroll") for (int m = 0; m < 4; ++m) _Pragma("unroll") for (int k = 0; k < 2; ++k) dst[m][k] = *(const PG8_LAS bf16x8*)(lds + PG8_SA(b, h) + aoff + m * 2048 + k * 1024); } while (0)
; #define PG8_MMA(ai, bj, At, Bt) do { __builtin_amdgcn_s_setprio(1); _Pragma("unroll") for (int m = 0; m < 4; ++m) _Pragma("unroll") for (int n = 0; n < 2; ++n) _Pragma("unroll") for (int k = 0; k < 2; ++k) \
;         acc[ai][bj][m][n] = __builtin_amdgcn_mfma_f32_16x16x32_bf16(Bt[n][k], At[m][k], acc[ai][bj][m][n], 0, 0, 0); __builtin_amdgcn_s_setprio(0); } while (0)
; #define PG8_WAIT_V(n) asm volatile("s_waitcnt vmcnt(" #n ")" ::: "memory")
; #define PG8_WAIT_L(n) asm volatile("s_waitcnt lgkmcnt(" #n ")" ::: "memory")
; #define PG8_BAR __builtin_amdgcn_s_barrier()
; #define PG8_SCHED __builtin_amdgcn_sched_barrier(0)
; template <class Epi, class Sched, bool ALIGN_EPI = false, bool SP2 = false>
; __device__ __forceinline__ void gemm_phase(PG8_LAS unsigned char* lds, const Gemm g, const Sched& S, const Epi& E) {
;     ...
;         for (int t = 0; t < nt; t += 2) {
;             const bool last = (t == nt - 2);
;             const char* a1 = cA + (size_t)(t + 1) * kstep;
;             const char* a2 = last ? nA : cA + (size_t)(t + 2) * kstep; const char* b2 = last ? nB : cB + (size_t)(t + 2) * kstep;
;             const char* a3 = a2 + kstep; const char* b3 = b2 + kstep;
;     ...
;             PG8_WAIT_V(8); PG8_WAIT_L(0); PG8_BAR; PG8_MMA(0, 0, At, B0); PG8_MMA(0, 1, At, B1); PG8_BAR; PG8_SCHED;
;             PG8_LDA(At, 1, 1); PG8_STAGE(PG8_SB(1, 0), b3, voffB); PG8_STAGE(PG8_SB(1, 1), b3 + hstep, voffB); PG8_STAGE(PG8_SA(1, 0), a3, voffA);
;             PG8_WAIT_V(8); PG8_WAIT_L(0); PG8_BAR; PG8_MMA(1, 0, At, B0); PG8_MMA(1, 1, At, B1); PG8_BAR; PG8_SCHED;
	v_mfma_f32_16x16x32_bf16 v[36:39], v[174:177], v[214:217], v[36:39]
	v_mfma_f32_16x16x32_bf16 v[32:35], v[182:185], v[214:217], v[32:35]
	s_setprio 0
	s_add_i32 s44, s64, s33
	v_lshl_add_u64 v[162:163], v[162:163], 0, s[8:9]
	s_mov_b32 m0, s44
	ds_read_b128 v[186:189], v169 offset:49152
	ds_read_b128 v[190:193], v169 offset:50176
	ds_read_b128 v[194:197], v169 offset:51200
	ds_read_b128 v[198:201], v169 offset:52224
	ds_read_b128 v[202:205], v169 offset:53248
	ds_read_b128 v[206:209], v169 offset:54272
	ds_read_b128 v[210:213], v169 offset:55296
	ds_read_b128 v[214:217], v169 offset:56320
	global_load_lds_dwordx4 v[162:163], off
	s_add_i32 m0, s44, 0x2000
	s_add_u32 s42, s42, 0x200080
	v_lshl_add_u64 v[162:163], v[218:219], 0, s[8:9]
	s_addc_u32 s43, s43, 0
	s_add_i32 s44, s65, s33
	global_load_lds_dwordx4 v[162:163], off
	v_lshl_add_u64 v[162:163], s[42:43], 0, v[138:139]
	s_mov_b32 m0, s44
	s_nop 0
	global_load_lds_dwordx4 v[162:163], off
	v_lshl_add_u64 v[162:163], s[42:43], 0, v[142:143]
	s_add_i32 m0, s44, 0x2000
	s_nop 0
	global_load_lds_dwordx4 v[162:163], off
	v_lshl_add_u64 v[162:163], v[220:221], 0, s[8:9]
	s_mov_b32 m0, s52
	s_nop 0
	global_load_lds_dwordx4 v[162:163], off
	v_lshl_add_u64 v[162:163], v[222:223], 0, s[8:9]
	s_mov_b32 m0, s53
	s_nop 0
	global_load_lds_dwordx4 v[162:163], off
	s_waitcnt vmcnt(8)
	s_waitcnt lgkmcnt(0)
	s_barrier
	s_setprio 1
	s_waitcnt lgkmcnt(0)
	v_mfma_f32_16x16x32_bf16 v[92:95], v[128:131], v[186:189], v[92:95]
	v_mfma_f32_16x16x32_bf16 v[88:91], v[154:157], v[186:189], v[88:91]
	v_mfma_f32_16x16x32_bf16 v[84:87], v[128:131], v[194:197], v[84:87]
	v_mfma_f32_16x16x32_bf16 v[80:83], v[154:157], v[194:197], v[80:83]
	v_mfma_f32_16x16x32_bf16 v[76:79], v[128:131], v[202:205], v[76:79]
	v_mfma_f32_16x16x32_bf16 v[72:75], v[154:157], v[202:205], v[72:75]
	v_mfma_f32_16x16x32_bf16 v[64:67], v[128:131], v[210:213], v[64:67]
	v_mfma_f32_16x16x32_bf16 v[56:59], v[154:157], v[210:213], v[56:59]
	v_mfma_f32_16x16x32_bf16 v[92:95], v[132:135], v[190:193], v[92:95]
	v_mfma_f32_16x16x32_bf16 v[88:91], v[158:161], v[190:193], v[88:91]
	v_mfma_f32_16x16x32_bf16 v[84:87], v[132:135], v[198:201], v[84:87]
	v_mfma_f32_16x16x32_bf16 v[80:83], v[158:161], v[198:201], v[80:83]
	v_mfma_f32_16x16x32_bf16 v[76:79], v[132:135], v[206:209], v[76:79]
	v_mfma_f32_16x16x32_bf16 v[72:75], v[158:161], v[206:209], v[72:75]
	v_mfma_f32_16x16x32_bf16 v[64:67], v[132:135], v[214:217], v[64:67]
	v_mfma_f32_16x16x32_bf16 v[56:59], v[158:161], v[214:217], v[56:59]
	s_setprio 0
	s_setprio 1
	v_mfma_f32_16x16x32_bf16 v[28:31], v[170:173], v[186:189], v[28:31]
	v_mfma_f32_16x16x32_bf16 v[24:27], v[178:181], v[186:189], v[24:27]
	v_mfma_f32_16x16x32_bf16 v[20:23], v[170:173], v[194:197], v[20:23]
	v_mfma_f32_16x16x32_bf16 v[16:19], v[178:181], v[194:197], v[16:19]
	v_mfma_f32_16x16x32_bf16 v[12:15], v[170:173], v[202:205], v[12:15]
	v_mfma_f32_16x16x32_bf16 v[8:11], v[178:181], v[202:205], v[8:11]
	v_mfma_f32_16x16x32_bf16 v[4:7], v[170:173], v[210:213], v[4:7]
	v_mfma_f32_16x16x32_bf16 v[0:3], v[178:181], v[210:213], v[0:3]
	v_mfma_f32_16x16x32_bf16 v[28:31], v[174:177], v[190:193], v[28:31]
	v_mfma_f32_16x16x32_bf16 v[24:27], v[182:185], v[190:193], v[24:27]
	v_mfma_f32_16x16x32_bf16 v[20:23], v[174:177], v[198:201], v[20:23]
	v_mfma_f32_16x16x32_bf16 v[16:19], v[182:185], v[198:201], v[16:19]
	v_mfma_f32_16x16x32_bf16 v[12:15], v[174:177], v[206:209], v[12:15]
	v_mfma_f32_16x16x32_bf16 v[8:11], v[182:185], v[206:209], v[8:11]
	s_setprio 2
	s_barrier
	v_mfma_f32_16x16x32_bf16 v[4:7], v[174:177], v[214:217], v[4:7]
	v_mfma_f32_16x16x32_bf16 v[0:3], v[182:185], v[214:217], v[0:3]
	s_setprio 0
	s_add_i32 s63, s63, 2
	s_add_u32 s40, s40, 0x100
	s_addc_u32 s41, s41, 0
	s_add_u32 s61, s61, 0x100
	s_addc_u32 s62, s62, 0
	s_cmpk_gt_u32 s63, 0x7d
	s_cbranch_scc0 .LBB0_1219
	s_and_b64 vcc, exec, s[10:11]
	s_cbranch_vccz .LBB0_1222
	s_barrier
